# GEMM epilogue row_scale: the 8 per-row sum-of-squares loads issued together at 5 epilogue sites (were dependent round trips)
# speedup vs baseline: 1.0061x; 1.0061x over previous
.LBB0_134:
	v_mov_b32_e32 v140, v0
	s_lshl_b32 s7, s28, 8
	s_mov_b64 s[30:31], s[84:85]
	v_and_b32_e32 v160, 15, v140
	s_add_i32 s7, s7, s50
	v_bfe_u32 v161, v140, 4, 2
	v_or_b32_e32 v140, s7, v160
	s_add_u32 s34, s30, s10
	s_addc_u32 s35, s31, s11
	v_ashrrev_i32_e32 v141, 31, v140
	v_lshl_add_u64 v[142:143], v[140:141], 2, s[34:35]
	s_mov_b64 s[34:35], 0x10000
	v_lshl_add_u64 v[158:159], v[142:143], 0, s[34:35]
	v_add_co_u32_e32 v142, vcc, s91, v142
	s_lshl_b32 s2, s2, 11
	s_nop 0
	v_addc_co_u32_e32 v143, vcc, 0, v143, vcc
	global_load_dword v142, v[142:143], off
	s_and_b32 s2, s2, 0x800
	global_load_dword v205, v[158:159], off offset:64
	global_load_dword v204, v[158:159], off offset:128
	global_load_dword v203, v[158:159], off offset:192
	global_load_dword v202, v[158:159], off offset:512
	global_load_dword v201, v[158:159], off offset:576
	global_load_dword v200, v[158:159], off offset:640
	global_load_dword v199, v[158:159], off offset:704
	s_waitcnt vmcnt(0)
	v_fmamk_f32 v142, v142, 0x39800000, v246
	v_cmp_gt_f32_e32 vcc, s95, v142
	v_mul_f32_e32 v143, 0x4b800000, v142
	s_nop 0
	v_cndmask_b32_e32 v142, v142, v143, vcc
	v_rsq_f32_e32 v142, v142
	s_nop 0
	v_mul_f32_e32 v143, 0x45800000, v142
	v_cndmask_b32_e32 v142, v142, v143, vcc
	v_pk_mul_f32 v[154:155], v[132:133], v[142:143] op_sel_hi:[1,0]
	v_pk_mul_f32 v[132:133], v[118:119], v[142:143] op_sel_hi:[1,0]
	v_pk_mul_f32 v[152:153], v[126:127], v[142:143] op_sel_hi:[1,0]
	v_pk_mul_f32 v[156:157], v[130:131], v[142:143] op_sel_hi:[1,0]
	v_pk_mul_f32 v[150:151], v[128:129], v[142:143] op_sel_hi:[1,0]
	v_pk_mul_f32 v[144:145], v[124:125], v[142:143] op_sel_hi:[1,0]
	v_pk_mul_f32 v[148:149], v[122:123], v[142:143] op_sel_hi:[1,0]
	v_pk_mul_f32 v[128:129], v[120:121], v[142:143] op_sel_hi:[1,0]
	s_waitcnt vmcnt(0)
	v_fmamk_f32 v118, v205, 0x39800000, v246
	v_cmp_gt_f32_e32 vcc, s95, v118
	v_mul_f32_e32 v119, 0x4b800000, v118
	s_nop 0
	v_cndmask_b32_e32 v118, v118, v119, vcc
	v_rsq_f32_e32 v118, v118
	s_nop 0
	v_mul_f32_e32 v119, 0x45800000, v118
	v_cndmask_b32_e32 v118, v118, v119, vcc
	v_pk_mul_f32 v[126:127], v[112:113], v[118:119] op_sel_hi:[1,0]
	v_pk_mul_f32 v[112:113], v[102:103], v[118:119] op_sel_hi:[1,0]
	v_pk_mul_f32 v[142:143], v[116:117], v[118:119] op_sel_hi:[1,0]
	v_pk_mul_f32 v[146:147], v[114:115], v[118:119] op_sel_hi:[1,0]
	v_pk_mul_f32 v[130:131], v[110:111], v[118:119] op_sel_hi:[1,0]
	v_pk_mul_f32 v[114:115], v[108:109], v[118:119] op_sel_hi:[1,0]
	v_pk_mul_f32 v[116:117], v[106:107], v[118:119] op_sel_hi:[1,0]
	v_pk_mul_f32 v[108:109], v[104:105], v[118:119] op_sel_hi:[1,0]
	s_waitcnt vmcnt(0)
	v_fmamk_f32 v102, v204, 0x39800000, v246
	v_cmp_gt_f32_e32 vcc, s95, v102
	v_mul_f32_e32 v103, 0x4b800000, v102
	s_nop 0
	v_cndmask_b32_e32 v102, v102, v103, vcc
	v_rsq_f32_e32 v102, v102
	s_nop 0
	v_mul_f32_e32 v103, 0x45800000, v102
	v_cndmask_b32_e32 v118, v102, v103, vcc
	v_pk_mul_f32 v[104:105], v[94:95], v[118:119] op_sel_hi:[1,0]
	v_pk_mul_f32 v[102:103], v[96:97], v[118:119] op_sel_hi:[1,0]
	v_pk_mul_f32 v[106:107], v[100:101], v[118:119] op_sel_hi:[1,0]
	v_pk_mul_f32 v[110:111], v[98:99], v[118:119] op_sel_hi:[1,0]
	v_pk_mul_f32 v[92:93], v[92:93], v[118:119] op_sel_hi:[1,0]
	v_pk_mul_f32 v[90:91], v[90:91], v[118:119] op_sel_hi:[1,0]
	v_pk_mul_f32 v[88:89], v[88:89], v[118:119] op_sel_hi:[1,0]
	v_pk_mul_f32 v[86:87], v[86:87], v[118:119] op_sel_hi:[1,0]
	s_waitcnt vmcnt(0)
	v_fmamk_f32 v94, v203, 0x39800000, v246
	v_cmp_gt_f32_e32 vcc, s95, v94
	v_mul_f32_e32 v95, 0x4b800000, v94
	s_nop 0
	v_cndmask_b32_e32 v94, v94, v95, vcc
	v_rsq_f32_e32 v94, v94
	s_nop 0
	v_mul_f32_e32 v95, 0x45800000, v94
	v_cndmask_b32_e32 v94, v94, v95, vcc
	v_pk_mul_f32 v[84:85], v[84:85], v[94:95] op_sel_hi:[1,0]
	v_pk_mul_f32 v[82:83], v[82:83], v[94:95] op_sel_hi:[1,0]
	v_pk_mul_f32 v[80:81], v[80:81], v[94:95] op_sel_hi:[1,0]
	v_pk_mul_f32 v[78:79], v[78:79], v[94:95] op_sel_hi:[1,0]
	v_pk_mul_f32 v[76:77], v[76:77], v[94:95] op_sel_hi:[1,0]
	v_pk_mul_f32 v[74:75], v[74:75], v[94:95] op_sel_hi:[1,0]
	v_pk_mul_f32 v[72:73], v[72:73], v[94:95] op_sel_hi:[1,0]
	v_pk_mul_f32 v[70:71], v[70:71], v[94:95] op_sel_hi:[1,0]
	s_waitcnt vmcnt(0)
	v_fmamk_f32 v94, v202, 0x39800000, v246
	v_cmp_gt_f32_e32 vcc, s95, v94
	v_mul_f32_e32 v95, 0x4b800000, v94
	s_nop 0
	v_cndmask_b32_e32 v94, v94, v95, vcc
	v_rsq_f32_e32 v94, v94
	s_nop 0
	v_mul_f32_e32 v95, 0x45800000, v94
	v_cndmask_b32_e32 v94, v94, v95, vcc
	v_pk_mul_f32 v[68:69], v[68:69], v[94:95] op_sel_hi:[1,0]
	v_pk_mul_f32 v[66:67], v[66:67], v[94:95] op_sel_hi:[1,0]
	v_pk_mul_f32 v[64:65], v[64:65], v[94:95] op_sel_hi:[1,0]
	v_pk_mul_f32 v[62:63], v[62:63], v[94:95] op_sel_hi:[1,0]
	v_pk_mul_f32 v[60:61], v[60:61], v[94:95] op_sel_hi:[1,0]
	v_pk_mul_f32 v[58:59], v[58:59], v[94:95] op_sel_hi:[1,0]
	v_pk_mul_f32 v[56:57], v[56:57], v[94:95] op_sel_hi:[1,0]
	v_pk_mul_f32 v[54:55], v[54:55], v[94:95] op_sel_hi:[1,0]
	v_mul_f32_e32 v162, v59, v59
	v_mul_f32_e32 v163, v61, v61
	v_fmac_f32_e32 v162, v58, v58
	v_fmac_f32_e32 v163, v60, v60
	v_add_f32_e32 v162, v162, v163
	v_mul_f32_e32 v163, v55, v55
	v_fmac_f32_e32 v163, v54, v54
	v_add_f32_e32 v162, v163, v162
	v_mul_f32_e32 v163, v57, v57
	v_fmac_f32_e32 v163, v56, v56
	v_add_f32_e32 v162, v163, v162
	ds_swizzle_b32 v163, v162 offset:swizzle(SWAP,16)
	s_waitcnt lgkmcnt(0)
	v_add_f32_e32 v162, v162, v163
	v_mov_b32_e32 v163, v162
	s_nop 1
	v_permlane32_swap_b32_e32 v162, v163
	s_waitcnt vmcnt(0)
	v_fmamk_f32 v94, v201, 0x39800000, v246
	v_cmp_gt_f32_e32 vcc, s95, v94
	v_mul_f32_e32 v95, 0x4b800000, v94
	s_nop 0
	v_cndmask_b32_e32 v94, v94, v95, vcc
	v_rsq_f32_e32 v94, v94
	s_nop 0
	v_mul_f32_e32 v95, 0x45800000, v94
	v_cndmask_b32_e32 v94, v94, v95, vcc
	v_pk_mul_f32 v[52:53], v[52:53], v[94:95] op_sel_hi:[1,0]
	v_pk_mul_f32 v[50:51], v[50:51], v[94:95] op_sel_hi:[1,0]
	v_pk_mul_f32 v[48:49], v[48:49], v[94:95] op_sel_hi:[1,0]
	v_pk_mul_f32 v[46:47], v[46:47], v[94:95] op_sel_hi:[1,0]
	v_pk_mul_f32 v[44:45], v[44:45], v[94:95] op_sel_hi:[1,0]
	v_pk_mul_f32 v[42:43], v[42:43], v[94:95] op_sel_hi:[1,0]
	v_pk_mul_f32 v[40:41], v[40:41], v[94:95] op_sel_hi:[1,0]
	v_pk_mul_f32 v[38:39], v[38:39], v[94:95] op_sel_hi:[1,0]
	v_mul_f32_e32 v164, v51, v51
	v_mul_f32_e32 v165, v53, v53
	v_mul_f32_e32 v166, v43, v43
	v_mul_f32_e32 v167, v45, v45
	v_fmac_f32_e32 v164, v50, v50
	v_fmac_f32_e32 v165, v52, v52
	v_fmac_f32_e32 v166, v42, v42
	v_fmac_f32_e32 v167, v44, v44
	v_add_f32_e32 v164, v164, v165
	v_mul_f32_e32 v165, v47, v47
	v_add_f32_e32 v166, v166, v167
	v_mul_f32_e32 v167, v39, v39
	v_fmac_f32_e32 v165, v46, v46
	v_fmac_f32_e32 v167, v38, v38
	v_add_f32_e32 v164, v165, v164
	v_mul_f32_e32 v165, v49, v49
	v_add_f32_e32 v166, v167, v166
	v_mul_f32_e32 v167, v41, v41
	v_fmac_f32_e32 v165, v48, v48
	v_fmac_f32_e32 v167, v40, v40
	v_add_f32_e32 v164, v165, v164
	v_add_f32_e32 v166, v167, v166
	ds_swizzle_b32 v165, v164 offset:swizzle(SWAP,16)
	ds_swizzle_b32 v167, v166 offset:swizzle(SWAP,16)
	s_waitcnt lgkmcnt(1)
	v_add_f32_e32 v164, v164, v165
	s_waitcnt lgkmcnt(0)
	v_add_f32_e32 v166, v166, v167
	v_mov_b32_e32 v165, v164
	v_mov_b32_e32 v167, v166
	s_nop 0
	v_permlane32_swap_b32_e32 v164, v165
	v_permlane32_swap_b32_e32 v166, v167
	s_waitcnt vmcnt(0)
	v_fmamk_f32 v94, v200, 0x39800000, v246
	v_cmp_gt_f32_e32 vcc, s95, v94
	v_mul_f32_e32 v95, 0x4b800000, v94
	s_nop 0
	v_cndmask_b32_e32 v94, v94, v95, vcc
	v_rsq_f32_e32 v94, v94
	s_nop 0
	v_mul_f32_e32 v95, 0x45800000, v94
	v_cndmask_b32_e32 v94, v94, v95, vcc
	v_pk_mul_f32 v[36:37], v[36:37], v[94:95] op_sel_hi:[1,0]
	v_pk_mul_f32 v[34:35], v[34:35], v[94:95] op_sel_hi:[1,0]
	v_pk_mul_f32 v[32:33], v[32:33], v[94:95] op_sel_hi:[1,0]
	v_pk_mul_f32 v[30:31], v[30:31], v[94:95] op_sel_hi:[1,0]
	v_pk_mul_f32 v[28:29], v[28:29], v[94:95] op_sel_hi:[1,0]
	v_pk_mul_f32 v[26:27], v[26:27], v[94:95] op_sel_hi:[1,0]
	v_pk_mul_f32 v[24:25], v[24:25], v[94:95] op_sel_hi:[1,0]
	v_pk_mul_f32 v[22:23], v[22:23], v[94:95] op_sel_hi:[1,0]
	v_mul_f32_e32 v158, v67, v67
	v_mul_f32_e32 v159, v69, v69
	v_mul_f32_e32 v168, v35, v35
	v_mul_f32_e32 v169, v37, v37
	v_mul_f32_e32 v170, v27, v27
	v_mul_f32_e32 v171, v29, v29
	v_fmac_f32_e32 v158, v66, v66
	v_fmac_f32_e32 v159, v68, v68
	v_fmac_f32_e32 v168, v34, v34
	v_fmac_f32_e32 v169, v36, v36
	v_fmac_f32_e32 v170, v26, v26
	v_fmac_f32_e32 v171, v28, v28
	v_add_f32_e32 v158, v158, v159
	v_mul_f32_e32 v159, v63, v63
	v_add_f32_e32 v168, v168, v169
	v_mul_f32_e32 v169, v31, v31
	v_add_f32_e32 v170, v170, v171
	v_mul_f32_e32 v171, v23, v23
	v_fmac_f32_e32 v159, v62, v62
	v_fmac_f32_e32 v169, v30, v30
	v_fmac_f32_e32 v171, v22, v22
	v_add_f32_e32 v158, v159, v158
	v_mul_f32_e32 v159, v65, v65
	v_add_f32_e32 v168, v169, v168
	v_mul_f32_e32 v169, v33, v33
	v_add_f32_e32 v170, v171, v170
	v_mul_f32_e32 v171, v25, v25
	v_fmac_f32_e32 v159, v64, v64
	v_fmac_f32_e32 v169, v32, v32
	v_fmac_f32_e32 v171, v24, v24
	v_add_f32_e32 v158, v159, v158
	v_add_f32_e32 v168, v169, v168
	v_add_f32_e32 v170, v171, v170
	ds_swizzle_b32 v159, v158 offset:swizzle(SWAP,16)
	ds_swizzle_b32 v169, v168 offset:swizzle(SWAP,16)
	ds_swizzle_b32 v171, v170 offset:swizzle(SWAP,16)
	s_waitcnt lgkmcnt(2)
	v_add_f32_e32 v158, v158, v159
	s_waitcnt lgkmcnt(1)
	v_add_f32_e32 v168, v168, v169
	s_waitcnt lgkmcnt(0)
	v_add_f32_e32 v170, v170, v171
	v_mov_b32_e32 v159, v158
	v_mov_b32_e32 v169, v168
	v_mov_b32_e32 v171, v170
	v_permlane32_swap_b32_e32 v158, v159
	v_permlane32_swap_b32_e32 v168, v169
	v_permlane32_swap_b32_e32 v170, v171
	s_waitcnt vmcnt(0)
	v_fmamk_f32 v94, v199, 0x39800000, v246
	v_cmp_gt_f32_e32 vcc, s95, v94
	v_mul_f32_e32 v95, 0x4b800000, v94
	s_nop 0
	v_cndmask_b32_e32 v94, v94, v95, vcc
	v_rsq_f32_e32 v94, v94
	s_nop 0
	v_mul_f32_e32 v95, 0x45800000, v94
	v_cndmask_b32_e32 v96, v94, v95, vcc
	v_pk_mul_f32 v[122:123], v[20:21], v[96:97] op_sel_hi:[1,0]
	v_pk_mul_f32 v[124:125], v[18:19], v[96:97] op_sel_hi:[1,0]
	v_pk_mul_f32 v[98:99], v[12:13], v[96:97] op_sel_hi:[1,0]
	v_pk_mul_f32 v[100:101], v[10:11], v[96:97] op_sel_hi:[1,0]
	v_pk_mul_f32 v[118:119], v[16:17], v[96:97] op_sel_hi:[1,0]
	v_pk_mul_f32 v[120:121], v[14:15], v[96:97] op_sel_hi:[1,0]
	v_pk_mul_f32 v[94:95], v[8:9], v[96:97] op_sel_hi:[1,0]
	v_pk_mul_f32 v[96:97], v[6:7], v[96:97] op_sel_hi:[1,0]
	v_mul_f32_e32 v6, v157, v157
	v_mul_f32_e32 v7, v155, v155
	v_mul_f32_e32 v8, v149, v149
	v_mul_f32_e32 v9, v145, v145
	v_mul_f32_e32 v10, v147, v147
	v_mul_f32_e32 v11, v143, v143
	v_mul_f32_e32 v12, v117, v117
	v_mul_f32_e32 v13, v115, v115
	v_mul_f32_e32 v14, v111, v111
	v_mul_f32_e32 v15, v107, v107
	v_mul_f32_e32 v16, v91, v91
	v_mul_f32_e32 v17, v93, v93
	v_mul_f32_e32 v18, v83, v83
	v_mul_f32_e32 v19, v85, v85
	v_mul_f32_e32 v20, v75, v75
	v_mul_f32_e32 v21, v77, v77
	v_mul_f32_e32 v172, v125, v125
	v_mul_f32_e32 v173, v123, v123
	v_mul_f32_e32 v174, v101, v101
	v_mul_f32_e32 v175, v99, v99
	v_fmac_f32_e32 v6, v156, v156
	v_fmac_f32_e32 v7, v154, v154
	v_fmac_f32_e32 v8, v148, v148
	v_fmac_f32_e32 v9, v144, v144
	v_fmac_f32_e32 v10, v146, v146
	v_fmac_f32_e32 v11, v142, v142
	v_fmac_f32_e32 v12, v116, v116
	v_fmac_f32_e32 v13, v114, v114
	v_fmac_f32_e32 v14, v110, v110
	v_fmac_f32_e32 v15, v106, v106
	v_fmac_f32_e32 v16, v90, v90
	v_fmac_f32_e32 v17, v92, v92
	v_fmac_f32_e32 v18, v82, v82
	v_fmac_f32_e32 v19, v84, v84
	v_fmac_f32_e32 v20, v74, v74
	v_fmac_f32_e32 v21, v76, v76
	v_fmac_f32_e32 v172, v124, v124
	v_fmac_f32_e32 v173, v122, v122
	v_fmac_f32_e32 v174, v100, v100
	v_fmac_f32_e32 v175, v98, v98
	v_add_f32_e32 v6, v6, v7
	v_mul_f32_e32 v7, v153, v153
	v_add_f32_e32 v8, v8, v9
	v_mul_f32_e32 v9, v133, v133
	v_add_f32_e32 v10, v10, v11
	v_mul_f32_e32 v11, v131, v131
	v_add_f32_e32 v12, v12, v13
	v_mul_f32_e32 v13, v113, v113
	v_add_f32_e32 v14, v14, v15
	v_mul_f32_e32 v15, v105, v105
	v_add_f32_e32 v16, v16, v17
	v_mul_f32_e32 v17, v87, v87
	v_add_f32_e32 v18, v18, v19
	v_mul_f32_e32 v19, v79, v79
	v_add_f32_e32 v20, v20, v21
	v_mul_f32_e32 v21, v71, v71
	v_add_f32_e32 v172, v172, v173
	v_mul_f32_e32 v173, v121, v121
	v_add_f32_e32 v174, v174, v175
	v_mul_f32_e32 v175, v97, v97
	v_fmac_f32_e32 v7, v152, v152
	v_fmac_f32_e32 v9, v132, v132
	v_fmac_f32_e32 v11, v130, v130
	v_fmac_f32_e32 v13, v112, v112
	v_fmac_f32_e32 v15, v104, v104
	v_fmac_f32_e32 v17, v86, v86
	v_fmac_f32_e32 v19, v78, v78
	v_fmac_f32_e32 v21, v70, v70
	v_fmac_f32_e32 v173, v120, v120
	v_fmac_f32_e32 v175, v96, v96
	v_add_f32_e32 v6, v7, v6
	v_mul_f32_e32 v7, v151, v151
	v_add_f32_e32 v8, v9, v8
	v_mul_f32_e32 v9, v129, v129
	v_add_f32_e32 v10, v11, v10
	v_mul_f32_e32 v11, v127, v127
	v_add_f32_e32 v12, v13, v12
	v_mul_f32_e32 v13, v109, v109
	v_add_f32_e32 v14, v15, v14
	v_mul_f32_e32 v15, v103, v103
	v_add_f32_e32 v16, v17, v16
	v_mul_f32_e32 v17, v89, v89
	v_add_f32_e32 v18, v19, v18
	v_mul_f32_e32 v19, v81, v81
	v_add_f32_e32 v20, v21, v20
	v_mul_f32_e32 v21, v73, v73
	v_add_f32_e32 v172, v173, v172
	v_mul_f32_e32 v173, v119, v119
	v_add_f32_e32 v174, v175, v174
	v_mul_f32_e32 v175, v95, v95
	v_fmac_f32_e32 v7, v150, v150
	v_fmac_f32_e32 v9, v128, v128
	v_fmac_f32_e32 v11, v126, v126
	v_fmac_f32_e32 v13, v108, v108
	v_fmac_f32_e32 v15, v102, v102
	v_fmac_f32_e32 v17, v88, v88
	v_fmac_f32_e32 v19, v80, v80
	v_fmac_f32_e32 v21, v72, v72
	v_fmac_f32_e32 v173, v118, v118
	v_fmac_f32_e32 v175, v94, v94
	v_add_f32_e32 v6, v7, v6
	v_add_f32_e32 v8, v9, v8
	v_add_f32_e32 v10, v11, v10
	v_add_f32_e32 v12, v13, v12
	v_add_f32_e32 v14, v15, v14
	v_add_f32_e32 v16, v17, v16
	v_add_f32_e32 v18, v19, v18
	v_add_f32_e32 v20, v21, v20
	v_add_f32_e32 v172, v173, v172
	v_add_f32_e32 v174, v175, v174
	ds_swizzle_b32 v7, v6 offset:swizzle(SWAP,16)
	ds_swizzle_b32 v9, v8 offset:swizzle(SWAP,16)
	ds_swizzle_b32 v11, v10 offset:swizzle(SWAP,16)
	ds_swizzle_b32 v13, v12 offset:swizzle(SWAP,16)
	ds_swizzle_b32 v15, v14 offset:swizzle(SWAP,16)
	ds_swizzle_b32 v17, v16 offset:swizzle(SWAP,16)
	ds_swizzle_b32 v19, v18 offset:swizzle(SWAP,16)
	ds_swizzle_b32 v21, v20 offset:swizzle(SWAP,16)
	ds_swizzle_b32 v173, v172 offset:swizzle(SWAP,16)
	ds_swizzle_b32 v175, v174 offset:swizzle(SWAP,16)
	s_waitcnt lgkmcnt(9)
	v_add_f32_e32 v6, v6, v7
	s_waitcnt lgkmcnt(8)
	v_add_f32_e32 v8, v8, v9
	s_waitcnt lgkmcnt(7)
	v_add_f32_e32 v10, v10, v11
	s_waitcnt lgkmcnt(6)
	v_add_f32_e32 v12, v12, v13
	s_waitcnt lgkmcnt(5)
	v_add_f32_e32 v14, v14, v15
	s_waitcnt lgkmcnt(4)
	v_add_f32_e32 v16, v16, v17
	s_waitcnt lgkmcnt(3)
	v_add_f32_e32 v18, v18, v19
	s_waitcnt lgkmcnt(2)
	v_add_f32_e32 v20, v20, v21
	s_waitcnt lgkmcnt(1)
	v_add_f32_e32 v172, v172, v173
	s_waitcnt lgkmcnt(0)
	v_add_f32_e32 v174, v174, v175
	v_mov_b32_e32 v7, v6
	v_mov_b32_e32 v9, v8
	v_mov_b32_e32 v11, v10
	v_mov_b32_e32 v13, v12
	v_mov_b32_e32 v15, v14
	v_mov_b32_e32 v17, v16
	v_mov_b32_e32 v19, v18
	v_mov_b32_e32 v21, v20
	v_mov_b32_e32 v173, v172
	v_mov_b32_e32 v175, v174
	v_permlane32_swap_b32_e32 v6, v7
	v_permlane32_swap_b32_e32 v8, v9
	v_permlane32_swap_b32_e32 v10, v11
	v_permlane32_swap_b32_e32 v12, v13
	v_permlane32_swap_b32_e32 v14, v15
	v_permlane32_swap_b32_e32 v16, v17
	v_permlane32_swap_b32_e32 v18, v19
	v_permlane32_swap_b32_e32 v20, v21
	v_permlane32_swap_b32_e32 v172, v173
	v_permlane32_swap_b32_e32 v174, v175
	v_cmp_eq_u32_e32 vcc, 0, v161
	s_and_saveexec_b64 s[34:35], vcc
	s_cbranch_execz .LBB0_136
	s_lshl_b32 s7, s2, 2
	s_add_i32 s7, s54, s7
	v_add_f32_e32 v8, v8, v9
	v_add_f32_e32 v6, v6, v7
	v_lshl_add_u32 v7, v160, 5, s7
	v_add_f32_e32 v16, v16, v17
	v_add_f32_e32 v14, v14, v15
	v_add_f32_e32 v12, v12, v13
	v_add_f32_e32 v10, v10, v11
	ds_write2_b32 v7, v6, v8 offset1:4
	ds_write2_b32 v7, v10, v12 offset0:128 offset1:132
	v_add_u32_e32 v6, 0x400, v7
	v_add_f32_e32 v162, v162, v163
	v_add_f32_e32 v158, v158, v159
	v_add_f32_e32 v20, v20, v21
	v_add_f32_e32 v18, v18, v19
	ds_write2_b32 v6, v14, v16 offset1:4
	ds_write2_b32 v6, v18, v20 offset0:128 offset1:132
	v_add_u32_e32 v6, 0x1000, v7
	v_add_f32_e32 v170, v170, v171
	v_add_f32_e32 v168, v168, v169
	v_add_f32_e32 v166, v166, v167
	v_add_f32_e32 v164, v164, v165
	ds_write2_b32 v6, v158, v162 offset1:4
	ds_write2_b32 v6, v164, v166 offset0:128 offset1:132
	v_add_u32_e32 v6, 0x1400, v7
	v_add_f32_e32 v174, v174, v175
	v_add_f32_e32 v172, v172, v173
	ds_write2_b32 v6, v168, v170 offset1:4
	ds_write2_b32 v6, v172, v174 offset0:128 offset1:132

.LBB0_251:
	s_add_u32 s56, s52, 0xffffff80
	s_addc_u32 s57, s53, -1
	s_cmp_eq_u32 s54, 60
	s_cselect_b32 s28, s2, s52
	s_cselect_b32 s29, s1, s53
	s_cselect_b32 s31, s11, s33
	s_cselect_b32 s30, s15, s19
	s_add_u32 s24, s28, 0x80
	s_addc_u32 s25, s29, 0
	s_add_u32 s26, s30, 0x80
	s_addc_u32 s27, s31, 0
	s_add_i32 s55, 0, 0x10000
	s_add_i32 s58, 0, 0x14000
	v_add_u32_e32 v152, s55, v1
	v_add_u32_e32 v168, s58, v1
	ds_read_b128 v[140:143], v152
	ds_read_b128 v[144:147], v152 offset:1024
	ds_read_b128 v[148:151], v152 offset:2048
	ds_read_b128 v[152:155], v152 offset:3072
	ds_read_b128 v[156:159], v168
	ds_read_b128 v[160:163], v168 offset:1024
	ds_read_b128 v[164:167], v168 offset:2048
	ds_read_b128 v[168:171], v168 offset:3072
	s_add_u32 s56, s56, 0x100000
	s_addc_u32 s57, s57, 0
	v_lshl_add_u64 v[204:205], s[56:57], 0, v[138:139]
	s_add_i32 m0, s23, 0xc000
	ds_read_b128 v[172:175], v5
	ds_read_b128 v[176:179], v5 offset:1024
	ds_read_b128 v[180:183], v5 offset:2048
	ds_read_b128 v[184:187], v5 offset:3072
	ds_read_b128 v[188:191], v5 offset:4096
	ds_read_b128 v[192:195], v5 offset:5120
	ds_read_b128 v[196:199], v5 offset:6144
	ds_read_b128 v[200:203], v5 offset:7168
	global_load_lds_dwordx4 v[204:205], off
	v_lshl_add_u64 v[204:205], s[56:57], 0, v[134:135]
	s_add_i32 m0, s23, 0xe000
	s_nop 0
	global_load_lds_dwordx4 v[204:205], off
	s_waitcnt vmcnt(8)
	s_waitcnt lgkmcnt(0)
	s_barrier
	s_setprio 1
	s_waitcnt lgkmcnt(0)
	v_mfma_f32_16x16x32_bf16 v[6:9], v[140:143], v[172:175], v[6:9]
	v_mfma_f32_16x16x32_bf16 v[10:13], v[148:151], v[172:175], v[10:13]
	v_mfma_f32_16x16x32_bf16 v[22:25], v[140:143], v[180:183], v[22:25]
	v_mfma_f32_16x16x32_bf16 v[26:29], v[148:151], v[180:183], v[26:29]
	v_mfma_f32_16x16x32_bf16 v[38:41], v[140:143], v[188:191], v[38:41]
	v_mfma_f32_16x16x32_bf16 v[42:45], v[148:151], v[188:191], v[42:45]
	v_mfma_f32_16x16x32_bf16 v[54:57], v[140:143], v[196:199], v[54:57]
	v_mfma_f32_16x16x32_bf16 v[58:61], v[148:151], v[196:199], v[58:61]
	v_mfma_f32_16x16x32_bf16 v[6:9], v[144:147], v[176:179], v[6:9]
	v_mfma_f32_16x16x32_bf16 v[10:13], v[152:155], v[176:179], v[10:13]
	v_mfma_f32_16x16x32_bf16 v[22:25], v[144:147], v[184:187], v[22:25]
	v_mfma_f32_16x16x32_bf16 v[26:29], v[152:155], v[184:187], v[26:29]
	v_mfma_f32_16x16x32_bf16 v[38:41], v[144:147], v[192:195], v[38:41]
	v_mfma_f32_16x16x32_bf16 v[42:45], v[152:155], v[192:195], v[42:45]
	v_mfma_f32_16x16x32_bf16 v[54:57], v[144:147], v[200:203], v[54:57]
	v_mfma_f32_16x16x32_bf16 v[58:61], v[152:155], v[200:203], v[58:61]
	s_setprio 0
	s_setprio 1
	v_mfma_f32_16x16x32_bf16 v[14:17], v[156:159], v[172:175], v[14:17]
	v_mfma_f32_16x16x32_bf16 v[18:21], v[164:167], v[172:175], v[18:21]
	v_mfma_f32_16x16x32_bf16 v[30:33], v[156:159], v[180:183], v[30:33]
	v_mfma_f32_16x16x32_bf16 v[34:37], v[164:167], v[180:183], v[34:37]
	v_mfma_f32_16x16x32_bf16 v[46:49], v[156:159], v[188:191], v[46:49]
	v_mfma_f32_16x16x32_bf16 v[50:53], v[164:167], v[188:191], v[50:53]
	v_mfma_f32_16x16x32_bf16 v[62:65], v[156:159], v[196:199], v[62:65]
	v_mfma_f32_16x16x32_bf16 v[66:69], v[164:167], v[196:199], v[66:69]
	v_mfma_f32_16x16x32_bf16 v[14:17], v[160:163], v[176:179], v[14:17]
	v_mfma_f32_16x16x32_bf16 v[18:21], v[168:171], v[176:179], v[18:21]
	v_mfma_f32_16x16x32_bf16 v[30:33], v[160:163], v[184:187], v[30:33]
	v_mfma_f32_16x16x32_bf16 v[34:37], v[168:171], v[184:187], v[34:37]
	v_mfma_f32_16x16x32_bf16 v[46:49], v[160:163], v[192:195], v[46:49]
	v_mfma_f32_16x16x32_bf16 v[50:53], v[168:171], v[192:195], v[50:53]
	v_mfma_f32_16x16x32_bf16 v[62:65], v[160:163], v[200:203], v[62:65]
	v_mfma_f32_16x16x32_bf16 v[66:69], v[168:171], v[200:203], v[66:69]
	s_setprio 0
	s_barrier
	s_add_i32 s55, s55, s37
	v_lshl_add_u64 v[204:205], s[30:31], 0, v[136:137]
	s_mov_b32 m0, s55
	ds_read_b128 v[172:175], v5 offset:16384
	ds_read_b128 v[176:179], v5 offset:17408
	ds_read_b128 v[180:183], v5 offset:18432
	ds_read_b128 v[184:187], v5 offset:19456
	ds_read_b128 v[188:191], v5 offset:20480
	ds_read_b128 v[192:195], v5 offset:21504
	ds_read_b128 v[196:199], v5 offset:22528
	ds_read_b128 v[200:203], v5 offset:23552
	global_load_lds_dwordx4 v[204:205], off
	s_add_i32 m0, s55, 0x2000
	v_lshl_add_u64 v[204:205], s[30:31], 0, v[2:3]
	s_add_u32 s30, s30, 0x100000
	s_addc_u32 s31, s31, 0
	s_add_i32 s55, s58, s37
	global_load_lds_dwordx4 v[204:205], off
	v_lshl_add_u64 v[204:205], s[30:31], 0, v[136:137]
	s_mov_b32 m0, s55
	s_nop 0
	global_load_lds_dwordx4 v[204:205], off
	v_lshl_add_u64 v[204:205], s[30:31], 0, v[2:3]
	s_add_i32 m0, s55, 0x2000
	s_nop 0
	global_load_lds_dwordx4 v[204:205], off
	v_lshl_add_u64 v[204:205], s[28:29], 0, v[138:139]
	s_mov_b32 m0, s23
	s_nop 0
	global_load_lds_dwordx4 v[204:205], off
	v_lshl_add_u64 v[204:205], s[28:29], 0, v[134:135]
	s_mov_b32 m0, s40
	s_nop 0
	global_load_lds_dwordx4 v[204:205], off
	s_waitcnt vmcnt(8)
	s_waitcnt lgkmcnt(0)
	s_barrier
	s_setprio 1
	s_waitcnt lgkmcnt(0)
	v_mfma_f32_16x16x32_bf16 v[70:73], v[140:143], v[172:175], v[70:73]
	v_mfma_f32_16x16x32_bf16 v[74:77], v[148:151], v[172:175], v[74:77]
	v_mfma_f32_16x16x32_bf16 v[86:89], v[140:143], v[180:183], v[86:89]
	v_mfma_f32_16x16x32_bf16 v[90:93], v[148:151], v[180:183], v[90:93]
	v_mfma_f32_16x16x32_bf16 v[102:105], v[140:143], v[188:191], v[102:105]
	v_mfma_f32_16x16x32_bf16 v[106:109], v[148:151], v[188:191], v[106:109]
	v_mfma_f32_16x16x32_bf16 v[130:133], v[140:143], v[196:199], v[130:133]
	v_mfma_f32_16x16x32_bf16 v[126:129], v[148:151], v[196:199], v[126:129]
	v_mfma_f32_16x16x32_bf16 v[70:73], v[144:147], v[176:179], v[70:73]
	v_mfma_f32_16x16x32_bf16 v[74:77], v[152:155], v[176:179], v[74:77]
	v_mfma_f32_16x16x32_bf16 v[86:89], v[144:147], v[184:187], v[86:89]
	v_mfma_f32_16x16x32_bf16 v[90:93], v[152:155], v[184:187], v[90:93]
	v_mfma_f32_16x16x32_bf16 v[102:105], v[144:147], v[192:195], v[102:105]
	v_mfma_f32_16x16x32_bf16 v[106:109], v[152:155], v[192:195], v[106:109]
	v_mfma_f32_16x16x32_bf16 v[130:133], v[144:147], v[200:203], v[130:133]
	v_mfma_f32_16x16x32_bf16 v[126:129], v[152:155], v[200:203], v[126:129]
	s_setprio 0
	s_setprio 1
	v_mfma_f32_16x16x32_bf16 v[78:81], v[156:159], v[172:175], v[78:81]
	v_mfma_f32_16x16x32_bf16 v[82:85], v[164:167], v[172:175], v[82:85]
	v_mfma_f32_16x16x32_bf16 v[94:97], v[156:159], v[180:183], v[94:97]
	v_mfma_f32_16x16x32_bf16 v[98:101], v[164:167], v[180:183], v[98:101]
	v_mfma_f32_16x16x32_bf16 v[110:113], v[156:159], v[188:191], v[110:113]
	v_mfma_f32_16x16x32_bf16 v[114:117], v[164:167], v[188:191], v[114:117]
	v_mfma_f32_16x16x32_bf16 v[122:125], v[156:159], v[196:199], v[122:125]
	v_mfma_f32_16x16x32_bf16 v[118:121], v[164:167], v[196:199], v[118:121]
	v_mfma_f32_16x16x32_bf16 v[78:81], v[160:163], v[176:179], v[78:81]
	v_mfma_f32_16x16x32_bf16 v[82:85], v[168:171], v[176:179], v[82:85]
	v_mfma_f32_16x16x32_bf16 v[94:97], v[160:163], v[184:187], v[94:97]
	v_mfma_f32_16x16x32_bf16 v[98:101], v[168:171], v[184:187], v[98:101]
	v_mfma_f32_16x16x32_bf16 v[110:113], v[160:163], v[192:195], v[110:113]
	v_mfma_f32_16x16x32_bf16 v[114:117], v[168:171], v[192:195], v[114:117]
	v_mfma_f32_16x16x32_bf16 v[122:125], v[160:163], v[200:203], v[122:125]
	v_mfma_f32_16x16x32_bf16 v[118:121], v[168:171], v[200:203], v[118:121]
	s_setprio 0
	s_barrier
	s_add_i32 s30, 0, 0x18000
	s_add_i32 s31, 0, 0x1c000
	v_add_u32_e32 v152, s30, v1
	v_add_u32_e32 v168, s31, v1
	ds_read_b128 v[140:143], v152
	ds_read_b128 v[144:147], v152 offset:1024
	ds_read_b128 v[148:151], v152 offset:2048
	ds_read_b128 v[152:155], v152 offset:3072
	ds_read_b128 v[156:159], v168
	ds_read_b128 v[160:163], v168 offset:1024
	ds_read_b128 v[164:167], v168 offset:2048
	ds_read_b128 v[168:171], v168 offset:3072
	s_add_u32 s28, s28, 0x100000
	s_addc_u32 s29, s29, 0
	s_mov_b32 m0, s41
	v_lshl_add_u64 v[204:205], s[28:29], 0, v[138:139]
	ds_read_b128 v[172:175], v5 offset:32768
	ds_read_b128 v[176:179], v5 offset:33792
	ds_read_b128 v[180:183], v5 offset:34816
	ds_read_b128 v[184:187], v5 offset:35840
	ds_read_b128 v[188:191], v5 offset:36864
	ds_read_b128 v[192:195], v5 offset:37888
	ds_read_b128 v[196:199], v5 offset:38912
	ds_read_b128 v[200:203], v5 offset:39936
	global_load_lds_dwordx4 v[204:205], off
	v_lshl_add_u64 v[204:205], s[28:29], 0, v[134:135]
	s_mov_b32 m0, s42
	s_nop 0
	global_load_lds_dwordx4 v[204:205], off
	s_waitcnt vmcnt(8)
	s_waitcnt lgkmcnt(0)
	s_barrier
	s_setprio 1
	s_waitcnt lgkmcnt(0)
	v_mfma_f32_16x16x32_bf16 v[6:9], v[140:143], v[172:175], v[6:9]
	v_mfma_f32_16x16x32_bf16 v[10:13], v[148:151], v[172:175], v[10:13]
	v_mfma_f32_16x16x32_bf16 v[22:25], v[140:143], v[180:183], v[22:25]
	v_mfma_f32_16x16x32_bf16 v[26:29], v[148:151], v[180:183], v[26:29]
	v_mfma_f32_16x16x32_bf16 v[38:41], v[140:143], v[188:191], v[38:41]
	v_mfma_f32_16x16x32_bf16 v[42:45], v[148:151], v[188:191], v[42:45]
	v_mfma_f32_16x16x32_bf16 v[54:57], v[140:143], v[196:199], v[54:57]
	v_mfma_f32_16x16x32_bf16 v[58:61], v[148:151], v[196:199], v[58:61]
	v_mfma_f32_16x16x32_bf16 v[6:9], v[144:147], v[176:179], v[6:9]
	v_mfma_f32_16x16x32_bf16 v[10:13], v[152:155], v[176:179], v[10:13]
	v_mfma_f32_16x16x32_bf16 v[22:25], v[144:147], v[184:187], v[22:25]
	v_mfma_f32_16x16x32_bf16 v[26:29], v[152:155], v[184:187], v[26:29]
	v_mfma_f32_16x16x32_bf16 v[38:41], v[144:147], v[192:195], v[38:41]
	v_mfma_f32_16x16x32_bf16 v[42:45], v[152:155], v[192:195], v[42:45]
	v_mfma_f32_16x16x32_bf16 v[54:57], v[144:147], v[200:203], v[54:57]
	v_mfma_f32_16x16x32_bf16 v[58:61], v[152:155], v[200:203], v[58:61]
	s_setprio 0
	s_setprio 1
	v_mfma_f32_16x16x32_bf16 v[14:17], v[156:159], v[172:175], v[14:17]
	v_mfma_f32_16x16x32_bf16 v[18:21], v[164:167], v[172:175], v[18:21]
	v_mfma_f32_16x16x32_bf16 v[30:33], v[156:159], v[180:183], v[30:33]
	v_mfma_f32_16x16x32_bf16 v[34:37], v[164:167], v[180:183], v[34:37]
	v_mfma_f32_16x16x32_bf16 v[46:49], v[156:159], v[188:191], v[46:49]
	v_mfma_f32_16x16x32_bf16 v[50:53], v[164:167], v[188:191], v[50:53]
	v_mfma_f32_16x16x32_bf16 v[62:65], v[156:159], v[196:199], v[62:65]
	v_mfma_f32_16x16x32_bf16 v[66:69], v[164:167], v[196:199], v[66:69]
	v_mfma_f32_16x16x32_bf16 v[14:17], v[160:163], v[176:179], v[14:17]
	v_mfma_f32_16x16x32_bf16 v[18:21], v[168:171], v[176:179], v[18:21]
	v_mfma_f32_16x16x32_bf16 v[30:33], v[160:163], v[184:187], v[30:33]
	v_mfma_f32_16x16x32_bf16 v[34:37], v[168:171], v[184:187], v[34:37]
	v_mfma_f32_16x16x32_bf16 v[46:49], v[160:163], v[192:195], v[46:49]
	v_mfma_f32_16x16x32_bf16 v[50:53], v[168:171], v[192:195], v[50:53]
	v_mfma_f32_16x16x32_bf16 v[62:65], v[160:163], v[200:203], v[62:65]
	v_mfma_f32_16x16x32_bf16 v[66:69], v[168:171], v[200:203], v[66:69]
	s_setprio 0
	s_barrier
	s_add_i32 s28, s30, s37
	v_lshl_add_u64 v[204:205], s[26:27], 0, v[136:137]
	s_mov_b32 m0, s28
	ds_read_b128 v[172:175], v5 offset:49152
	ds_read_b128 v[176:179], v5 offset:50176
	ds_read_b128 v[180:183], v5 offset:51200
	ds_read_b128 v[184:187], v5 offset:52224
	ds_read_b128 v[188:191], v5 offset:53248
	ds_read_b128 v[192:195], v5 offset:54272
	ds_read_b128 v[196:199], v5 offset:55296
	ds_read_b128 v[200:203], v5 offset:56320
	global_load_lds_dwordx4 v[204:205], off
	s_add_i32 m0, s28, 0x2000
	v_lshl_add_u64 v[204:205], s[26:27], 0, v[2:3]
	s_add_u32 s26, s26, 0x100000
	s_addc_u32 s27, s27, 0
	s_add_i32 s28, s31, s37
	global_load_lds_dwordx4 v[204:205], off
	v_lshl_add_u64 v[204:205], s[26:27], 0, v[136:137]
	s_mov_b32 m0, s28
	s_nop 0
	global_load_lds_dwordx4 v[204:205], off
	v_lshl_add_u64 v[204:205], s[26:27], 0, v[2:3]
	s_add_i32 m0, s28, 0x2000
	s_nop 0
	global_load_lds_dwordx4 v[204:205], off
	v_lshl_add_u64 v[204:205], s[24:25], 0, v[138:139]
	s_mov_b32 m0, s49
	s_nop 0
	global_load_lds_dwordx4 v[204:205], off
	v_lshl_add_u64 v[204:205], s[24:25], 0, v[134:135]
	s_mov_b32 m0, s50
	s_nop 0
	global_load_lds_dwordx4 v[204:205], off
	s_waitcnt vmcnt(8)
	s_waitcnt lgkmcnt(0)
	s_barrier
	s_setprio 1
	s_waitcnt lgkmcnt(0)
	v_mfma_f32_16x16x32_bf16 v[70:73], v[140:143], v[172:175], v[70:73]
	v_mfma_f32_16x16x32_bf16 v[74:77], v[148:151], v[172:175], v[74:77]
	v_mfma_f32_16x16x32_bf16 v[86:89], v[140:143], v[180:183], v[86:89]
	v_mfma_f32_16x16x32_bf16 v[90:93], v[148:151], v[180:183], v[90:93]
	v_mfma_f32_16x16x32_bf16 v[102:105], v[140:143], v[188:191], v[102:105]
	v_mfma_f32_16x16x32_bf16 v[106:109], v[148:151], v[188:191], v[106:109]
	v_mfma_f32_16x16x32_bf16 v[130:133], v[140:143], v[196:199], v[130:133]
	v_mfma_f32_16x16x32_bf16 v[126:129], v[148:151], v[196:199], v[126:129]
	v_mfma_f32_16x16x32_bf16 v[70:73], v[144:147], v[176:179], v[70:73]
	v_mfma_f32_16x16x32_bf16 v[74:77], v[152:155], v[176:179], v[74:77]
	v_mfma_f32_16x16x32_bf16 v[86:89], v[144:147], v[184:187], v[86:89]
	v_mfma_f32_16x16x32_bf16 v[90:93], v[152:155], v[184:187], v[90:93]
	v_mfma_f32_16x16x32_bf16 v[102:105], v[144:147], v[192:195], v[102:105]
	v_mfma_f32_16x16x32_bf16 v[106:109], v[152:155], v[192:195], v[106:109]
	v_mfma_f32_16x16x32_bf16 v[130:133], v[144:147], v[200:203], v[130:133]
	v_mfma_f32_16x16x32_bf16 v[126:129], v[152:155], v[200:203], v[126:129]
	s_setprio 0
	s_setprio 1
	v_mfma_f32_16x16x32_bf16 v[78:81], v[156:159], v[172:175], v[78:81]
	v_mfma_f32_16x16x32_bf16 v[82:85], v[164:167], v[172:175], v[82:85]
	v_mfma_f32_16x16x32_bf16 v[94:97], v[156:159], v[180:183], v[94:97]
	v_mfma_f32_16x16x32_bf16 v[98:101], v[164:167], v[180:183], v[98:101]
	v_mfma_f32_16x16x32_bf16 v[110:113], v[156:159], v[188:191], v[110:113]
	v_mfma_f32_16x16x32_bf16 v[114:117], v[164:167], v[188:191], v[114:117]
	v_mfma_f32_16x16x32_bf16 v[122:125], v[156:159], v[196:199], v[122:125]
	v_mfma_f32_16x16x32_bf16 v[118:121], v[164:167], v[196:199], v[118:121]
	v_mfma_f32_16x16x32_bf16 v[78:81], v[160:163], v[176:179], v[78:81]
	v_mfma_f32_16x16x32_bf16 v[82:85], v[168:171], v[176:179], v[82:85]
	v_mfma_f32_16x16x32_bf16 v[94:97], v[160:163], v[184:187], v[94:97]
	v_mfma_f32_16x16x32_bf16 v[98:101], v[168:171], v[184:187], v[98:101]
	v_mfma_f32_16x16x32_bf16 v[110:113], v[160:163], v[192:195], v[110:113]
	v_mfma_f32_16x16x32_bf16 v[114:117], v[168:171], v[192:195], v[114:117]
	v_mfma_f32_16x16x32_bf16 v[122:125], v[160:163], v[200:203], v[122:125]
	v_mfma_f32_16x16x32_bf16 v[118:121], v[168:171], v[200:203], v[118:121]
	s_setprio 0
	s_barrier
	s_add_i32 s54, s54, 2
	s_add_u32 s19, s19, 0x100
	s_addc_u32 s33, s33, 0
	s_add_u32 s52, s52, 0x100
	s_addc_u32 s53, s53, 0
	s_cmp_gt_u32 s54, 61
	s_cbranch_scc0 .LBB0_251
	v_mov_b32_e32 v141, v0
	s_lshl_b32 s1, s0, 8
	s_mov_b64 s[24:25], s[84:85]
	s_add_i32 s1, s1, s43
	v_and_or_b32 v140, v141, 15, s1
	v_lshrrev_b32_e32 v141, 1, v141
	s_add_u32 s26, s24, s6
	v_and_or_b32 v148, v141, 24, s48
	s_addc_u32 s27, s25, s7
	v_ashrrev_i32_e32 v141, 31, v140
	v_lshl_add_u64 v[142:143], v[140:141], 2, s[26:27]
	s_mov_b64 s[26:27], 0x10000
	v_lshl_add_u64 v[144:145], v[142:143], 0, s[26:27]
	v_add_co_u32_e32 v142, vcc, s91, v142
	global_load_dword v146, v[144:145], off offset:512
	s_nop 0
	v_addc_co_u32_e32 v143, vcc, 0, v143, vcc
	global_load_dword v142, v[142:143], off
	s_cmp_lt_i32 s22, 8
	s_mov_b64 s[26:27], -1
	global_load_dword v205, v[144:145], off offset:64
	global_load_dword v204, v[144:145], off offset:128
	global_load_dword v203, v[144:145], off offset:192
	global_load_dword v202, v[144:145], off offset:576
	global_load_dword v201, v[144:145], off offset:640
	global_load_dword v200, v[144:145], off offset:704
	s_waitcnt vmcnt(0)
	v_fmamk_f32 v146, v146, 0x39800000, v246
	v_mul_f32_e32 v147, 0x4b800000, v146
	v_fmamk_f32 v142, v142, 0x39800000, v246
	v_cmp_gt_f32_e32 vcc, s95, v142
	v_mul_f32_e32 v143, 0x4b800000, v142
	s_nop 0
	v_cndmask_b32_e32 v142, v142, v143, vcc
	v_rsq_f32_e32 v142, v142
	s_nop 0
	v_mul_f32_e32 v143, 0x45800000, v142
	v_cndmask_b32_e32 v142, v142, v143, vcc
	v_pk_mul_f32 v[8:9], v[8:9], v[142:143] op_sel_hi:[1,0]
	v_pk_mul_f32 v[6:7], v[6:7], v[142:143] op_sel_hi:[1,0]
	v_pk_mul_f32 v[12:13], v[12:13], v[142:143] op_sel_hi:[1,0]
	v_pk_mul_f32 v[10:11], v[10:11], v[142:143] op_sel_hi:[1,0]
	v_pk_mul_f32 v[16:17], v[16:17], v[142:143] op_sel_hi:[1,0]
	v_pk_mul_f32 v[14:15], v[14:15], v[142:143] op_sel_hi:[1,0]
	v_pk_mul_f32 v[20:21], v[20:21], v[142:143] op_sel_hi:[1,0]
	v_pk_mul_f32 v[18:19], v[18:19], v[142:143] op_sel_hi:[1,0]
	s_waitcnt vmcnt(0)
	v_fmamk_f32 v142, v205, 0x39800000, v246
	v_cmp_gt_f32_e32 vcc, s95, v142
	v_mul_f32_e32 v143, 0x4b800000, v142
	s_nop 0
	v_cndmask_b32_e32 v142, v142, v143, vcc
	v_rsq_f32_e32 v142, v142
	s_nop 0
	v_mul_f32_e32 v143, 0x45800000, v142
	v_cndmask_b32_e32 v142, v142, v143, vcc
	v_pk_mul_f32 v[24:25], v[24:25], v[142:143] op_sel_hi:[1,0]
	v_pk_mul_f32 v[22:23], v[22:23], v[142:143] op_sel_hi:[1,0]
	v_pk_mul_f32 v[28:29], v[28:29], v[142:143] op_sel_hi:[1,0]
	v_pk_mul_f32 v[26:27], v[26:27], v[142:143] op_sel_hi:[1,0]
	v_pk_mul_f32 v[32:33], v[32:33], v[142:143] op_sel_hi:[1,0]
	v_pk_mul_f32 v[30:31], v[30:31], v[142:143] op_sel_hi:[1,0]
	v_pk_mul_f32 v[36:37], v[36:37], v[142:143] op_sel_hi:[1,0]
	v_pk_mul_f32 v[34:35], v[34:35], v[142:143] op_sel_hi:[1,0]
	s_waitcnt vmcnt(0)
	v_fmamk_f32 v142, v204, 0x39800000, v246
	v_cmp_gt_f32_e32 vcc, s95, v142
	v_mul_f32_e32 v143, 0x4b800000, v142
	s_nop 0
	v_cndmask_b32_e32 v142, v142, v143, vcc
	v_rsq_f32_e32 v142, v142
	s_nop 0
	v_mul_f32_e32 v143, 0x45800000, v142
	v_cndmask_b32_e32 v142, v142, v143, vcc
	v_pk_mul_f32 v[40:41], v[40:41], v[142:143] op_sel_hi:[1,0]
	v_pk_mul_f32 v[38:39], v[38:39], v[142:143] op_sel_hi:[1,0]
	v_pk_mul_f32 v[44:45], v[44:45], v[142:143] op_sel_hi:[1,0]
	v_pk_mul_f32 v[42:43], v[42:43], v[142:143] op_sel_hi:[1,0]
	v_pk_mul_f32 v[48:49], v[48:49], v[142:143] op_sel_hi:[1,0]
	v_pk_mul_f32 v[46:47], v[46:47], v[142:143] op_sel_hi:[1,0]
	v_pk_mul_f32 v[52:53], v[52:53], v[142:143] op_sel_hi:[1,0]
	v_pk_mul_f32 v[50:51], v[50:51], v[142:143] op_sel_hi:[1,0]
	s_waitcnt vmcnt(0)
	v_fmamk_f32 v142, v203, 0x39800000, v246
	v_cmp_gt_f32_e32 vcc, s95, v142
	v_mul_f32_e32 v143, 0x4b800000, v142
	s_nop 0
	v_cndmask_b32_e32 v142, v142, v143, vcc
	v_rsq_f32_e32 v142, v142
	s_nop 0
	v_mul_f32_e32 v143, 0x45800000, v142
	v_cndmask_b32_e32 v142, v142, v143, vcc
	v_cmp_gt_f32_e32 vcc, s95, v146
	v_pk_mul_f32 v[56:57], v[56:57], v[142:143] op_sel_hi:[1,0]
	v_pk_mul_f32 v[54:55], v[54:55], v[142:143] op_sel_hi:[1,0]
	v_cndmask_b32_e32 v146, v146, v147, vcc
	v_rsq_f32_e32 v146, v146
	v_pk_mul_f32 v[60:61], v[60:61], v[142:143] op_sel_hi:[1,0]
	v_pk_mul_f32 v[58:59], v[58:59], v[142:143] op_sel_hi:[1,0]
	v_pk_mul_f32 v[64:65], v[64:65], v[142:143] op_sel_hi:[1,0]
	v_mul_f32_e32 v147, 0x45800000, v146
	v_cndmask_b32_e32 v146, v146, v147, vcc
	v_pk_mul_f32 v[72:73], v[72:73], v[146:147] op_sel_hi:[1,0]
	v_pk_mul_f32 v[70:71], v[70:71], v[146:147] op_sel_hi:[1,0]
	v_pk_mul_f32 v[76:77], v[76:77], v[146:147] op_sel_hi:[1,0]
	v_pk_mul_f32 v[74:75], v[74:75], v[146:147] op_sel_hi:[1,0]
	v_pk_mul_f32 v[80:81], v[80:81], v[146:147] op_sel_hi:[1,0]
	v_pk_mul_f32 v[78:79], v[78:79], v[146:147] op_sel_hi:[1,0]
	v_pk_mul_f32 v[84:85], v[84:85], v[146:147] op_sel_hi:[1,0]
	v_pk_mul_f32 v[82:83], v[82:83], v[146:147] op_sel_hi:[1,0]
	v_pk_mul_f32 v[62:63], v[62:63], v[142:143] op_sel_hi:[1,0]
	v_pk_mul_f32 v[68:69], v[68:69], v[142:143] op_sel_hi:[1,0]
	v_pk_mul_f32 v[66:67], v[66:67], v[142:143] op_sel_hi:[1,0]
	v_add_u32_e32 v142, 0x80, v140
	v_ashrrev_i32_e32 v143, 31, v142
	s_waitcnt vmcnt(0)
	v_fmamk_f32 v146, v202, 0x39800000, v246
	v_cmp_gt_f32_e32 vcc, s95, v146
	v_mul_f32_e32 v147, 0x4b800000, v146
	s_nop 0
	v_cndmask_b32_e32 v146, v146, v147, vcc
	v_rsq_f32_e32 v146, v146
	s_nop 0
	v_mul_f32_e32 v147, 0x45800000, v146
	v_cndmask_b32_e32 v146, v146, v147, vcc
	v_pk_mul_f32 v[88:89], v[88:89], v[146:147] op_sel_hi:[1,0]
	v_pk_mul_f32 v[86:87], v[86:87], v[146:147] op_sel_hi:[1,0]
	v_pk_mul_f32 v[92:93], v[92:93], v[146:147] op_sel_hi:[1,0]
	v_pk_mul_f32 v[90:91], v[90:91], v[146:147] op_sel_hi:[1,0]
	v_pk_mul_f32 v[96:97], v[96:97], v[146:147] op_sel_hi:[1,0]
	v_pk_mul_f32 v[94:95], v[94:95], v[146:147] op_sel_hi:[1,0]
	v_pk_mul_f32 v[100:101], v[100:101], v[146:147] op_sel_hi:[1,0]
	v_pk_mul_f32 v[98:99], v[98:99], v[146:147] op_sel_hi:[1,0]
	s_waitcnt vmcnt(0)
	v_fmamk_f32 v146, v201, 0x39800000, v246
	v_cmp_gt_f32_e32 vcc, s95, v146
	v_mul_f32_e32 v147, 0x4b800000, v146
	s_waitcnt vmcnt(0)
	v_fmamk_f32 v144, v200, 0x39800000, v246
	v_cndmask_b32_e32 v146, v146, v147, vcc
	v_rsq_f32_e32 v146, v146
	v_mul_f32_e32 v145, 0x4b800000, v144
	v_mul_f32_e32 v147, 0x45800000, v146
	v_cndmask_b32_e32 v146, v146, v147, vcc
	v_cmp_gt_f32_e32 vcc, s95, v144
	v_pk_mul_f32 v[104:105], v[104:105], v[146:147] op_sel_hi:[1,0]
	v_pk_mul_f32 v[102:103], v[102:103], v[146:147] op_sel_hi:[1,0]
	v_cndmask_b32_e32 v144, v144, v145, vcc
	v_rsq_f32_e32 v144, v144
	v_pk_mul_f32 v[108:109], v[108:109], v[146:147] op_sel_hi:[1,0]
	v_pk_mul_f32 v[106:107], v[106:107], v[146:147] op_sel_hi:[1,0]
	v_pk_mul_f32 v[112:113], v[112:113], v[146:147] op_sel_hi:[1,0]
	v_mul_f32_e32 v145, 0x45800000, v144
	v_cndmask_b32_e32 v144, v144, v145, vcc
	v_pk_mul_f32 v[110:111], v[110:111], v[146:147] op_sel_hi:[1,0]
	v_pk_mul_f32 v[116:117], v[116:117], v[146:147] op_sel_hi:[1,0]
	v_pk_mul_f32 v[114:115], v[114:115], v[146:147] op_sel_hi:[1,0]
	v_pk_mul_f32 v[132:133], v[132:133], v[144:145] op_sel_hi:[1,0]
	v_pk_mul_f32 v[130:131], v[130:131], v[144:145] op_sel_hi:[1,0]
	v_pk_mul_f32 v[128:129], v[128:129], v[144:145] op_sel_hi:[1,0]
	v_pk_mul_f32 v[126:127], v[126:127], v[144:145] op_sel_hi:[1,0]
	v_pk_mul_f32 v[124:125], v[124:125], v[144:145] op_sel_hi:[1,0]
	v_pk_mul_f32 v[122:123], v[122:123], v[144:145] op_sel_hi:[1,0]
	v_pk_mul_f32 v[120:121], v[120:121], v[144:145] op_sel_hi:[1,0]
	v_pk_mul_f32 v[118:119], v[118:119], v[144:145] op_sel_hi:[1,0]
	s_cbranch_scc1 .LBB0_254
	v_mul_f32_e32 v145, 0xbfb8aa3b, v7
	v_mul_f32_e32 v146, 0xbfb8aa3b, v8
	v_exp_f32_e32 v145, v145
	v_exp_f32_e32 v146, v146
	v_mul_f32_e32 v144, 0xbfb8aa3b, v6
	v_exp_f32_e32 v144, v144
	v_add_f32_e32 v145, 1.0, v145
	v_add_f32_e32 v146, 1.0, v146
	v_rcp_f32_e32 v145, v145
	v_rcp_f32_e32 v149, v146
	v_add_f32_e32 v144, 1.0, v144
	v_mul_f32_e32 v146, 0xbfb8aa3b, v9
	v_mul_f32_e32 v147, v7, v145
	v_mul_f32_e32 v195, v8, v149
	v_mul_f32_e32 v145, 0xbfb8aa3b, v10
	v_mul_f32_e32 v149, 0xbfb8aa3b, v11
	v_rcp_f32_e32 v144, v144
	v_exp_f32_e32 v150, v146
	v_exp_f32_e32 v145, v145
	v_exp_f32_e32 v149, v149
	v_mul_f32_e32 v146, v6, v144
	v_add_f32_e32 v144, 1.0, v150
	v_add_f32_e32 v145, 1.0, v145
	v_add_f32_e32 v149, 1.0, v149
	v_mul_f32_e32 v150, 0xbfb8aa3b, v12
	v_rcp_f32_e32 v144, v144
	v_rcp_f32_e32 v145, v145
	v_rcp_f32_e32 v149, v149
	v_exp_f32_e32 v150, v150
	v_mul_f32_e32 v209, v9, v144
	v_mul_f32_e32 v144, v10, v145
	v_mul_f32_e32 v145, v11, v149
	v_add_f32_e32 v149, 1.0, v150
	v_mul_f32_e32 v150, 0xbfb8aa3b, v13
	v_exp_f32_e32 v150, v150
	v_mul_f32_e32 v151, 0xbfb8aa3b, v14
	v_exp_f32_e32 v151, v151
	v_mul_f32_e32 v240, 0xbfb8aa3b, v99
	v_add_f32_e32 v150, 1.0, v150
	v_rcp_f32_e32 v150, v150
	v_add_f32_e32 v151, 1.0, v151
	v_rcp_f32_e32 v151, v151
	v_exp_f32_e32 v240, v240
	v_mul_f32_e32 v206, v13, v150
	v_mul_f32_e32 v150, 0xbfb8aa3b, v16
	v_mul_f32_e32 v194, v14, v151
	v_exp_f32_e32 v150, v150
	v_mul_f32_e32 v151, 0xbfb8aa3b, v17
	v_exp_f32_e32 v151, v151
	v_mul_f32_e32 v152, 0xbfb8aa3b, v15
	v_rcp_f32_e32 v149, v149
	v_exp_f32_e32 v152, v152
	v_add_f32_e32 v150, 1.0, v150
	v_rcp_f32_e32 v150, v150
	v_add_f32_e32 v151, 1.0, v151
	v_add_f32_e32 v242, 1.0, v240
	v_cvt_pk_bf16_f32 v240, v146, v147
	v_mul_f32_e32 v146, 0xbfb8aa3b, v100
	v_rcp_f32_e32 v151, v151
	v_exp_f32_e32 v146, v146
	v_mul_f32_e32 v147, 0xbfb8aa3b, v101
	v_exp_f32_e32 v147, v147
	v_mul_f32_e32 v205, v12, v149
	v_add_f32_e32 v149, 1.0, v152
	v_mul_f32_e32 v152, 0xbfb8aa3b, v18
	s_lshl_b32 s1, s22, 8
	v_rcp_f32_e32 v149, v149
	v_exp_f32_e32 v152, v152
	v_mul_f32_e32 v203, v16, v150
	v_mul_f32_e32 v150, 0xbfb8aa3b, v19
	v_cvt_pk_bf16_f32 v241, v195, v209
	v_rcp_f32_e32 v195, v242
	s_addk_i32 s1, 0xf800
	v_cvt_pk_bf16_f32 v242, v144, v145
	v_cvt_pk_bf16_f32 v243, v205, v206
	v_mul_f32_e32 v205, 0xbfb8aa3b, v102
	v_mul_f32_e32 v204, v17, v151
	v_exp_f32_e32 v150, v150
	v_mul_f32_e32 v151, 0xbfb8aa3b, v20
	v_add_f32_e32 v146, 1.0, v146
	v_or_b32_e32 v144, s1, v148
	v_mov_b32_e32 v145, v4
	v_exp_f32_e32 v205, v205
	v_exp_f32_e32 v151, v151
	v_rcp_f32_e32 v209, v146
	v_add_f32_e32 v146, 1.0, v147
	v_lshl_add_u64 v[144:145], v[144:145], 1, s[24:25]
	s_mov_b64 s[26:27], 0x1b480000
	v_rcp_f32_e32 v244, v146
	v_lshl_add_u64 v[146:147], v[144:145], 0, s[26:27]
	v_lshlrev_b64 v[144:145], 13, v[140:141]
	v_mul_f32_e32 v202, v15, v149
	v_add_f32_e32 v149, 1.0, v152
	v_lshl_add_u64 v[144:145], v[146:147], 0, v[144:145]
	v_rcp_f32_e32 v149, v149
	v_add_f32_e32 v150, 1.0, v150
	global_store_dwordx4 v[144:145], v[240:243], off nt
	v_add_f32_e32 v205, 1.0, v205
	v_rcp_f32_e32 v150, v150
	v_mul_f32_e32 v240, 0xbfb8aa3b, v103
	v_add_f32_e32 v151, 1.0, v151
	v_exp_f32_e32 v240, v240
	v_cvt_pk_bf16_f32 v202, v194, v202
	v_cvt_pk_bf16_f32 v203, v203, v204
	v_rcp_f32_e32 v204, v205
	v_rcp_f32_e32 v151, v151
	v_mul_f32_e32 v152, 0xbfb8aa3b, v21
	v_mul_f32_e32 v200, v18, v149
	v_exp_f32_e32 v152, v152
	v_mul_f32_e32 v201, v19, v150
	v_add_f32_e32 v205, 1.0, v240
	v_mul_f32_e32 v240, 0xbfb8aa3b, v105
	v_mul_f32_e32 v241, v102, v204
	v_cvt_pk_bf16_f32 v204, v200, v201
	v_mul_f32_e32 v200, 0xbfb8aa3b, v106
	v_mul_f32_e32 v192, v20, v151
	v_mul_f32_e32 v151, 0xbfb8aa3b, v23
	v_rcp_f32_e32 v205, v205
	v_exp_f32_e32 v240, v240
	v_exp_f32_e32 v200, v200
	v_exp_f32_e32 v151, v151
	v_mul_f32_e32 v150, 0xbfb8aa3b, v22
	v_add_f32_e32 v149, 1.0, v152
	v_exp_f32_e32 v150, v150
	v_rcp_f32_e32 v149, v149
	v_mul_f32_e32 v242, v103, v205
	v_add_f32_e32 v205, 1.0, v240
	v_mul_f32_e32 v201, 0xbfb8aa3b, v107
	v_add_f32_e32 v200, 1.0, v200
	v_add_f32_e32 v151, 1.0, v151
	v_exp_f32_e32 v201, v201
	v_rcp_f32_e32 v240, v205
	v_rcp_f32_e32 v200, v200
	v_rcp_f32_e32 v151, v151
	v_add_f32_e32 v150, 1.0, v150
	v_rcp_f32_e32 v150, v150
	v_mul_f32_e32 v197, v21, v149
	v_mul_f32_e32 v152, 0xbfb8aa3b, v24
	v_add_f32_e32 v201, 1.0, v201
	v_cvt_pk_bf16_f32 v205, v192, v197
	v_mul_f32_e32 v197, v105, v240
	v_mul_f32_e32 v240, v106, v200
	v_mul_f32_e32 v200, 0xbfb8aa3b, v109
	v_exp_f32_e32 v152, v152
	v_mul_f32_e32 v181, v23, v151
	v_mul_f32_e32 v151, 0xbfb8aa3b, v26
	v_rcp_f32_e32 v201, v201
	v_exp_f32_e32 v200, v200
	v_exp_f32_e32 v151, v151
	v_mul_f32_e32 v179, v22, v150
	v_mul_f32_e32 v150, 0xbfb8aa3b, v25
	v_exp_f32_e32 v150, v150
	v_add_f32_e32 v149, 1.0, v152
	v_mul_f32_e32 v152, 0xbfb8aa3b, v27
	v_mul_f32_e32 v243, v107, v201
	v_mul_f32_e32 v201, 0xbfb8aa3b, v110
	v_add_f32_e32 v200, 1.0, v200
	v_rcp_f32_e32 v149, v149
	v_add_f32_e32 v151, 1.0, v151
	v_exp_f32_e32 v152, v152
	v_exp_f32_e32 v201, v201
	v_rcp_f32_e32 v200, v200
	v_rcp_f32_e32 v151, v151
	v_add_f32_e32 v150, 1.0, v150
	v_rcp_f32_e32 v150, v150
	global_store_dwordx4 v[144:145], v[202:205], off offset:256 nt
	v_mul_f32_e32 v188, v24, v149
	v_add_f32_e32 v149, 1.0, v152
	v_mul_f32_e32 v202, 0xbfb8aa3b, v111
	v_add_f32_e32 v201, 1.0, v201
	v_exp_f32_e32 v202, v202
	v_mul_f32_e32 v204, v109, v200
	v_cvt_pk_bf16_f32 v200, v179, v181
	v_mul_f32_e32 v181, 0xbfb8aa3b, v113
	v_mul_f32_e32 v178, v26, v151
	v_mul_f32_e32 v151, 0xbfb8aa3b, v29
	v_rcp_f32_e32 v149, v149
	v_rcp_f32_e32 v201, v201
	v_exp_f32_e32 v181, v181
	v_exp_f32_e32 v151, v151
	v_mul_f32_e32 v179, 0xbfb8aa3b, v112
	v_mul_f32_e32 v189, v25, v150
	v_mul_f32_e32 v150, 0xbfb8aa3b, v28
	v_exp_f32_e32 v179, v179
	v_exp_f32_e32 v150, v150
	v_add_f32_e32 v202, 1.0, v202
	v_mul_f32_e32 v187, v27, v149
	v_mul_f32_e32 v205, v110, v201
	v_cvt_pk_bf16_f32 v201, v188, v189
	v_rcp_f32_e32 v188, v202
	v_add_f32_e32 v181, 1.0, v181
	v_cvt_pk_bf16_f32 v202, v178, v187
	v_mul_f32_e32 v178, 0xbfb8aa3b, v114
	v_add_f32_e32 v151, 1.0, v151
	v_rcp_f32_e32 v181, v181
	v_exp_f32_e32 v178, v178
	v_rcp_f32_e32 v151, v151
	v_add_f32_e32 v179, 1.0, v179
	v_add_f32_e32 v150, 1.0, v150
	v_rcp_f32_e32 v179, v179
	v_rcp_f32_e32 v150, v150
	v_mul_f32_e32 v245, v113, v181
	v_add_f32_e32 v181, 1.0, v178
	v_mul_f32_e32 v178, 0xbfb8aa3b, v115
	v_mul_f32_e32 v182, v29, v151
	v_mul_f32_e32 v151, 0xbfb8aa3b, v32
	v_exp_f32_e32 v248, v178
	v_or_b32_e32 v178, 16, v140
	v_exp_f32_e32 v151, v151
	v_mul_f32_e32 v206, v100, v209
	v_mul_f32_e32 v209, v101, v244
	v_mul_f32_e32 v244, v112, v179
	v_ashrrev_i32_e32 v179, 31, v178
	v_mul_f32_e32 v152, 0xbfb8aa3b, v30
	v_mul_f32_e32 v180, v28, v150
	v_mul_f32_e32 v150, 0xbfb8aa3b, v31
	v_lshlrev_b64 v[178:179], 13, v[178:179]
	v_exp_f32_e32 v152, v152
	v_exp_f32_e32 v150, v150
	v_mul_f32_e32 v187, v111, v188
	v_lshl_add_u64 v[188:189], v[146:147], 0, v[178:179]
	v_mul_f32_e32 v178, 0xbfb8aa3b, v116
	v_exp_f32_e32 v178, v178
	v_add_f32_e32 v151, 1.0, v151
	v_rcp_f32_e32 v151, v151
	v_add_f32_e32 v149, 1.0, v152
	v_add_f32_e32 v150, 1.0, v150
	v_rcp_f32_e32 v149, v149
	v_rcp_f32_e32 v150, v150
	v_add_f32_e32 v178, 1.0, v178
	v_rcp_f32_e32 v178, v178
	v_mul_f32_e32 v173, v32, v151
	v_mul_f32_e32 v151, 0xbfb8aa3b, v35
	v_exp_f32_e32 v151, v151
	v_mul_f32_e32 v152, 0xbfb8aa3b, v33
	v_mul_f32_e32 v170, v30, v149
	v_mul_f32_e32 v172, v31, v150
	v_mul_f32_e32 v150, 0xbfb8aa3b, v34
	v_exp_f32_e32 v152, v152
	v_exp_f32_e32 v150, v150
	v_cvt_pk_bf16_f32 v203, v180, v182
	global_store_dwordx4 v[188:189], v[200:203], off nt
	v_add_f32_e32 v151, 1.0, v151
	v_rcp_f32_e32 v151, v151
	v_mul_f32_e32 v201, v116, v178
	v_cvt_pk_bf16_f32 v178, v170, v172
	v_mul_f32_e32 v170, 0xbfb8aa3b, v130
	v_exp_f32_e32 v170, v170
	v_add_f32_e32 v149, 1.0, v152
	v_add_f32_e32 v150, 1.0, v150
	v_rcp_f32_e32 v149, v149
	v_rcp_f32_e32 v150, v150
	v_add_f32_e32 v170, 1.0, v170
	v_rcp_f32_e32 v179, v181
	v_rcp_f32_e32 v170, v170
	v_mul_f32_e32 v152, 0xbfb8aa3b, v36
	v_mul_f32_e32 v169, v35, v151
	v_mul_f32_e32 v151, 0xbfb8aa3b, v38
	v_exp_f32_e32 v152, v152
	v_exp_f32_e32 v151, v151
	v_add_f32_e32 v180, 1.0, v248
	v_mul_f32_e32 v181, 0xbfb8aa3b, v117
	v_mul_f32_e32 v183, v33, v149
	v_mul_f32_e32 v168, v34, v150
	v_mul_f32_e32 v150, 0xbfb8aa3b, v37
	v_rcp_f32_e32 v180, v180
	v_exp_f32_e32 v181, v181
	v_exp_f32_e32 v150, v150
	v_mul_f32_e32 v182, v114, v179
	v_cvt_pk_bf16_f32 v179, v173, v183
	v_mul_f32_e32 v183, v130, v170
	v_mul_f32_e32 v170, 0xbfb8aa3b, v126
	v_exp_f32_e32 v170, v170
	v_add_f32_e32 v149, 1.0, v152
	v_add_f32_e32 v151, 1.0, v151
	v_rcp_f32_e32 v149, v149
	v_rcp_f32_e32 v151, v151
	v_mul_f32_e32 v200, v115, v180
	v_add_f32_e32 v180, 1.0, v181
	v_add_f32_e32 v150, 1.0, v150
	v_rcp_f32_e32 v173, v180
	v_cvt_pk_bf16_f32 v180, v168, v169
	v_mul_f32_e32 v168, 0xbfb8aa3b, v132
	v_mul_f32_e32 v169, 0xbfb8aa3b, v133
	v_rcp_f32_e32 v150, v150
	v_exp_f32_e32 v168, v168
	v_exp_f32_e32 v169, v169
	v_add_f32_e32 v170, 1.0, v170
	v_rcp_f32_e32 v170, v170
	v_mul_f32_e32 v171, v36, v149
	v_mul_f32_e32 v149, v38, v151
	v_mul_f32_e32 v151, 0xbfb8aa3b, v40
	v_mul_f32_e32 v152, 0xbfb8aa3b, v39
	v_exp_f32_e32 v151, v151
	v_exp_f32_e32 v152, v152
	v_mul_f32_e32 v174, v37, v150
	v_add_f32_e32 v168, 1.0, v168
	v_cvt_pk_bf16_f32 v181, v171, v174
	v_add_f32_e32 v169, 1.0, v169
	v_mul_f32_e32 v171, 0xbfb8aa3b, v127
	v_rcp_f32_e32 v168, v168
	v_rcp_f32_e32 v169, v169
	v_exp_f32_e32 v171, v171
	v_mul_f32_e32 v203, v126, v170
	v_mul_f32_e32 v170, 0xbfb8aa3b, v129
	v_exp_f32_e32 v170, v170
	v_add_f32_e32 v151, 1.0, v151
	v_add_f32_e32 v150, 1.0, v152
	v_mul_f32_e32 v152, 0xbfb8aa3b, v41
	v_rcp_f32_e32 v151, v151
	v_exp_f32_e32 v152, v152
	v_mul_f32_e32 v174, v132, v168
	v_mul_f32_e32 v202, v133, v169
	v_add_f32_e32 v168, 1.0, v171
	v_mul_f32_e32 v169, 0xbfb8aa3b, v128
	v_exp_f32_e32 v169, v169
	v_rcp_f32_e32 v168, v168
	v_add_f32_e32 v170, 1.0, v170
	v_mul_f32_e32 v171, 0xbfb8aa3b, v122
	v_rcp_f32_e32 v170, v170
	v_exp_f32_e32 v171, v171
	v_mul_f32_e32 v153, 0xbfb8aa3b, v42
	v_mul_f32_e32 v154, v40, v151
	v_mul_f32_e32 v151, 0xbfb8aa3b, v43
	v_rcp_f32_e32 v150, v150
	v_add_f32_e32 v152, 1.0, v152
	v_exp_f32_e32 v156, v153
	v_exp_f32_e32 v151, v151
	v_rcp_f32_e32 v152, v152
	global_store_dwordx4 v[188:189], v[178:181], off offset:256 nt
	v_add_f32_e32 v169, 1.0, v169
	v_rcp_f32_e32 v169, v169
	v_mul_f32_e32 v178, v127, v168
	v_mul_f32_e32 v168, 0xbfb8aa3b, v123
	v_mul_f32_e32 v180, v129, v170
	v_add_f32_e32 v170, 1.0, v171
	v_exp_f32_e32 v171, v168
	v_mul_f32_e32 v153, v39, v150
	v_add_f32_e32 v150, 1.0, v156
	v_add_f32_e32 v151, 1.0, v151
	v_mul_f32_e32 v156, 0xbfb8aa3b, v45
	v_mul_f32_e32 v155, v41, v152
	v_mul_f32_e32 v152, 0xbfb8aa3b, v44
	v_rcp_f32_e32 v150, v150
	v_rcp_f32_e32 v151, v151
	v_exp_f32_e32 v158, v156
	v_exp_f32_e32 v152, v152
	v_mul_f32_e32 v179, v128, v169
	v_cvt_pk_bf16_f32 v168, v149, v153
	v_cvt_pk_bf16_f32 v169, v154, v155
	v_add_f32_e32 v154, 1.0, v171
	v_mul_f32_e32 v155, 0xbfb8aa3b, v125
	v_rcp_f32_e32 v153, v170
	v_rcp_f32_e32 v154, v154
	v_exp_f32_e32 v155, v155
	v_mul_f32_e32 v156, v42, v150
	v_mul_f32_e32 v157, v43, v151
	v_add_f32_e32 v150, 1.0, v158
	v_mul_f32_e32 v151, 0xbfb8aa3b, v46
	v_mul_f32_e32 v158, 0xbfb8aa3b, v47
	v_add_f32_e32 v152, 1.0, v152
	v_exp_f32_e32 v151, v151
	v_exp_f32_e32 v158, v158
	v_rcp_f32_e32 v152, v152
	v_mul_f32_e32 v185, 0xbfb8aa3b, v61
	v_mul_f32_e32 v181, v122, v153
	v_mul_f32_e32 v188, v123, v154
	v_add_f32_e32 v153, 1.0, v155
	v_mul_f32_e32 v154, 0xbfb8aa3b, v118
	v_rcp_f32_e32 v150, v150
	v_exp_f32_e32 v185, v185
	v_mul_f32_e32 v186, 0xbfb8aa3b, v62
	v_rcp_f32_e32 v153, v153
	v_exp_f32_e32 v154, v154
	v_mul_f32_e32 v184, 0xbfb8aa3b, v60
	v_exp_f32_e32 v186, v186
	v_add_f32_e32 v151, 1.0, v151
	v_add_f32_e32 v158, 1.0, v158
	v_mul_f32_e32 v159, 0xbfb8aa3b, v48
	v_exp_f32_e32 v184, v184
	v_mul_f32_e32 v210, 0xbfb8aa3b, v71
	v_mul_f32_e32 v155, 0xbfb8aa3b, v119
	v_mul_f32_e32 v152, v44, v152
	v_rcp_f32_e32 v151, v151
	v_rcp_f32_e32 v158, v158
	v_exp_f32_e32 v159, v159
	v_mul_f32_e32 v207, 0xbfb8aa3b, v69
	v_mul_f32_e32 v208, 0xbfb8aa3b, v70
	v_exp_f32_e32 v210, v210
	v_mul_f32_e32 v226, 0xbfb8aa3b, v85
	v_exp_f32_e32 v155, v155
	v_mul_f32_e32 v161, v45, v150
	v_add_f32_e32 v185, 1.0, v185
	v_exp_f32_e32 v207, v207
	v_exp_f32_e32 v208, v208
	v_exp_f32_e32 v226, v226
	v_mul_f32_e32 v227, 0xbfb8aa3b, v86
	v_cvt_pk_bf16_f32 v170, v156, v157
	v_mul_f32_e32 v156, v125, v153
	v_add_f32_e32 v153, 1.0, v154
	v_cvt_pk_bf16_f32 v171, v152, v161
	v_or_b32_e32 v152, 32, v140
	v_rcp_f32_e32 v190, v185
	v_add_f32_e32 v185, 1.0, v186
	v_mul_f32_e32 v225, 0xbfb8aa3b, v84
	v_exp_f32_e32 v227, v227
	v_mul_f32_e32 v236, 0xbfb8aa3b, v95
	v_rcp_f32_e32 v157, v153
	v_ashrrev_i32_e32 v153, 31, v152
	v_add_f32_e32 v184, 1.0, v184
	v_rcp_f32_e32 v191, v185
	v_mul_f32_e32 v185, 0xbfb8aa3b, v63
	v_exp_f32_e32 v225, v225
	v_mul_f32_e32 v234, 0xbfb8aa3b, v93
	v_mul_f32_e32 v235, 0xbfb8aa3b, v94
	v_exp_f32_e32 v236, v236
	v_lshlrev_b64 v[152:153], 13, v[152:153]
	v_mul_f32_e32 v150, v46, v151
	v_mul_f32_e32 v151, v47, v158
	v_add_f32_e32 v158, 1.0, v159
	v_mul_f32_e32 v159, 0xbfb8aa3b, v49
	v_mul_f32_e32 v160, 0xbfb8aa3b, v50
	v_mul_f32_e32 v162, 0xbfb8aa3b, v51
	v_mul_f32_e32 v163, 0xbfb8aa3b, v52
	v_mul_f32_e32 v164, 0xbfb8aa3b, v53
	v_rcp_f32_e32 v184, v184
	v_exp_f32_e32 v193, v185
	v_add_f32_e32 v210, 1.0, v210
	v_exp_f32_e32 v234, v234
	v_exp_f32_e32 v235, v235
	v_add_f32_e32 v189, 1.0, v155
	v_lshl_add_u64 v[154:155], v[146:147], 0, v[152:153]
	v_mul_f32_e32 v152, 0xbfb8aa3b, v120
	v_mul_f32_e32 v153, 0xbfb8aa3b, v121
	v_exp_f32_e32 v159, v159
	v_exp_f32_e32 v160, v160
	v_exp_f32_e32 v162, v162
	v_exp_f32_e32 v163, v163
	v_exp_f32_e32 v164, v164
	v_add_f32_e32 v207, 1.0, v207
	v_add_f32_e32 v208, 1.0, v208
	v_rcp_f32_e32 v211, v210
	v_mul_f32_e32 v210, 0xbfb8aa3b, v72
	v_add_f32_e32 v226, 1.0, v226
	v_exp_f32_e32 v152, v152
	v_exp_f32_e32 v153, v153
	v_rcp_f32_e32 v207, v207
	v_rcp_f32_e32 v208, v208
	v_exp_f32_e32 v212, v210
	v_rcp_f32_e32 v228, v226
	v_add_f32_e32 v226, 1.0, v227
	v_mul_f32_e32 v165, 0xbfb8aa3b, v54
	v_mul_f32_e32 v166, 0xbfb8aa3b, v55
	v_mul_f32_e32 v167, 0xbfb8aa3b, v56
	v_mul_f32_e32 v175, 0xbfb8aa3b, v57
	v_add_f32_e32 v225, 1.0, v225
	v_rcp_f32_e32 v229, v226
	v_mul_f32_e32 v226, 0xbfb8aa3b, v87
	v_add_f32_e32 v236, 1.0, v236
	v_exp_f32_e32 v165, v165
	v_exp_f32_e32 v166, v166
	v_exp_f32_e32 v167, v167
	v_exp_f32_e32 v175, v175
	v_mul_f32_e32 v176, 0xbfb8aa3b, v58
	v_mul_f32_e32 v177, 0xbfb8aa3b, v59
	v_mul_f32_e32 v185, v60, v184
	v_mul_f32_e32 v186, v61, v190
	v_mul_f32_e32 v184, v62, v191
	v_add_f32_e32 v190, 1.0, v193
	v_mul_f32_e32 v191, 0xbfb8aa3b, v64
	v_mul_f32_e32 v193, 0xbfb8aa3b, v65
	v_rcp_f32_e32 v225, v225
	v_exp_f32_e32 v230, v226
	v_add_f32_e32 v234, 1.0, v234
	v_add_f32_e32 v235, 1.0, v235
	v_rcp_f32_e32 v237, v236
	v_mul_f32_e32 v236, 0xbfb8aa3b, v96
	v_add_f32_e32 v159, 1.0, v159
	v_add_f32_e32 v160, 1.0, v160
	v_add_f32_e32 v162, 1.0, v162
	v_add_f32_e32 v163, 1.0, v163
	v_add_f32_e32 v164, 1.0, v164
	v_exp_f32_e32 v176, v176
	v_exp_f32_e32 v177, v177
	v_exp_f32_e32 v191, v191
	v_exp_f32_e32 v193, v193
	v_mul_f32_e32 v196, 0xbfb8aa3b, v66
	v_mul_f32_e32 v198, 0xbfb8aa3b, v67
	v_mul_f32_e32 v199, 0xbfb8aa3b, v68
	v_rcp_f32_e32 v234, v234
	v_rcp_f32_e32 v235, v235
	v_exp_f32_e32 v238, v236
	v_add_f32_e32 v152, 1.0, v152
	v_add_f32_e32 v153, 1.0, v153
	v_rcp_f32_e32 v158, v158
	v_rcp_f32_e32 v159, v159
	v_rcp_f32_e32 v160, v160
	v_rcp_f32_e32 v162, v162
	v_rcp_f32_e32 v163, v163
	v_rcp_f32_e32 v164, v164
	v_exp_f32_e32 v196, v196
	v_exp_f32_e32 v198, v198
	v_exp_f32_e32 v199, v199
	v_mul_f32_e32 v210, v69, v207
	v_mul_f32_e32 v207, v70, v208
	v_mul_f32_e32 v208, v71, v211
	v_add_f32_e32 v211, 1.0, v212
	v_mul_f32_e32 v212, 0xbfb8aa3b, v73
	v_mul_f32_e32 v213, 0xbfb8aa3b, v74
	v_mul_f32_e32 v216, 0xbfb8aa3b, v75
	v_mul_f32_e32 v217, 0xbfb8aa3b, v76
	v_mul_f32_e32 v218, 0xbfb8aa3b, v77
	v_rcp_f32_e32 v152, v152
	v_rcp_f32_e32 v153, v153
	v_exp_f32_e32 v212, v212
	v_exp_f32_e32 v213, v213
	v_exp_f32_e32 v216, v216
	v_exp_f32_e32 v217, v217
	v_exp_f32_e32 v218, v218
	v_mul_f32_e32 v219, 0xbfb8aa3b, v78
	v_mul_f32_e32 v220, 0xbfb8aa3b, v79
	v_mul_f32_e32 v221, 0xbfb8aa3b, v80
	v_mul_f32_e32 v222, 0xbfb8aa3b, v81
	v_mul_f32_e32 v223, 0xbfb8aa3b, v82
	v_mul_f32_e32 v224, 0xbfb8aa3b, v83
	v_add_f32_e32 v165, 1.0, v165
	v_add_f32_e32 v166, 1.0, v166
	v_add_f32_e32 v167, 1.0, v167
	v_add_f32_e32 v175, 1.0, v175
	v_exp_f32_e32 v219, v219
	v_exp_f32_e32 v220, v220
	v_exp_f32_e32 v221, v221
	v_exp_f32_e32 v222, v222
	v_exp_f32_e32 v223, v223
	v_exp_f32_e32 v224, v224
	v_mul_f32_e32 v226, v84, v225
	v_mul_f32_e32 v227, v85, v228
	v_mul_f32_e32 v225, v86, v229
	v_add_f32_e32 v228, 1.0, v230
	v_mul_f32_e32 v229, 0xbfb8aa3b, v88
	v_mul_f32_e32 v230, 0xbfb8aa3b, v89
	v_mul_f32_e32 v231, 0xbfb8aa3b, v90
	v_mul_f32_e32 v232, 0xbfb8aa3b, v91
	v_mul_f32_e32 v233, 0xbfb8aa3b, v92
	v_rcp_f32_e32 v165, v165
	v_rcp_f32_e32 v166, v166
	v_rcp_f32_e32 v167, v167
	v_rcp_f32_e32 v175, v175
	v_add_f32_e32 v176, 1.0, v176
	v_add_f32_e32 v177, 1.0, v177
	v_add_f32_e32 v191, 1.0, v191
	v_add_f32_e32 v193, 1.0, v193
	v_exp_f32_e32 v229, v229
	v_exp_f32_e32 v230, v230
	v_exp_f32_e32 v231, v231
	v_exp_f32_e32 v232, v232
	v_exp_f32_e32 v233, v233
	v_mul_f32_e32 v236, v93, v234
	v_mul_f32_e32 v234, v94, v235
	v_mul_f32_e32 v235, v95, v237
	v_add_f32_e32 v237, 1.0, v238
	v_mul_f32_e32 v238, 0xbfb8aa3b, v97
	v_mul_f32_e32 v239, 0xbfb8aa3b, v98
	global_store_dwordx4 v[154:155], v[168:171], off nt
	v_cvt_pk_bf16_f32 v150, v150, v151
	v_mul_f32_e32 v158, v48, v158
	v_mul_f32_e32 v159, v49, v159
	v_mul_f32_e32 v160, v50, v160
	v_mul_f32_e32 v162, v51, v162
	v_mul_f32_e32 v163, v52, v163
	v_mul_f32_e32 v164, v53, v164
	v_rcp_f32_e32 v176, v176
	v_rcp_f32_e32 v177, v177
	v_rcp_f32_e32 v190, v190
	v_rcp_f32_e32 v191, v191
	v_rcp_f32_e32 v193, v193
	v_add_f32_e32 v196, 1.0, v196
	v_add_f32_e32 v198, 1.0, v198
	v_add_f32_e32 v199, 1.0, v199
	v_exp_f32_e32 v238, v238
	v_exp_f32_e32 v239, v239
	v_mul_f32_e32 v194, 0xbfb8aa3b, v104
	v_mul_f32_e32 v192, 0xbfb8aa3b, v108
	v_mul_f32_e32 v168, v120, v152
	v_mul_f32_e32 v169, v121, v153
	v_cvt_pk_bf16_f32 v151, v158, v159
	v_cvt_pk_bf16_f32 v152, v160, v162
	v_cvt_pk_bf16_f32 v153, v163, v164
	global_store_dwordx4 v[154:155], v[150:153], off offset:256 nt
	v_rcp_f32_e32 v196, v196
	v_rcp_f32_e32 v198, v198
	v_or_b32_e32 v150, 48, v140
	v_rcp_f32_e32 v199, v199
	v_add_f32_e32 v212, 1.0, v212
	v_add_f32_e32 v213, 1.0, v213
	v_add_f32_e32 v216, 1.0, v216
	v_add_f32_e32 v217, 1.0, v217
	v_add_f32_e32 v218, 1.0, v218
	v_exp_f32_e32 v194, v194
	v_exp_f32_e32 v192, v192
	v_ashrrev_i32_e32 v151, 31, v150
	v_rcp_f32_e32 v211, v211
	v_rcp_f32_e32 v212, v212
	v_rcp_f32_e32 v213, v213
	v_rcp_f32_e32 v216, v216
	v_rcp_f32_e32 v217, v217
	v_rcp_f32_e32 v218, v218
	v_add_f32_e32 v219, 1.0, v219
	v_add_f32_e32 v220, 1.0, v220
	v_add_f32_e32 v221, 1.0, v221
	v_add_f32_e32 v222, 1.0, v222
	v_add_f32_e32 v223, 1.0, v223
	v_add_f32_e32 v224, 1.0, v224
	v_mul_f32_e32 v172, 0xbfb8aa3b, v131
	v_mul_f32_e32 v149, 0xbfb8aa3b, v124
	v_lshlrev_b64 v[150:151], 13, v[150:151]
	v_mul_f32_e32 v165, v54, v165
	v_mul_f32_e32 v166, v55, v166
	v_mul_f32_e32 v167, v56, v167
	v_mul_f32_e32 v175, v57, v175
	v_rcp_f32_e32 v219, v219
	v_rcp_f32_e32 v220, v220
	v_rcp_f32_e32 v221, v221
	v_rcp_f32_e32 v222, v222
	v_rcp_f32_e32 v223, v223
	v_rcp_f32_e32 v224, v224
	v_add_f32_e32 v229, 1.0, v229
	v_add_f32_e32 v230, 1.0, v230
	v_add_f32_e32 v231, 1.0, v231
	v_add_f32_e32 v232, 1.0, v232
	v_add_f32_e32 v233, 1.0, v233
	v_exp_f32_e32 v172, v172
	v_exp_f32_e32 v149, v149
	v_lshl_add_u64 v[154:155], v[146:147], 0, v[150:151]
	v_cvt_pk_bf16_f32 v150, v165, v166
	v_cvt_pk_bf16_f32 v151, v167, v175
	v_mul_f32_e32 v176, v58, v176
	v_mul_f32_e32 v177, v59, v177
	v_mul_f32_e32 v190, v63, v190
	v_mul_f32_e32 v191, v64, v191
	v_mul_f32_e32 v193, v65, v193
	v_rcp_f32_e32 v228, v228
	v_rcp_f32_e32 v229, v229
	v_rcp_f32_e32 v230, v230
	v_rcp_f32_e32 v231, v231
	v_rcp_f32_e32 v232, v232
	v_rcp_f32_e32 v233, v233
	v_add_f32_e32 v238, 1.0, v238
	v_add_f32_e32 v239, 1.0, v239
	v_cvt_pk_bf16_f32 v152, v176, v177
	v_cvt_pk_bf16_f32 v153, v185, v186
	global_store_dwordx4 v[154:155], v[150:153], off nt
	v_mul_f32_e32 v196, v66, v196
	v_mul_f32_e32 v198, v67, v198
	v_cvt_pk_bf16_f32 v150, v184, v190
	v_cvt_pk_bf16_f32 v151, v191, v193
	v_mul_f32_e32 v199, v68, v199
	v_rcp_f32_e32 v237, v237
	v_rcp_f32_e32 v238, v238
	v_rcp_f32_e32 v239, v239
	v_add_f32_e32 v194, 1.0, v194
	v_add_f32_e32 v192, 1.0, v192
	v_cvt_pk_bf16_f32 v152, v196, v198
	v_cvt_pk_bf16_f32 v153, v199, v210
	global_store_dwordx4 v[154:155], v[150:153], off offset:256 nt
	v_mul_f32_e32 v211, v72, v211
	v_mul_f32_e32 v212, v73, v212
	v_lshlrev_b64 v[150:151], 13, v[142:143]
	v_mul_f32_e32 v213, v74, v213
	v_mul_f32_e32 v216, v75, v216
	v_mul_f32_e32 v217, v76, v217
	v_mul_f32_e32 v218, v77, v218
	v_rcp_f32_e32 v194, v194
	v_rcp_f32_e32 v192, v192
	v_lshl_add_u64 v[146:147], v[146:147], 0, v[150:151]
	v_cvt_pk_bf16_f32 v150, v207, v208
	v_cvt_pk_bf16_f32 v151, v211, v212
	v_cvt_pk_bf16_f32 v152, v213, v216
	v_cvt_pk_bf16_f32 v153, v217, v218
	v_add_co_u32_e32 v154, vcc, s72, v144
	v_mul_f32_e32 v219, v78, v219
	v_mul_f32_e32 v220, v79, v220
	v_mul_f32_e32 v221, v80, v221
	v_mul_f32_e32 v222, v81, v222
	v_mul_f32_e32 v223, v82, v223
	v_mul_f32_e32 v224, v83, v224
	v_add_f32_e32 v172, 1.0, v172
	v_add_f32_e32 v149, 1.0, v149
	global_store_dwordx4 v[146:147], v[150:153], off nt
	s_mov_b64 s[26:27], 0x120000
	v_addc_co_u32_e32 v155, vcc, 0, v145, vcc
	v_cvt_pk_bf16_f32 v150, v219, v220
	v_cvt_pk_bf16_f32 v151, v221, v222
	v_cvt_pk_bf16_f32 v152, v223, v224
	v_cvt_pk_bf16_f32 v153, v226, v227
	global_store_dwordx4 v[146:147], v[150:153], off offset:256 nt
	v_mul_f32_e32 v228, v87, v228
	v_mul_f32_e32 v229, v88, v229
	v_mul_f32_e32 v230, v89, v230
	v_mul_f32_e32 v231, v90, v231
	v_mul_f32_e32 v232, v91, v232
	v_mul_f32_e32 v233, v92, v233
	v_rcp_f32_e32 v172, v172
	v_rcp_f32_e32 v149, v149
	v_rcp_f32_e32 v161, v189
	v_lshl_add_u64 v[146:147], v[144:145], 0, s[26:27]
	v_cvt_pk_bf16_f32 v150, v225, v228
	v_cvt_pk_bf16_f32 v151, v229, v230
	v_cvt_pk_bf16_f32 v152, v231, v232
	v_cvt_pk_bf16_f32 v153, v233, v236
	global_store_dwordx4 v[154:155], v[150:153], off nt
	s_mov_b64 s[26:27], 0x140000
	v_add_co_u32_e32 v154, vcc, s73, v144
	v_mul_f32_e32 v237, v96, v237
	v_mul_f32_e32 v238, v97, v238
	v_mul_f32_e32 v239, v98, v239
	v_mul_f32_e32 v195, v99, v195
	v_cvt_pk_bf16_f32 v150, v234, v235
	v_cvt_pk_bf16_f32 v151, v237, v238
	v_cvt_pk_bf16_f32 v152, v239, v195
	v_cvt_pk_bf16_f32 v153, v206, v209
	global_store_dwordx4 v[146:147], v[150:153], off offset:256 nt
	v_lshl_add_u64 v[146:147], v[144:145], 0, s[26:27]
	v_addc_co_u32_e32 v155, vcc, 0, v145, vcc
	s_mov_b64 s[26:27], 0x160000
	v_mul_f32_e32 v194, v104, v194
	v_mul_f32_e32 v192, v108, v192
	v_cvt_pk_bf16_f32 v150, v241, v242
	v_cvt_pk_bf16_f32 v151, v194, v197
	v_cvt_pk_bf16_f32 v152, v240, v243
	v_cvt_pk_bf16_f32 v153, v192, v204
	global_store_dwordx4 v[154:155], v[150:153], off nt
	v_lshl_add_u64 v[154:155], v[144:145], 0, s[26:27]
	v_add_co_u32_e32 v144, vcc, 0x160000, v144
	v_mul_f32_e32 v173, v117, v173
	v_cvt_pk_bf16_f32 v150, v205, v187
	v_cvt_pk_bf16_f32 v151, v244, v245
	v_cvt_pk_bf16_f32 v152, v182, v200
	v_cvt_pk_bf16_f32 v153, v201, v173
	global_store_dwordx4 v[146:147], v[150:153], off offset:256 nt
	v_addc_co_u32_e32 v145, vcc, 0, v145, vcc
	v_mul_f32_e32 v172, v131, v172
	v_mul_f32_e32 v149, v124, v149
	v_mul_f32_e32 v157, v118, v157
	v_mul_f32_e32 v161, v119, v161
	v_cvt_pk_bf16_f32 v150, v183, v172
	v_cvt_pk_bf16_f32 v151, v174, v202
	v_cvt_pk_bf16_f32 v152, v203, v178
	v_cvt_pk_bf16_f32 v153, v179, v180
	global_store_dwordx4 v[144:145], v[150:153], off nt
	v_cvt_pk_bf16_f32 v144, v181, v188
	v_cvt_pk_bf16_f32 v145, v149, v156
	v_cvt_pk_bf16_f32 v146, v157, v161
	v_cvt_pk_bf16_f32 v147, v168, v169
	global_store_dwordx4 v[154:155], v[144:147], off offset:256 nt
	s_mov_b64 s[26:27], 0

.LBB0_346:
	s_add_u32 s54, s33, 0xffffff80
	s_addc_u32 s55, s52, -1
	s_cmp_eq_u32 s53, 60
	s_cselect_b32 s28, s2, s33
	s_cselect_b32 s29, s1, s52
	s_cselect_b32 s31, s11, s23
	s_cselect_b32 s30, s15, s19
	s_add_u32 s24, s28, 0x80
	s_addc_u32 s25, s29, 0
	s_add_u32 s26, s30, 0x80
	s_addc_u32 s27, s31, 0
	s_add_i32 s56, 0, 0x10000
	s_add_i32 s57, 0, 0x14000
	v_add_u32_e32 v152, s56, v1
	v_add_u32_e32 v168, s57, v1
	ds_read_b128 v[140:143], v152
	ds_read_b128 v[144:147], v152 offset:1024
	ds_read_b128 v[148:151], v152 offset:2048
	ds_read_b128 v[152:155], v152 offset:3072
	ds_read_b128 v[156:159], v168
	ds_read_b128 v[160:163], v168 offset:1024
	ds_read_b128 v[164:167], v168 offset:2048
	ds_read_b128 v[168:171], v168 offset:3072
	s_add_u32 s54, s54, 0x100000
	s_addc_u32 s55, s55, 0
	v_lshl_add_u64 v[204:205], s[54:55], 0, v[2:3]
	s_add_i32 m0, s41, 0xc000
	ds_read_b128 v[172:175], v5
	ds_read_b128 v[176:179], v5 offset:1024
	ds_read_b128 v[180:183], v5 offset:2048
	ds_read_b128 v[184:187], v5 offset:3072
	ds_read_b128 v[188:191], v5 offset:4096
	ds_read_b128 v[192:195], v5 offset:5120
	ds_read_b128 v[196:199], v5 offset:6144
	ds_read_b128 v[200:203], v5 offset:7168
	global_load_lds_dwordx4 v[204:205], off
	v_lshl_add_u64 v[204:205], s[54:55], 0, v[136:137]
	s_add_i32 m0, s41, 0xe000
	s_nop 0
	global_load_lds_dwordx4 v[204:205], off
	s_waitcnt vmcnt(8)
	s_waitcnt lgkmcnt(0)
	s_barrier
	s_setprio 1
	s_waitcnt lgkmcnt(0)
	v_mfma_f32_16x16x32_bf16 v[130:133], v[140:143], v[172:175], v[130:133]
	v_mfma_f32_16x16x32_bf16 v[126:129], v[148:151], v[172:175], v[126:129]
	v_mfma_f32_16x16x32_bf16 v[114:117], v[140:143], v[180:183], v[114:117]
	v_mfma_f32_16x16x32_bf16 v[110:113], v[148:151], v[180:183], v[110:113]
	v_mfma_f32_16x16x32_bf16 v[98:101], v[140:143], v[188:191], v[98:101]
	v_mfma_f32_16x16x32_bf16 v[94:97], v[148:151], v[188:191], v[94:97]
	v_mfma_f32_16x16x32_bf16 v[82:85], v[140:143], v[196:199], v[82:85]
	v_mfma_f32_16x16x32_bf16 v[78:81], v[148:151], v[196:199], v[78:81]
	v_mfma_f32_16x16x32_bf16 v[130:133], v[144:147], v[176:179], v[130:133]
	v_mfma_f32_16x16x32_bf16 v[126:129], v[152:155], v[176:179], v[126:129]
	v_mfma_f32_16x16x32_bf16 v[114:117], v[144:147], v[184:187], v[114:117]
	v_mfma_f32_16x16x32_bf16 v[110:113], v[152:155], v[184:187], v[110:113]
	v_mfma_f32_16x16x32_bf16 v[98:101], v[144:147], v[192:195], v[98:101]
	v_mfma_f32_16x16x32_bf16 v[94:97], v[152:155], v[192:195], v[94:97]
	v_mfma_f32_16x16x32_bf16 v[82:85], v[144:147], v[200:203], v[82:85]
	v_mfma_f32_16x16x32_bf16 v[78:81], v[152:155], v[200:203], v[78:81]
	s_setprio 0
	s_setprio 1
	v_mfma_f32_16x16x32_bf16 v[122:125], v[156:159], v[172:175], v[122:125]
	v_mfma_f32_16x16x32_bf16 v[118:121], v[164:167], v[172:175], v[118:121]
	v_mfma_f32_16x16x32_bf16 v[106:109], v[156:159], v[180:183], v[106:109]
	v_mfma_f32_16x16x32_bf16 v[102:105], v[164:167], v[180:183], v[102:105]
	v_mfma_f32_16x16x32_bf16 v[90:93], v[156:159], v[188:191], v[90:93]
	v_mfma_f32_16x16x32_bf16 v[86:89], v[164:167], v[188:191], v[86:89]
	v_mfma_f32_16x16x32_bf16 v[74:77], v[156:159], v[196:199], v[74:77]
	v_mfma_f32_16x16x32_bf16 v[70:73], v[164:167], v[196:199], v[70:73]
	v_mfma_f32_16x16x32_bf16 v[122:125], v[160:163], v[176:179], v[122:125]
	v_mfma_f32_16x16x32_bf16 v[118:121], v[168:171], v[176:179], v[118:121]
	v_mfma_f32_16x16x32_bf16 v[106:109], v[160:163], v[184:187], v[106:109]
	v_mfma_f32_16x16x32_bf16 v[102:105], v[168:171], v[184:187], v[102:105]
	v_mfma_f32_16x16x32_bf16 v[90:93], v[160:163], v[192:195], v[90:93]
	v_mfma_f32_16x16x32_bf16 v[86:89], v[168:171], v[192:195], v[86:89]
	v_mfma_f32_16x16x32_bf16 v[74:77], v[160:163], v[200:203], v[74:77]
	v_mfma_f32_16x16x32_bf16 v[70:73], v[168:171], v[200:203], v[70:73]
	s_setprio 0
	s_barrier
	s_add_i32 s54, s56, s38
	v_lshl_add_u64 v[204:205], s[30:31], 0, v[134:135]
	s_mov_b32 m0, s54
	ds_read_b128 v[172:175], v5 offset:16384
	ds_read_b128 v[176:179], v5 offset:17408
	ds_read_b128 v[180:183], v5 offset:18432
	ds_read_b128 v[184:187], v5 offset:19456
	ds_read_b128 v[188:191], v5 offset:20480
	ds_read_b128 v[192:195], v5 offset:21504
	ds_read_b128 v[196:199], v5 offset:22528
	ds_read_b128 v[200:203], v5 offset:23552
	global_load_lds_dwordx4 v[204:205], off
	s_add_i32 m0, s54, 0x2000
	v_lshl_add_u64 v[204:205], s[30:31], 0, v[138:139]
	s_add_u32 s30, s30, 0x100000
	s_addc_u32 s31, s31, 0
	s_add_i32 s54, s57, s38
	global_load_lds_dwordx4 v[204:205], off
	v_lshl_add_u64 v[204:205], s[30:31], 0, v[134:135]
	s_mov_b32 m0, s54
	s_nop 0
	global_load_lds_dwordx4 v[204:205], off
	v_lshl_add_u64 v[204:205], s[30:31], 0, v[138:139]
	s_add_i32 m0, s54, 0x2000
	s_nop 0
	global_load_lds_dwordx4 v[204:205], off
	v_lshl_add_u64 v[204:205], s[28:29], 0, v[2:3]
	s_mov_b32 m0, s41
	s_nop 0
	global_load_lds_dwordx4 v[204:205], off
	v_lshl_add_u64 v[204:205], s[28:29], 0, v[136:137]
	s_mov_b32 m0, s3
	s_nop 0
	global_load_lds_dwordx4 v[204:205], off
	s_waitcnt vmcnt(8)
	s_waitcnt lgkmcnt(0)
	s_barrier
	s_setprio 1
	s_waitcnt lgkmcnt(0)
	v_mfma_f32_16x16x32_bf16 v[66:69], v[140:143], v[172:175], v[66:69]
	v_mfma_f32_16x16x32_bf16 v[62:65], v[148:151], v[172:175], v[62:65]
	v_mfma_f32_16x16x32_bf16 v[50:53], v[140:143], v[180:183], v[50:53]
	v_mfma_f32_16x16x32_bf16 v[46:49], v[148:151], v[180:183], v[46:49]
	v_mfma_f32_16x16x32_bf16 v[34:37], v[140:143], v[188:191], v[34:37]
	v_mfma_f32_16x16x32_bf16 v[30:33], v[148:151], v[188:191], v[30:33]
	v_mfma_f32_16x16x32_bf16 v[18:21], v[140:143], v[196:199], v[18:21]
	v_mfma_f32_16x16x32_bf16 v[14:17], v[148:151], v[196:199], v[14:17]
	v_mfma_f32_16x16x32_bf16 v[66:69], v[144:147], v[176:179], v[66:69]
	v_mfma_f32_16x16x32_bf16 v[62:65], v[152:155], v[176:179], v[62:65]
	v_mfma_f32_16x16x32_bf16 v[50:53], v[144:147], v[184:187], v[50:53]
	v_mfma_f32_16x16x32_bf16 v[46:49], v[152:155], v[184:187], v[46:49]
	v_mfma_f32_16x16x32_bf16 v[34:37], v[144:147], v[192:195], v[34:37]
	v_mfma_f32_16x16x32_bf16 v[30:33], v[152:155], v[192:195], v[30:33]
	v_mfma_f32_16x16x32_bf16 v[18:21], v[144:147], v[200:203], v[18:21]
	v_mfma_f32_16x16x32_bf16 v[14:17], v[152:155], v[200:203], v[14:17]
	s_setprio 0
	s_setprio 1
	v_mfma_f32_16x16x32_bf16 v[58:61], v[156:159], v[172:175], v[58:61]
	v_mfma_f32_16x16x32_bf16 v[54:57], v[164:167], v[172:175], v[54:57]
	v_mfma_f32_16x16x32_bf16 v[42:45], v[156:159], v[180:183], v[42:45]
	v_mfma_f32_16x16x32_bf16 v[38:41], v[164:167], v[180:183], v[38:41]
	v_mfma_f32_16x16x32_bf16 v[26:29], v[156:159], v[188:191], v[26:29]
	v_mfma_f32_16x16x32_bf16 v[22:25], v[164:167], v[188:191], v[22:25]
	v_mfma_f32_16x16x32_bf16 v[10:13], v[156:159], v[196:199], v[10:13]
	v_mfma_f32_16x16x32_bf16 v[6:9], v[164:167], v[196:199], v[6:9]
	v_mfma_f32_16x16x32_bf16 v[58:61], v[160:163], v[176:179], v[58:61]
	v_mfma_f32_16x16x32_bf16 v[54:57], v[168:171], v[176:179], v[54:57]
	v_mfma_f32_16x16x32_bf16 v[42:45], v[160:163], v[184:187], v[42:45]
	v_mfma_f32_16x16x32_bf16 v[38:41], v[168:171], v[184:187], v[38:41]
	v_mfma_f32_16x16x32_bf16 v[26:29], v[160:163], v[192:195], v[26:29]
	v_mfma_f32_16x16x32_bf16 v[22:25], v[168:171], v[192:195], v[22:25]
	v_mfma_f32_16x16x32_bf16 v[10:13], v[160:163], v[200:203], v[10:13]
	v_mfma_f32_16x16x32_bf16 v[6:9], v[168:171], v[200:203], v[6:9]
	s_setprio 0
	s_barrier
	s_add_i32 s30, 0, 0x18000
	s_add_i32 s31, 0, 0x1c000
	v_add_u32_e32 v152, s30, v1
	v_add_u32_e32 v168, s31, v1
	ds_read_b128 v[140:143], v152
	ds_read_b128 v[144:147], v152 offset:1024
	ds_read_b128 v[148:151], v152 offset:2048
	ds_read_b128 v[152:155], v152 offset:3072
	ds_read_b128 v[156:159], v168
	ds_read_b128 v[160:163], v168 offset:1024
	ds_read_b128 v[164:167], v168 offset:2048
	ds_read_b128 v[168:171], v168 offset:3072
	s_add_u32 s28, s28, 0x100000
	s_addc_u32 s29, s29, 0
	s_mov_b32 m0, s43
	v_lshl_add_u64 v[204:205], s[28:29], 0, v[2:3]
	ds_read_b128 v[172:175], v5 offset:32768
	ds_read_b128 v[176:179], v5 offset:33792
	ds_read_b128 v[180:183], v5 offset:34816
	ds_read_b128 v[184:187], v5 offset:35840
	ds_read_b128 v[188:191], v5 offset:36864
	ds_read_b128 v[192:195], v5 offset:37888
	ds_read_b128 v[196:199], v5 offset:38912
	ds_read_b128 v[200:203], v5 offset:39936
	global_load_lds_dwordx4 v[204:205], off
	v_lshl_add_u64 v[204:205], s[28:29], 0, v[136:137]
	s_mov_b32 m0, s46
	s_nop 0
	global_load_lds_dwordx4 v[204:205], off
	s_waitcnt vmcnt(8)
	s_waitcnt lgkmcnt(0)
	s_barrier
	s_setprio 1
	s_waitcnt lgkmcnt(0)
	v_mfma_f32_16x16x32_bf16 v[130:133], v[140:143], v[172:175], v[130:133]
	v_mfma_f32_16x16x32_bf16 v[126:129], v[148:151], v[172:175], v[126:129]
	v_mfma_f32_16x16x32_bf16 v[114:117], v[140:143], v[180:183], v[114:117]
	v_mfma_f32_16x16x32_bf16 v[110:113], v[148:151], v[180:183], v[110:113]
	v_mfma_f32_16x16x32_bf16 v[98:101], v[140:143], v[188:191], v[98:101]
	v_mfma_f32_16x16x32_bf16 v[94:97], v[148:151], v[188:191], v[94:97]
	v_mfma_f32_16x16x32_bf16 v[82:85], v[140:143], v[196:199], v[82:85]
	v_mfma_f32_16x16x32_bf16 v[78:81], v[148:151], v[196:199], v[78:81]
	v_mfma_f32_16x16x32_bf16 v[130:133], v[144:147], v[176:179], v[130:133]
	v_mfma_f32_16x16x32_bf16 v[126:129], v[152:155], v[176:179], v[126:129]
	v_mfma_f32_16x16x32_bf16 v[114:117], v[144:147], v[184:187], v[114:117]
	v_mfma_f32_16x16x32_bf16 v[110:113], v[152:155], v[184:187], v[110:113]
	v_mfma_f32_16x16x32_bf16 v[98:101], v[144:147], v[192:195], v[98:101]
	v_mfma_f32_16x16x32_bf16 v[94:97], v[152:155], v[192:195], v[94:97]
	v_mfma_f32_16x16x32_bf16 v[82:85], v[144:147], v[200:203], v[82:85]
	v_mfma_f32_16x16x32_bf16 v[78:81], v[152:155], v[200:203], v[78:81]
	s_setprio 0
	s_setprio 1
	v_mfma_f32_16x16x32_bf16 v[122:125], v[156:159], v[172:175], v[122:125]
	v_mfma_f32_16x16x32_bf16 v[118:121], v[164:167], v[172:175], v[118:121]
	v_mfma_f32_16x16x32_bf16 v[106:109], v[156:159], v[180:183], v[106:109]
	v_mfma_f32_16x16x32_bf16 v[102:105], v[164:167], v[180:183], v[102:105]
	v_mfma_f32_16x16x32_bf16 v[90:93], v[156:159], v[188:191], v[90:93]
	v_mfma_f32_16x16x32_bf16 v[86:89], v[164:167], v[188:191], v[86:89]
	v_mfma_f32_16x16x32_bf16 v[74:77], v[156:159], v[196:199], v[74:77]
	v_mfma_f32_16x16x32_bf16 v[70:73], v[164:167], v[196:199], v[70:73]
	v_mfma_f32_16x16x32_bf16 v[122:125], v[160:163], v[176:179], v[122:125]
	v_mfma_f32_16x16x32_bf16 v[118:121], v[168:171], v[176:179], v[118:121]
	v_mfma_f32_16x16x32_bf16 v[106:109], v[160:163], v[184:187], v[106:109]
	v_mfma_f32_16x16x32_bf16 v[102:105], v[168:171], v[184:187], v[102:105]
	v_mfma_f32_16x16x32_bf16 v[90:93], v[160:163], v[192:195], v[90:93]
	v_mfma_f32_16x16x32_bf16 v[86:89], v[168:171], v[192:195], v[86:89]
	v_mfma_f32_16x16x32_bf16 v[74:77], v[160:163], v[200:203], v[74:77]
	v_mfma_f32_16x16x32_bf16 v[70:73], v[168:171], v[200:203], v[70:73]
	s_setprio 0
	s_barrier
	s_add_i32 s28, s30, s38
	v_lshl_add_u64 v[204:205], s[26:27], 0, v[134:135]
	s_mov_b32 m0, s28
	ds_read_b128 v[172:175], v5 offset:49152
	ds_read_b128 v[176:179], v5 offset:50176
	ds_read_b128 v[180:183], v5 offset:51200
	ds_read_b128 v[184:187], v5 offset:52224
	ds_read_b128 v[188:191], v5 offset:53248
	ds_read_b128 v[192:195], v5 offset:54272
	ds_read_b128 v[196:199], v5 offset:55296
	ds_read_b128 v[200:203], v5 offset:56320
	global_load_lds_dwordx4 v[204:205], off
	s_add_i32 m0, s28, 0x2000
	v_lshl_add_u64 v[204:205], s[26:27], 0, v[138:139]
	s_add_u32 s26, s26, 0x100000
	s_addc_u32 s27, s27, 0
	s_add_i32 s28, s31, s38
	global_load_lds_dwordx4 v[204:205], off
	v_lshl_add_u64 v[204:205], s[26:27], 0, v[134:135]
	s_mov_b32 m0, s28
	s_nop 0
	global_load_lds_dwordx4 v[204:205], off
	v_lshl_add_u64 v[204:205], s[26:27], 0, v[138:139]
	s_add_i32 m0, s28, 0x2000
	s_nop 0
	global_load_lds_dwordx4 v[204:205], off
	v_lshl_add_u64 v[204:205], s[24:25], 0, v[2:3]
	s_mov_b32 m0, s49
	s_nop 0
	global_load_lds_dwordx4 v[204:205], off
	v_lshl_add_u64 v[204:205], s[24:25], 0, v[136:137]
	s_mov_b32 m0, s50
	s_nop 0
	global_load_lds_dwordx4 v[204:205], off
	s_waitcnt vmcnt(8)
	s_waitcnt lgkmcnt(0)
	s_barrier
	s_setprio 1
	s_waitcnt lgkmcnt(0)
	v_mfma_f32_16x16x32_bf16 v[66:69], v[140:143], v[172:175], v[66:69]
	v_mfma_f32_16x16x32_bf16 v[62:65], v[148:151], v[172:175], v[62:65]
	v_mfma_f32_16x16x32_bf16 v[50:53], v[140:143], v[180:183], v[50:53]
	v_mfma_f32_16x16x32_bf16 v[46:49], v[148:151], v[180:183], v[46:49]
	v_mfma_f32_16x16x32_bf16 v[34:37], v[140:143], v[188:191], v[34:37]
	v_mfma_f32_16x16x32_bf16 v[30:33], v[148:151], v[188:191], v[30:33]
	v_mfma_f32_16x16x32_bf16 v[18:21], v[140:143], v[196:199], v[18:21]
	v_mfma_f32_16x16x32_bf16 v[14:17], v[148:151], v[196:199], v[14:17]
	v_mfma_f32_16x16x32_bf16 v[66:69], v[144:147], v[176:179], v[66:69]
	v_mfma_f32_16x16x32_bf16 v[62:65], v[152:155], v[176:179], v[62:65]
	v_mfma_f32_16x16x32_bf16 v[50:53], v[144:147], v[184:187], v[50:53]
	v_mfma_f32_16x16x32_bf16 v[46:49], v[152:155], v[184:187], v[46:49]
	v_mfma_f32_16x16x32_bf16 v[34:37], v[144:147], v[192:195], v[34:37]
	v_mfma_f32_16x16x32_bf16 v[30:33], v[152:155], v[192:195], v[30:33]
	v_mfma_f32_16x16x32_bf16 v[18:21], v[144:147], v[200:203], v[18:21]
	v_mfma_f32_16x16x32_bf16 v[14:17], v[152:155], v[200:203], v[14:17]
	s_setprio 0
	s_setprio 1
	v_mfma_f32_16x16x32_bf16 v[58:61], v[156:159], v[172:175], v[58:61]
	v_mfma_f32_16x16x32_bf16 v[54:57], v[164:167], v[172:175], v[54:57]
	v_mfma_f32_16x16x32_bf16 v[42:45], v[156:159], v[180:183], v[42:45]
	v_mfma_f32_16x16x32_bf16 v[38:41], v[164:167], v[180:183], v[38:41]
	v_mfma_f32_16x16x32_bf16 v[26:29], v[156:159], v[188:191], v[26:29]
	v_mfma_f32_16x16x32_bf16 v[22:25], v[164:167], v[188:191], v[22:25]
	v_mfma_f32_16x16x32_bf16 v[10:13], v[156:159], v[196:199], v[10:13]
	v_mfma_f32_16x16x32_bf16 v[6:9], v[164:167], v[196:199], v[6:9]
	v_mfma_f32_16x16x32_bf16 v[58:61], v[160:163], v[176:179], v[58:61]
	v_mfma_f32_16x16x32_bf16 v[54:57], v[168:171], v[176:179], v[54:57]
	v_mfma_f32_16x16x32_bf16 v[42:45], v[160:163], v[184:187], v[42:45]
	v_mfma_f32_16x16x32_bf16 v[38:41], v[168:171], v[184:187], v[38:41]
	v_mfma_f32_16x16x32_bf16 v[26:29], v[160:163], v[192:195], v[26:29]
	v_mfma_f32_16x16x32_bf16 v[22:25], v[168:171], v[192:195], v[22:25]
	v_mfma_f32_16x16x32_bf16 v[10:13], v[160:163], v[200:203], v[10:13]
	v_mfma_f32_16x16x32_bf16 v[6:9], v[168:171], v[200:203], v[6:9]
	s_setprio 0
	s_barrier
	s_add_i32 s53, s53, 2
	s_add_u32 s19, s19, 0x100
	s_addc_u32 s23, s23, 0
	s_add_u32 s33, s33, 0x100
	s_addc_u32 s52, s52, 0
	s_cmp_gt_u32 s53, 61
	s_cbranch_scc0 .LBB0_346
	v_mov_b32_e32 v140, v0
	s_lshl_b32 s1, s0, 8
	s_mov_b64 s[24:25], s[84:85]
	s_add_i32 s1, s1, s47
	v_bfe_u32 v210, v140, 4, 2
	v_and_or_b32 v140, v140, 15, s1
	s_add_u32 s26, s24, s6
	s_addc_u32 s27, s25, s7
	v_ashrrev_i32_e32 v141, 31, v140
	v_lshl_add_u64 v[142:143], v[140:141], 2, s[26:27]
	s_mov_b64 s[26:27], 0x10000
	v_lshl_add_u64 v[154:155], v[142:143], 0, s[26:27]
	v_add_co_u32_e32 v142, vcc, s91, v142
	s_cmp_gt_i32 s22, 3
	s_nop 0
	v_addc_co_u32_e32 v143, vcc, 0, v143, vcc
	global_load_dword v142, v[142:143], off
	s_cselect_b64 s[28:29], -1, 0
	s_cmp_lt_i32 s22, 4
	s_cselect_b64 s[26:27], -1, 0
	global_load_dword v205, v[154:155], off offset:64
	global_load_dword v204, v[154:155], off offset:128
	global_load_dword v203, v[154:155], off offset:192
	global_load_dword v202, v[154:155], off offset:512
	global_load_dword v201, v[154:155], off offset:576
	global_load_dword v200, v[154:155], off offset:640
	global_load_dword v199, v[154:155], off offset:704
	s_waitcnt vmcnt(0)
	v_fmamk_f32 v142, v142, 0x39800000, v246
	v_cmp_gt_f32_e32 vcc, s95, v142
	v_mul_f32_e32 v143, 0x4b800000, v142
	s_nop 0
	v_cndmask_b32_e32 v142, v142, v143, vcc
	v_rsq_f32_e32 v142, v142
	s_nop 0
	v_mul_f32_e32 v143, 0x45800000, v142
	v_cndmask_b32_e32 v142, v142, v143, vcc
	v_pk_mul_f32 v[132:133], v[132:133], v[142:143] op_sel_hi:[1,0]
	v_pk_mul_f32 v[130:131], v[130:131], v[142:143] op_sel_hi:[1,0]
	v_pk_mul_f32 v[128:129], v[128:129], v[142:143] op_sel_hi:[1,0]
	v_pk_mul_f32 v[126:127], v[126:127], v[142:143] op_sel_hi:[1,0]
	v_pk_mul_f32 v[124:125], v[124:125], v[142:143] op_sel_hi:[1,0]
	v_pk_mul_f32 v[122:123], v[122:123], v[142:143] op_sel_hi:[1,0]
	v_pk_mul_f32 v[120:121], v[120:121], v[142:143] op_sel_hi:[1,0]
	v_pk_mul_f32 v[118:119], v[118:119], v[142:143] op_sel_hi:[1,0]
	s_waitcnt vmcnt(0)
	v_fmamk_f32 v142, v205, 0x39800000, v246
	v_cmp_gt_f32_e32 vcc, s95, v142
	v_mul_f32_e32 v143, 0x4b800000, v142
	s_nop 0
	v_cndmask_b32_e32 v142, v142, v143, vcc
	v_rsq_f32_e32 v142, v142
	s_nop 0
	v_mul_f32_e32 v143, 0x45800000, v142
	v_cndmask_b32_e32 v142, v142, v143, vcc
	v_pk_mul_f32 v[116:117], v[116:117], v[142:143] op_sel_hi:[1,0]
	v_pk_mul_f32 v[114:115], v[114:115], v[142:143] op_sel_hi:[1,0]
	v_pk_mul_f32 v[112:113], v[112:113], v[142:143] op_sel_hi:[1,0]
	v_pk_mul_f32 v[110:111], v[110:111], v[142:143] op_sel_hi:[1,0]
	v_pk_mul_f32 v[108:109], v[108:109], v[142:143] op_sel_hi:[1,0]
	v_pk_mul_f32 v[106:107], v[106:107], v[142:143] op_sel_hi:[1,0]
	v_pk_mul_f32 v[104:105], v[104:105], v[142:143] op_sel_hi:[1,0]
	v_pk_mul_f32 v[102:103], v[102:103], v[142:143] op_sel_hi:[1,0]
	s_waitcnt vmcnt(0)
	v_fmamk_f32 v142, v204, 0x39800000, v246
	v_cmp_gt_f32_e32 vcc, s95, v142
	v_mul_f32_e32 v143, 0x4b800000, v142
	s_nop 0
	v_cndmask_b32_e32 v142, v142, v143, vcc
	v_rsq_f32_e32 v142, v142
	s_nop 0
	v_mul_f32_e32 v143, 0x45800000, v142
	v_cndmask_b32_e32 v142, v142, v143, vcc
	v_pk_mul_f32 v[150:151], v[94:95], v[142:143] op_sel_hi:[1,0]
	v_pk_mul_f32 v[152:153], v[98:99], v[142:143] op_sel_hi:[1,0]
	v_pk_mul_f32 v[100:101], v[100:101], v[142:143] op_sel_hi:[1,0]
	v_pk_mul_f32 v[92:93], v[92:93], v[142:143] op_sel_hi:[1,0]
	v_pk_mul_f32 v[90:91], v[90:91], v[142:143] op_sel_hi:[1,0]
	v_pk_mul_f32 v[86:87], v[86:87], v[142:143] op_sel_hi:[1,0]
	v_pk_mul_f32 v[96:97], v[96:97], v[142:143] op_sel_hi:[1,0]
	v_pk_mul_f32 v[88:89], v[88:89], v[142:143] op_sel_hi:[1,0]
	s_waitcnt vmcnt(0)
	v_fmamk_f32 v94, v203, 0x39800000, v246
	v_cmp_gt_f32_e32 vcc, s95, v94
	v_mul_f32_e32 v95, 0x4b800000, v94
	s_nop 0
	v_cndmask_b32_e32 v94, v94, v95, vcc
	v_rsq_f32_e32 v94, v94
	s_nop 0
	v_mul_f32_e32 v95, 0x45800000, v94
	v_cndmask_b32_e32 v94, v94, v95, vcc
	v_pk_mul_f32 v[164:165], v[80:81], v[94:95] op_sel_hi:[1,0]
	v_pk_mul_f32 v[80:81], v[74:75], v[94:95] op_sel_hi:[1,0]
	v_pk_mul_f32 v[166:167], v[84:85], v[94:95] op_sel_hi:[1,0]
	v_pk_mul_f32 v[170:171], v[82:83], v[94:95] op_sel_hi:[1,0]
	v_pk_mul_f32 v[168:169], v[78:79], v[94:95] op_sel_hi:[1,0]
	v_pk_mul_f32 v[78:79], v[76:77], v[94:95] op_sel_hi:[1,0]
	v_pk_mul_f32 v[72:73], v[72:73], v[94:95] op_sel_hi:[1,0]
	v_pk_mul_f32 v[70:71], v[70:71], v[94:95] op_sel_hi:[1,0]
	s_waitcnt vmcnt(0)
	v_fmamk_f32 v74, v202, 0x39800000, v246
	v_cmp_gt_f32_e32 vcc, s95, v74
	v_mul_f32_e32 v75, 0x4b800000, v74
	s_nop 0
	v_cndmask_b32_e32 v74, v74, v75, vcc
	v_rsq_f32_e32 v74, v74
	s_nop 0
	v_mul_f32_e32 v75, 0x45800000, v74
	v_cndmask_b32_e32 v98, v74, v75, vcc
	v_pk_mul_f32 v[76:77], v[68:69], v[98:99] op_sel_hi:[1,0]
	v_pk_mul_f32 v[176:177], v[66:67], v[98:99] op_sel_hi:[1,0]
	v_pk_mul_f32 v[74:75], v[64:65], v[98:99] op_sel_hi:[1,0]
	v_pk_mul_f32 v[174:175], v[62:63], v[98:99] op_sel_hi:[1,0]
	v_pk_mul_f32 v[84:85], v[60:61], v[98:99] op_sel_hi:[1,0]
	v_pk_mul_f32 v[94:95], v[58:59], v[98:99] op_sel_hi:[1,0]
	v_pk_mul_f32 v[82:83], v[56:57], v[98:99] op_sel_hi:[1,0]
	v_pk_mul_f32 v[98:99], v[54:55], v[98:99] op_sel_hi:[1,0]
	s_waitcnt vmcnt(0)
	v_fmamk_f32 v54, v201, 0x39800000, v246
	v_cmp_gt_f32_e32 vcc, s95, v54
	v_mul_f32_e32 v55, 0x4b800000, v54
	s_nop 0
	v_cndmask_b32_e32 v54, v54, v55, vcc
	v_rsq_f32_e32 v54, v54
	s_nop 0
	v_mul_f32_e32 v55, 0x45800000, v54
	v_cndmask_b32_e32 v54, v54, v55, vcc
	v_pk_mul_f32 v[146:147], v[38:39], v[54:55] op_sel_hi:[1,0]
	v_pk_mul_f32 v[180:181], v[52:53], v[54:55] op_sel_hi:[1,0]
	v_pk_mul_f32 v[184:185], v[50:51], v[54:55] op_sel_hi:[1,0]
	v_pk_mul_f32 v[144:145], v[44:45], v[54:55] op_sel_hi:[1,0]
	v_pk_mul_f32 v[148:149], v[42:43], v[54:55] op_sel_hi:[1,0]
	v_pk_mul_f32 v[182:183], v[46:47], v[54:55] op_sel_hi:[1,0]
	v_pk_mul_f32 v[178:179], v[48:49], v[54:55] op_sel_hi:[1,0]
	v_pk_mul_f32 v[142:143], v[40:41], v[54:55] op_sel_hi:[1,0]
	s_waitcnt vmcnt(0)
	v_fmamk_f32 v38, v200, 0x39800000, v246
	v_cmp_gt_f32_e32 vcc, s95, v38
	v_mul_f32_e32 v39, 0x4b800000, v38
	s_nop 0
	v_cndmask_b32_e32 v38, v38, v39, vcc
	v_rsq_f32_e32 v38, v38
	s_nop 0
	v_mul_f32_e32 v39, 0x45800000, v38
	v_cndmask_b32_e32 v38, v38, v39, vcc
	v_pk_mul_f32 v[160:161], v[22:23], v[38:39] op_sel_hi:[1,0]
	v_pk_mul_f32 v[188:189], v[36:37], v[38:39] op_sel_hi:[1,0]
	v_pk_mul_f32 v[192:193], v[34:35], v[38:39] op_sel_hi:[1,0]
	v_pk_mul_f32 v[158:159], v[28:29], v[38:39] op_sel_hi:[1,0]
	v_pk_mul_f32 v[162:163], v[26:27], v[38:39] op_sel_hi:[1,0]
	v_pk_mul_f32 v[186:187], v[32:33], v[38:39] op_sel_hi:[1,0]
	v_pk_mul_f32 v[190:191], v[30:31], v[38:39] op_sel_hi:[1,0]
	v_pk_mul_f32 v[156:157], v[24:25], v[38:39] op_sel_hi:[1,0]
	v_mul_f32_e32 v24, v95, v95
	v_mul_f32_e32 v25, v85, v85
	v_mul_f32_e32 v26, v185, v185
	v_mul_f32_e32 v27, v181, v181
	v_mul_f32_e32 v28, v149, v149
	v_mul_f32_e32 v29, v145, v145
	v_mul_f32_e32 v30, v193, v193
	v_mul_f32_e32 v31, v189, v189
	v_mul_f32_e32 v32, v163, v163
	v_mul_f32_e32 v33, v159, v159
	v_fmac_f32_e32 v24, v94, v94
	v_fmac_f32_e32 v25, v84, v84
	v_fmac_f32_e32 v26, v184, v184
	v_fmac_f32_e32 v27, v180, v180
	v_fmac_f32_e32 v28, v148, v148
	v_fmac_f32_e32 v29, v144, v144
	v_fmac_f32_e32 v30, v192, v192
	v_fmac_f32_e32 v31, v188, v188
	v_fmac_f32_e32 v32, v162, v162
	v_fmac_f32_e32 v33, v158, v158
	v_add_f32_e32 v24, v24, v25
	v_mul_f32_e32 v25, v99, v99
	v_add_f32_e32 v26, v26, v27
	v_mul_f32_e32 v27, v183, v183
	v_add_f32_e32 v28, v28, v29
	v_mul_f32_e32 v29, v147, v147
	v_add_f32_e32 v30, v30, v31
	v_mul_f32_e32 v31, v191, v191
	v_add_f32_e32 v32, v32, v33
	v_mul_f32_e32 v33, v161, v161
	v_fmac_f32_e32 v25, v98, v98
	v_fmac_f32_e32 v27, v182, v182
	v_fmac_f32_e32 v29, v146, v146
	v_fmac_f32_e32 v31, v190, v190
	v_fmac_f32_e32 v33, v160, v160
	v_add_f32_e32 v24, v25, v24
	v_mul_f32_e32 v25, v83, v83
	v_add_f32_e32 v26, v27, v26
	v_mul_f32_e32 v27, v179, v179
	v_add_f32_e32 v28, v29, v28
	v_mul_f32_e32 v29, v143, v143
	v_add_f32_e32 v30, v31, v30
	v_mul_f32_e32 v31, v187, v187
	v_add_f32_e32 v32, v33, v32
	v_mul_f32_e32 v33, v157, v157
	v_fmac_f32_e32 v25, v82, v82
	v_fmac_f32_e32 v27, v178, v178
	v_fmac_f32_e32 v29, v142, v142
	v_fmac_f32_e32 v31, v186, v186
	v_fmac_f32_e32 v33, v156, v156
	v_add_f32_e32 v24, v25, v24
	v_add_f32_e32 v26, v27, v26
	v_add_f32_e32 v28, v29, v28
	v_add_f32_e32 v30, v31, v30
	v_add_f32_e32 v32, v33, v32
	ds_swizzle_b32 v25, v24 offset:swizzle(SWAP,16)
	ds_swizzle_b32 v27, v26 offset:swizzle(SWAP,16)
	ds_swizzle_b32 v29, v28 offset:swizzle(SWAP,16)
	ds_swizzle_b32 v31, v30 offset:swizzle(SWAP,16)
	ds_swizzle_b32 v33, v32 offset:swizzle(SWAP,16)
	s_waitcnt lgkmcnt(4)
	v_add_f32_e32 v24, v24, v25
	s_waitcnt lgkmcnt(3)
	v_add_f32_e32 v26, v26, v27
	s_waitcnt lgkmcnt(2)
	v_add_f32_e32 v28, v28, v29
	s_waitcnt lgkmcnt(1)
	v_add_f32_e32 v30, v30, v31
	s_waitcnt lgkmcnt(0)
	v_add_f32_e32 v32, v32, v33
	v_mov_b32_e32 v25, v24
	v_mov_b32_e32 v27, v26
	v_mov_b32_e32 v29, v28
	v_mov_b32_e32 v31, v30
	v_mov_b32_e32 v33, v32
	v_permlane32_swap_b32_e32 v24, v25
	s_waitcnt vmcnt(0)
	v_fmamk_f32 v22, v199, 0x39800000, v246
	v_cmp_gt_f32_e32 vcc, s95, v22
	v_mul_f32_e32 v23, 0x4b800000, v22
	v_permlane32_swap_b32_e32 v26, v27
	v_cndmask_b32_e32 v22, v22, v23, vcc
	v_rsq_f32_e32 v22, v22
	v_permlane32_swap_b32_e32 v28, v29
	v_permlane32_swap_b32_e32 v30, v31
	v_mul_f32_e32 v23, 0x45800000, v22
	v_cndmask_b32_e32 v22, v22, v23, vcc
	v_pk_mul_f32 v[202:203], v[20:21], v[22:23] op_sel_hi:[1,0]
	v_pk_mul_f32 v[204:205], v[18:19], v[22:23] op_sel_hi:[1,0]
	v_pk_mul_f32 v[194:195], v[12:13], v[22:23] op_sel_hi:[1,0]
	v_pk_mul_f32 v[196:197], v[10:11], v[22:23] op_sel_hi:[1,0]
	v_pk_mul_f32 v[206:207], v[16:17], v[22:23] op_sel_hi:[1,0]
	v_pk_mul_f32 v[208:209], v[14:15], v[22:23] op_sel_hi:[1,0]
	v_pk_mul_f32 v[198:199], v[8:9], v[22:23] op_sel_hi:[1,0]
	v_pk_mul_f32 v[200:201], v[6:7], v[22:23] op_sel_hi:[1,0]
	v_mul_f32_e32 v6, v131, v131
	v_mul_f32_e32 v7, v133, v133
	v_mul_f32_e32 v8, v123, v123
	v_mul_f32_e32 v9, v125, v125
	v_mul_f32_e32 v10, v115, v115
	v_mul_f32_e32 v11, v117, v117
	v_mul_f32_e32 v12, v107, v107
	v_mul_f32_e32 v13, v109, v109
	v_mul_f32_e32 v14, v153, v153
	v_mul_f32_e32 v15, v101, v101
	v_mul_f32_e32 v16, v91, v91
	v_mul_f32_e32 v17, v93, v93
	v_mul_f32_e32 v18, v171, v171
	v_mul_f32_e32 v19, v167, v167
	v_mul_f32_e32 v20, v81, v81
	v_mul_f32_e32 v21, v79, v79
	v_mul_f32_e32 v22, v177, v177
	v_mul_f32_e32 v23, v77, v77
	v_mul_f32_e32 v34, v205, v205
	v_mul_f32_e32 v35, v203, v203
	v_mul_f32_e32 v36, v197, v197
	v_mul_f32_e32 v37, v195, v195
	v_fmac_f32_e32 v6, v130, v130
	v_fmac_f32_e32 v7, v132, v132
	v_fmac_f32_e32 v8, v122, v122
	v_fmac_f32_e32 v9, v124, v124
	v_fmac_f32_e32 v10, v114, v114
	v_fmac_f32_e32 v11, v116, v116
	v_fmac_f32_e32 v12, v106, v106
	v_fmac_f32_e32 v13, v108, v108
	v_fmac_f32_e32 v14, v152, v152
	v_fmac_f32_e32 v15, v100, v100
	v_fmac_f32_e32 v16, v90, v90
	v_fmac_f32_e32 v17, v92, v92
	v_fmac_f32_e32 v18, v170, v170
	v_fmac_f32_e32 v19, v166, v166
	v_fmac_f32_e32 v20, v80, v80
	v_fmac_f32_e32 v21, v78, v78
	v_fmac_f32_e32 v22, v176, v176
	v_fmac_f32_e32 v23, v76, v76
	v_fmac_f32_e32 v34, v204, v204
	v_fmac_f32_e32 v35, v202, v202
	v_fmac_f32_e32 v36, v196, v196
	v_fmac_f32_e32 v37, v194, v194
	v_add_f32_e32 v6, v6, v7
	v_mul_f32_e32 v7, v127, v127
	v_add_f32_e32 v8, v8, v9
	v_mul_f32_e32 v9, v119, v119
	v_add_f32_e32 v10, v10, v11
	v_mul_f32_e32 v11, v111, v111
	v_add_f32_e32 v12, v12, v13
	v_mul_f32_e32 v13, v103, v103
	v_add_f32_e32 v14, v14, v15
	v_mul_f32_e32 v15, v151, v151
	v_add_f32_e32 v16, v16, v17
	v_mul_f32_e32 v17, v87, v87
	v_add_f32_e32 v18, v18, v19
	v_mul_f32_e32 v19, v169, v169
	v_add_f32_e32 v20, v20, v21
	v_mul_f32_e32 v21, v71, v71
	v_add_f32_e32 v22, v22, v23
	v_mul_f32_e32 v23, v175, v175
	v_add_f32_e32 v34, v34, v35
	v_mul_f32_e32 v35, v209, v209
	v_add_f32_e32 v36, v36, v37
	v_mul_f32_e32 v37, v201, v201
	v_fmac_f32_e32 v7, v126, v126
	v_fmac_f32_e32 v9, v118, v118
	v_fmac_f32_e32 v11, v110, v110
	v_fmac_f32_e32 v13, v102, v102
	v_fmac_f32_e32 v15, v150, v150
	v_fmac_f32_e32 v17, v86, v86
	v_fmac_f32_e32 v19, v168, v168
	v_fmac_f32_e32 v21, v70, v70
	v_fmac_f32_e32 v23, v174, v174
	v_fmac_f32_e32 v35, v208, v208
	v_fmac_f32_e32 v37, v200, v200
	v_add_f32_e32 v6, v7, v6
	v_mul_f32_e32 v7, v129, v129
	v_add_f32_e32 v8, v9, v8
	v_mul_f32_e32 v9, v121, v121
	v_add_f32_e32 v10, v11, v10
	v_mul_f32_e32 v11, v113, v113
	v_add_f32_e32 v12, v13, v12
	v_mul_f32_e32 v13, v105, v105
	v_add_f32_e32 v14, v15, v14
	v_mul_f32_e32 v15, v97, v97
	v_add_f32_e32 v16, v17, v16
	v_mul_f32_e32 v17, v89, v89
	v_add_f32_e32 v18, v19, v18
	v_mul_f32_e32 v19, v165, v165
	v_add_f32_e32 v20, v21, v20
	v_mul_f32_e32 v21, v73, v73
	v_add_f32_e32 v22, v23, v22
	v_mul_f32_e32 v23, v75, v75
	v_add_f32_e32 v34, v35, v34
	v_mul_f32_e32 v35, v207, v207
	v_add_f32_e32 v36, v37, v36
	v_mul_f32_e32 v37, v199, v199
	v_fmac_f32_e32 v7, v128, v128
	v_fmac_f32_e32 v9, v120, v120
	v_fmac_f32_e32 v11, v112, v112
	v_fmac_f32_e32 v13, v104, v104
	v_fmac_f32_e32 v15, v96, v96
	v_fmac_f32_e32 v17, v88, v88
	v_fmac_f32_e32 v19, v164, v164
	v_fmac_f32_e32 v21, v72, v72
	v_fmac_f32_e32 v23, v74, v74
	v_fmac_f32_e32 v35, v206, v206
	v_fmac_f32_e32 v37, v198, v198
	v_add_f32_e32 v6, v7, v6
	v_add_f32_e32 v8, v9, v8
	v_add_f32_e32 v10, v11, v10
	v_add_f32_e32 v12, v13, v12
	v_add_f32_e32 v14, v15, v14
	v_add_f32_e32 v16, v17, v16
	v_add_f32_e32 v18, v19, v18
	v_add_f32_e32 v20, v21, v20
	v_add_f32_e32 v22, v23, v22
	v_add_f32_e32 v34, v35, v34
	v_add_f32_e32 v36, v37, v36
	ds_swizzle_b32 v7, v6 offset:swizzle(SWAP,16)
	ds_swizzle_b32 v9, v8 offset:swizzle(SWAP,16)
	ds_swizzle_b32 v11, v10 offset:swizzle(SWAP,16)
	ds_swizzle_b32 v13, v12 offset:swizzle(SWAP,16)
	ds_swizzle_b32 v15, v14 offset:swizzle(SWAP,16)
	ds_swizzle_b32 v17, v16 offset:swizzle(SWAP,16)
	ds_swizzle_b32 v19, v18 offset:swizzle(SWAP,16)
	ds_swizzle_b32 v21, v20 offset:swizzle(SWAP,16)
	ds_swizzle_b32 v23, v22 offset:swizzle(SWAP,16)
	ds_swizzle_b32 v35, v34 offset:swizzle(SWAP,16)
	ds_swizzle_b32 v37, v36 offset:swizzle(SWAP,16)
	s_waitcnt lgkmcnt(10)
	v_add_f32_e32 v6, v6, v7
	s_waitcnt lgkmcnt(9)
	v_add_f32_e32 v8, v8, v9
	s_waitcnt lgkmcnt(8)
	v_add_f32_e32 v10, v10, v11
	s_waitcnt lgkmcnt(7)
	v_add_f32_e32 v12, v12, v13
	s_waitcnt lgkmcnt(6)
	v_add_f32_e32 v14, v14, v15
	s_waitcnt lgkmcnt(5)
	v_add_f32_e32 v16, v16, v17
	s_waitcnt lgkmcnt(4)
	v_add_f32_e32 v18, v18, v19
	s_waitcnt lgkmcnt(3)
	v_add_f32_e32 v20, v20, v21
	s_waitcnt lgkmcnt(2)
	v_add_f32_e32 v22, v22, v23
	s_waitcnt lgkmcnt(1)
	v_add_f32_e32 v34, v34, v35
	s_waitcnt lgkmcnt(0)
	v_add_f32_e32 v36, v36, v37
	v_mov_b32_e32 v7, v6
	v_mov_b32_e32 v9, v8
	v_mov_b32_e32 v11, v10
	v_mov_b32_e32 v13, v12
	v_mov_b32_e32 v15, v14
	v_mov_b32_e32 v17, v16
	v_mov_b32_e32 v19, v18
	v_mov_b32_e32 v21, v20
	v_mov_b32_e32 v23, v22
	v_mov_b32_e32 v35, v34
	v_mov_b32_e32 v37, v36
	v_permlane32_swap_b32_e32 v6, v7
	v_permlane32_swap_b32_e32 v8, v9
	v_permlane32_swap_b32_e32 v10, v11
	v_permlane32_swap_b32_e32 v12, v13
	v_permlane32_swap_b32_e32 v14, v15
	v_permlane32_swap_b32_e32 v16, v17
	v_permlane32_swap_b32_e32 v18, v19
	v_permlane32_swap_b32_e32 v20, v21
	v_permlane32_swap_b32_e32 v22, v23
	v_permlane32_swap_b32_e32 v32, v33
	v_permlane32_swap_b32_e32 v34, v35
	v_permlane32_swap_b32_e32 v36, v37
	v_cmp_eq_u32_e32 vcc, 0, v210
	s_and_saveexec_b64 s[30:31], vcc
	s_cbranch_execz .LBB0_349
	s_and_b64 s[52:53], s[28:29], exec
	s_mov_b32 s1, 0x31000
	s_cselect_b32 s1, s1, 0x20800
	s_add_u32 s1, s24, s1
	s_addc_u32 s2, s25, 0
	s_add_u32 s52, s1, s6
	v_add_f32_e32 v8, v8, v9
	v_add_f32_e32 v9, v6, v7
	s_addc_u32 s53, s2, s7
	v_add_f32_e32 v12, v12, v13
	v_add_f32_e32 v10, v10, v11
	v_lshl_add_u64 v[6:7], v[140:141], 2, s[52:53]
	v_add_f32_e32 v8, v9, v8
	v_add_f32_e32 v16, v16, v17
	v_add_f32_e32 v14, v14, v15
	global_atomic_add_f32 v[6:7], v8, off
	v_add_f32_e32 v8, v10, v12
	v_add_f32_e32 v20, v20, v21
	v_add_f32_e32 v18, v18, v19
	global_atomic_add_f32 v[6:7], v8, off offset:64
	v_add_f32_e32 v8, v14, v16
	v_add_f32_e32 v24, v24, v25
	v_add_f32_e32 v22, v22, v23
	global_atomic_add_f32 v[6:7], v8, off offset:128
	v_add_f32_e32 v8, v18, v20
	v_add_f32_e32 v28, v28, v29
	v_add_f32_e32 v26, v26, v27
	global_atomic_add_f32 v[6:7], v8, off offset:192
	v_add_f32_e32 v8, v22, v24
	v_add_f32_e32 v32, v32, v33
	v_add_f32_e32 v30, v30, v31
	global_atomic_add_f32 v[6:7], v8, off offset:512
	v_add_f32_e32 v8, v26, v28
	v_add_f32_e32 v36, v36, v37
	v_add_f32_e32 v34, v34, v35
	global_atomic_add_f32 v[6:7], v8, off offset:576
	v_add_f32_e32 v8, v30, v32
	global_atomic_add_f32 v[6:7], v8, off offset:640
	v_add_f32_e32 v8, v34, v36
	global_atomic_add_f32 v[6:7], v8, off offset:704

.LBB0_457:
	v_mov_b32_e32 v140, v0
	s_lshl_b32 s3, s30, 8
	s_mov_b64 s[34:35], s[84:85]
	v_and_b32_e32 v216, 15, v140
	s_add_i32 s3, s3, s54
	v_bfe_u32 v224, v140, 4, 2
	v_or_b32_e32 v140, s3, v216
	s_add_u32 s30, s34, s14
	s_addc_u32 s31, s35, s15
	v_ashrrev_i32_e32 v141, 31, v140
	v_lshl_add_u64 v[142:143], v[140:141], 2, s[30:31]
	s_mov_b64 s[30:31], 0x20800
	v_lshl_add_u64 v[198:199], v[142:143], 0, s[30:31]
	v_add_co_u32_e32 v142, vcc, s94, v142
	s_lshl_b32 s2, s2, 11
	s_nop 0
	v_addc_co_u32_e32 v143, vcc, 0, v143, vcc
	global_load_dword v141, v[142:143], off offset:2048
	s_and_b32 s2, s2, 0x800
	global_load_dword v205, v[198:199], off offset:64
	global_load_dword v204, v[198:199], off offset:128
	global_load_dword v203, v[198:199], off offset:192
	global_load_dword v202, v[198:199], off offset:512
	global_load_dword v201, v[198:199], off offset:576
	global_load_dword v200, v[198:199], off offset:640
	s_waitcnt vmcnt(0)
	v_fmamk_f32 v141, v141, 0x3a800000, v246
	v_cmp_gt_f32_e32 vcc, s95, v141
	v_mul_f32_e32 v142, 0x4b800000, v141
	s_nop 0
	v_cndmask_b32_e32 v141, v141, v142, vcc
	v_rsq_f32_e32 v141, v141
	s_nop 0
	v_mul_f32_e32 v142, 0x45800000, v141
	v_cndmask_b32_e32 v142, v141, v142, vcc
	v_pk_mul_f32 v[162:163], v[118:119], v[142:143] op_sel_hi:[1,0]
	v_pk_mul_f32 v[156:157], v[120:121], v[142:143] op_sel_hi:[1,0]
	v_pk_mul_f32 v[192:193], v[126:127], v[142:143] op_sel_hi:[1,0]
	v_pk_mul_f32 v[194:195], v[132:133], v[142:143] op_sel_hi:[1,0]
	v_pk_mul_f32 v[196:197], v[130:131], v[142:143] op_sel_hi:[1,0]
	v_pk_mul_f32 v[190:191], v[128:129], v[142:143] op_sel_hi:[1,0]
	v_pk_mul_f32 v[160:161], v[124:125], v[142:143] op_sel_hi:[1,0]
	v_pk_mul_f32 v[166:167], v[122:123], v[142:143] op_sel_hi:[1,0]
	s_waitcnt vmcnt(0)
	v_fmamk_f32 v118, v205, 0x3a800000, v246
	v_cmp_gt_f32_e32 vcc, s95, v118
	v_mul_f32_e32 v119, 0x4b800000, v118
	s_nop 0
	v_cndmask_b32_e32 v118, v118, v119, vcc
	v_rsq_f32_e32 v118, v118
	s_nop 0
	v_mul_f32_e32 v119, 0x45800000, v118
	v_cndmask_b32_e32 v118, v118, v119, vcc
	v_pk_mul_f32 v[154:155], v[102:103], v[118:119] op_sel_hi:[1,0]
	v_pk_mul_f32 v[158:159], v[106:107], v[118:119] op_sel_hi:[1,0]
	v_pk_mul_f32 v[184:185], v[116:117], v[118:119] op_sel_hi:[1,0]
	v_pk_mul_f32 v[188:189], v[114:115], v[118:119] op_sel_hi:[1,0]
	v_pk_mul_f32 v[182:183], v[112:113], v[118:119] op_sel_hi:[1,0]
	v_pk_mul_f32 v[186:187], v[110:111], v[118:119] op_sel_hi:[1,0]
	v_pk_mul_f32 v[150:151], v[108:109], v[118:119] op_sel_hi:[1,0]
	v_pk_mul_f32 v[146:147], v[104:105], v[118:119] op_sel_hi:[1,0]
	s_waitcnt vmcnt(0)
	v_fmamk_f32 v102, v204, 0x3a800000, v246
	v_cmp_gt_f32_e32 vcc, s95, v102
	v_mul_f32_e32 v103, 0x4b800000, v102
	s_nop 0
	v_cndmask_b32_e32 v102, v102, v103, vcc
	v_rsq_f32_e32 v102, v102
	s_nop 0
	v_mul_f32_e32 v103, 0x45800000, v102
	v_cndmask_b32_e32 v102, v102, v103, vcc
	v_pk_mul_f32 v[120:121], v[86:87], v[102:103] op_sel_hi:[1,0]
	v_pk_mul_f32 v[180:181], v[98:99], v[102:103] op_sel_hi:[1,0]
	v_pk_mul_f32 v[126:127], v[90:91], v[102:103] op_sel_hi:[1,0]
	v_pk_mul_f32 v[176:177], v[100:101], v[102:103] op_sel_hi:[1,0]
	v_pk_mul_f32 v[174:175], v[96:97], v[102:103] op_sel_hi:[1,0]
	v_pk_mul_f32 v[178:179], v[94:95], v[102:103] op_sel_hi:[1,0]
	v_pk_mul_f32 v[118:119], v[92:93], v[102:103] op_sel_hi:[1,0]
	v_pk_mul_f32 v[112:113], v[88:89], v[102:103] op_sel_hi:[1,0]
	s_waitcnt vmcnt(0)
	v_fmamk_f32 v86, v203, 0x3a800000, v246
	v_cmp_gt_f32_e32 vcc, s95, v86
	v_mul_f32_e32 v87, 0x4b800000, v86
	s_nop 0
	v_cndmask_b32_e32 v86, v86, v87, vcc
	v_rsq_f32_e32 v86, v86
	s_nop 0
	v_mul_f32_e32 v87, 0x45800000, v86
	v_cndmask_b32_e32 v86, v86, v87, vcc
	v_pk_mul_f32 v[106:107], v[70:71], v[86:87] op_sel_hi:[1,0]
	v_pk_mul_f32 v[172:173], v[82:83], v[86:87] op_sel_hi:[1,0]
	v_pk_mul_f32 v[168:169], v[84:85], v[86:87] op_sel_hi:[1,0]
	v_pk_mul_f32 v[164:165], v[80:81], v[86:87] op_sel_hi:[1,0]
	v_pk_mul_f32 v[104:105], v[76:77], v[86:87] op_sel_hi:[1,0]
	v_pk_mul_f32 v[108:109], v[74:75], v[86:87] op_sel_hi:[1,0]
	v_pk_mul_f32 v[170:171], v[78:79], v[86:87] op_sel_hi:[1,0]
	v_pk_mul_f32 v[102:103], v[72:73], v[86:87] op_sel_hi:[1,0]
	s_waitcnt vmcnt(0)
	v_fmamk_f32 v70, v202, 0x3a800000, v246
	v_cmp_gt_f32_e32 vcc, s95, v70
	v_mul_f32_e32 v71, 0x4b800000, v70
	s_nop 0
	v_cndmask_b32_e32 v70, v70, v71, vcc
	v_rsq_f32_e32 v70, v70
	s_nop 0
	v_mul_f32_e32 v71, 0x45800000, v70
	v_cndmask_b32_e32 v70, v70, v71, vcc
	v_pk_mul_f32 v[98:99], v[54:55], v[70:71] op_sel_hi:[1,0]
	v_pk_mul_f32 v[144:145], v[68:69], v[70:71] op_sel_hi:[1,0]
	v_pk_mul_f32 v[152:153], v[66:67], v[70:71] op_sel_hi:[1,0]
	v_pk_mul_f32 v[96:97], v[60:61], v[70:71] op_sel_hi:[1,0]
	v_pk_mul_f32 v[100:101], v[58:59], v[70:71] op_sel_hi:[1,0]
	v_pk_mul_f32 v[148:149], v[62:63], v[70:71] op_sel_hi:[1,0]
	v_pk_mul_f32 v[132:133], v[64:65], v[70:71] op_sel_hi:[1,0]
	v_pk_mul_f32 v[92:93], v[56:57], v[70:71] op_sel_hi:[1,0]
	s_waitcnt vmcnt(0)
	v_fmamk_f32 v54, v201, 0x3a800000, v246
	v_cmp_gt_f32_e32 vcc, s95, v54
	v_mul_f32_e32 v55, 0x4b800000, v54
	s_nop 0
	v_cndmask_b32_e32 v54, v54, v55, vcc
	v_rsq_f32_e32 v54, v54
	s_nop 0
	v_mul_f32_e32 v55, 0x45800000, v54
	v_cndmask_b32_e32 v54, v54, v55, vcc
	v_pk_mul_f32 v[90:91], v[38:39], v[54:55] op_sel_hi:[1,0]
	v_pk_mul_f32 v[128:129], v[52:53], v[54:55] op_sel_hi:[1,0]
	v_pk_mul_f32 v[142:143], v[50:51], v[54:55] op_sel_hi:[1,0]
	v_pk_mul_f32 v[88:89], v[44:45], v[54:55] op_sel_hi:[1,0]
	v_pk_mul_f32 v[94:95], v[42:43], v[54:55] op_sel_hi:[1,0]
	v_pk_mul_f32 v[130:131], v[46:47], v[54:55] op_sel_hi:[1,0]
	v_pk_mul_f32 v[124:125], v[48:49], v[54:55] op_sel_hi:[1,0]
	v_pk_mul_f32 v[86:87], v[40:41], v[54:55] op_sel_hi:[1,0]
	s_waitcnt vmcnt(0)
	v_fmamk_f32 v38, v200, 0x3a800000, v246
	v_cmp_gt_f32_e32 vcc, s95, v38
	v_mul_f32_e32 v39, 0x4b800000, v38
	s_nop 0
	v_cndmask_b32_e32 v38, v38, v39, vcc
	v_rsq_f32_e32 v38, v38
	s_nop 0
	v_mul_f32_e32 v39, 0x45800000, v38
	v_cndmask_b32_e32 v38, v38, v39, vcc
	v_pk_mul_f32 v[82:83], v[22:23], v[38:39] op_sel_hi:[1,0]
	global_load_dword v22, v[198:199], off offset:704
	v_pk_mul_f32 v[114:115], v[36:37], v[38:39] op_sel_hi:[1,0]
	v_pk_mul_f32 v[122:123], v[34:35], v[38:39] op_sel_hi:[1,0]
	v_pk_mul_f32 v[80:81], v[28:29], v[38:39] op_sel_hi:[1,0]
	v_pk_mul_f32 v[84:85], v[26:27], v[38:39] op_sel_hi:[1,0]
	v_pk_mul_f32 v[110:111], v[32:33], v[38:39] op_sel_hi:[1,0]
	v_pk_mul_f32 v[116:117], v[30:31], v[38:39] op_sel_hi:[1,0]
	v_pk_mul_f32 v[78:79], v[24:25], v[38:39] op_sel_hi:[1,0]
	v_mul_f32_e32 v24, v101, v101
	v_mul_f32_e32 v25, v97, v97
	v_mul_f32_e32 v26, v143, v143
	v_mul_f32_e32 v27, v129, v129
	v_mul_f32_e32 v28, v95, v95
	v_mul_f32_e32 v29, v89, v89
	v_mul_f32_e32 v30, v123, v123
	v_mul_f32_e32 v31, v115, v115
	v_mul_f32_e32 v32, v85, v85
	v_mul_f32_e32 v33, v81, v81
	v_fmac_f32_e32 v24, v100, v100
	v_fmac_f32_e32 v25, v96, v96
	v_fmac_f32_e32 v26, v142, v142
	v_fmac_f32_e32 v27, v128, v128
	v_fmac_f32_e32 v28, v94, v94
	v_fmac_f32_e32 v29, v88, v88
	v_fmac_f32_e32 v30, v122, v122
	v_fmac_f32_e32 v31, v114, v114
	v_fmac_f32_e32 v32, v84, v84
	v_fmac_f32_e32 v33, v80, v80
	v_add_f32_e32 v24, v24, v25
	v_mul_f32_e32 v25, v99, v99
	v_add_f32_e32 v26, v26, v27
	v_mul_f32_e32 v27, v131, v131
	v_add_f32_e32 v28, v28, v29
	v_mul_f32_e32 v29, v91, v91
	v_add_f32_e32 v30, v30, v31
	v_mul_f32_e32 v31, v117, v117
	v_add_f32_e32 v32, v32, v33
	v_mul_f32_e32 v33, v83, v83
	v_fmac_f32_e32 v25, v98, v98
	v_fmac_f32_e32 v27, v130, v130
	v_fmac_f32_e32 v29, v90, v90
	v_fmac_f32_e32 v31, v116, v116
	v_fmac_f32_e32 v33, v82, v82
	v_add_f32_e32 v24, v25, v24
	v_mul_f32_e32 v25, v93, v93
	v_add_f32_e32 v26, v27, v26
	v_mul_f32_e32 v27, v125, v125
	v_add_f32_e32 v28, v29, v28
	v_mul_f32_e32 v29, v87, v87
	v_add_f32_e32 v30, v31, v30
	v_mul_f32_e32 v31, v111, v111
	v_add_f32_e32 v32, v33, v32
	v_mul_f32_e32 v33, v79, v79
	v_fmac_f32_e32 v25, v92, v92
	v_fmac_f32_e32 v27, v124, v124
	v_fmac_f32_e32 v29, v86, v86
	v_fmac_f32_e32 v31, v110, v110
	v_fmac_f32_e32 v33, v78, v78
	v_add_f32_e32 v24, v25, v24
	v_add_f32_e32 v26, v27, v26
	v_add_f32_e32 v28, v29, v28
	v_add_f32_e32 v30, v31, v30
	v_add_f32_e32 v32, v33, v32
	ds_swizzle_b32 v25, v24 offset:swizzle(SWAP,16)
	ds_swizzle_b32 v27, v26 offset:swizzle(SWAP,16)
	ds_swizzle_b32 v29, v28 offset:swizzle(SWAP,16)
	ds_swizzle_b32 v31, v30 offset:swizzle(SWAP,16)
	ds_swizzle_b32 v33, v32 offset:swizzle(SWAP,16)
	s_waitcnt lgkmcnt(4)
	v_add_f32_e32 v24, v24, v25
	s_waitcnt lgkmcnt(3)
	v_add_f32_e32 v26, v26, v27
	s_waitcnt lgkmcnt(2)
	v_add_f32_e32 v28, v28, v29
	s_waitcnt lgkmcnt(1)
	v_add_f32_e32 v30, v30, v31
	s_waitcnt lgkmcnt(0)
	v_add_f32_e32 v32, v32, v33
	v_mov_b32_e32 v25, v24
	v_mov_b32_e32 v27, v26
	v_mov_b32_e32 v29, v28
	v_mov_b32_e32 v31, v30
	v_mov_b32_e32 v33, v32
	v_permlane32_swap_b32_e32 v24, v25
	s_waitcnt vmcnt(0)
	v_fmamk_f32 v22, v22, 0x3a800000, v246
	v_cmp_gt_f32_e32 vcc, s95, v22
	v_mul_f32_e32 v23, 0x4b800000, v22
	v_permlane32_swap_b32_e32 v26, v27
	v_cndmask_b32_e32 v22, v22, v23, vcc
	v_rsq_f32_e32 v22, v22
	v_permlane32_swap_b32_e32 v28, v29
	v_permlane32_swap_b32_e32 v30, v31
	v_mul_f32_e32 v23, 0x45800000, v22
	v_cndmask_b32_e32 v22, v22, v23, vcc
	v_pk_mul_f32 v[208:209], v[20:21], v[22:23] op_sel_hi:[1,0]
	v_pk_mul_f32 v[212:213], v[18:19], v[22:23] op_sel_hi:[1,0]
	v_pk_mul_f32 v[200:201], v[12:13], v[22:23] op_sel_hi:[1,0]
	v_pk_mul_f32 v[204:205], v[10:11], v[22:23] op_sel_hi:[1,0]
	v_pk_mul_f32 v[206:207], v[16:17], v[22:23] op_sel_hi:[1,0]
	v_pk_mul_f32 v[210:211], v[14:15], v[22:23] op_sel_hi:[1,0]
	v_pk_mul_f32 v[198:199], v[8:9], v[22:23] op_sel_hi:[1,0]
	v_pk_mul_f32 v[202:203], v[6:7], v[22:23] op_sel_hi:[1,0]
	v_mul_f32_e32 v6, v197, v197
	v_mul_f32_e32 v7, v195, v195
	v_mul_f32_e32 v8, v167, v167
	v_mul_f32_e32 v9, v161, v161
	v_mul_f32_e32 v10, v189, v189
	v_mul_f32_e32 v11, v185, v185
	v_mul_f32_e32 v12, v159, v159
	v_mul_f32_e32 v13, v151, v151
	v_mul_f32_e32 v14, v181, v181
	v_mul_f32_e32 v15, v177, v177
	v_mul_f32_e32 v16, v127, v127
	v_mul_f32_e32 v17, v119, v119
	v_mul_f32_e32 v18, v173, v173
	v_mul_f32_e32 v19, v169, v169
	v_mul_f32_e32 v20, v109, v109
	v_mul_f32_e32 v21, v105, v105
	v_mul_f32_e32 v22, v153, v153
	v_mul_f32_e32 v23, v145, v145
	v_mul_f32_e32 v34, v213, v213
	v_mul_f32_e32 v35, v209, v209
	v_mul_f32_e32 v36, v205, v205
	v_mul_f32_e32 v37, v201, v201
	v_fmac_f32_e32 v6, v196, v196
	v_fmac_f32_e32 v7, v194, v194
	v_fmac_f32_e32 v8, v166, v166
	v_fmac_f32_e32 v9, v160, v160
	v_fmac_f32_e32 v10, v188, v188
	v_fmac_f32_e32 v11, v184, v184
	v_fmac_f32_e32 v12, v158, v158
	v_fmac_f32_e32 v13, v150, v150
	v_fmac_f32_e32 v14, v180, v180
	v_fmac_f32_e32 v15, v176, v176
	v_fmac_f32_e32 v16, v126, v126
	v_fmac_f32_e32 v17, v118, v118
	v_fmac_f32_e32 v18, v172, v172
	v_fmac_f32_e32 v19, v168, v168
	v_fmac_f32_e32 v20, v108, v108
	v_fmac_f32_e32 v21, v104, v104
	v_fmac_f32_e32 v22, v152, v152
	v_fmac_f32_e32 v23, v144, v144
	v_fmac_f32_e32 v34, v212, v212
	v_fmac_f32_e32 v35, v208, v208
	v_fmac_f32_e32 v36, v204, v204
	v_fmac_f32_e32 v37, v200, v200
	v_add_f32_e32 v6, v6, v7
	v_mul_f32_e32 v7, v193, v193
	v_add_f32_e32 v8, v8, v9
	v_mul_f32_e32 v9, v163, v163
	v_add_f32_e32 v10, v10, v11
	v_mul_f32_e32 v11, v187, v187
	v_add_f32_e32 v12, v12, v13
	v_mul_f32_e32 v13, v155, v155
	v_add_f32_e32 v14, v14, v15
	v_mul_f32_e32 v15, v179, v179
	v_add_f32_e32 v16, v16, v17
	v_mul_f32_e32 v17, v121, v121
	v_add_f32_e32 v18, v18, v19
	v_mul_f32_e32 v19, v171, v171
	v_add_f32_e32 v20, v20, v21
	v_mul_f32_e32 v21, v107, v107
	v_add_f32_e32 v22, v22, v23
	v_mul_f32_e32 v23, v149, v149
	v_add_f32_e32 v34, v34, v35
	v_mul_f32_e32 v35, v211, v211
	v_add_f32_e32 v36, v36, v37
	v_mul_f32_e32 v37, v203, v203
	v_fmac_f32_e32 v7, v192, v192
	v_fmac_f32_e32 v9, v162, v162
	v_fmac_f32_e32 v11, v186, v186
	v_fmac_f32_e32 v13, v154, v154
	v_fmac_f32_e32 v15, v178, v178
	v_fmac_f32_e32 v17, v120, v120
	v_fmac_f32_e32 v19, v170, v170
	v_fmac_f32_e32 v21, v106, v106
	v_fmac_f32_e32 v23, v148, v148
	v_fmac_f32_e32 v35, v210, v210
	v_fmac_f32_e32 v37, v202, v202
	v_add_f32_e32 v6, v7, v6
	v_mul_f32_e32 v7, v191, v191
	v_add_f32_e32 v8, v9, v8
	v_mul_f32_e32 v9, v157, v157
	v_add_f32_e32 v10, v11, v10
	v_mul_f32_e32 v11, v183, v183
	v_add_f32_e32 v12, v13, v12
	v_mul_f32_e32 v13, v147, v147
	v_add_f32_e32 v14, v15, v14
	v_mul_f32_e32 v15, v175, v175
	v_add_f32_e32 v16, v17, v16
	v_mul_f32_e32 v17, v113, v113
	v_add_f32_e32 v18, v19, v18
	v_mul_f32_e32 v19, v165, v165
	v_add_f32_e32 v20, v21, v20
	v_mul_f32_e32 v21, v103, v103
	v_add_f32_e32 v22, v23, v22
	v_mul_f32_e32 v23, v133, v133
	v_add_f32_e32 v34, v35, v34
	v_mul_f32_e32 v35, v207, v207
	v_add_f32_e32 v36, v37, v36
	v_mul_f32_e32 v37, v199, v199
	v_fmac_f32_e32 v7, v190, v190
	v_fmac_f32_e32 v9, v156, v156
	v_fmac_f32_e32 v11, v182, v182
	v_fmac_f32_e32 v13, v146, v146
	v_fmac_f32_e32 v15, v174, v174
	v_fmac_f32_e32 v17, v112, v112
	v_fmac_f32_e32 v19, v164, v164
	v_fmac_f32_e32 v21, v102, v102
	v_fmac_f32_e32 v23, v132, v132
	v_fmac_f32_e32 v35, v206, v206
	v_fmac_f32_e32 v37, v198, v198
	v_add_f32_e32 v6, v7, v6
	v_add_f32_e32 v8, v9, v8
	v_add_f32_e32 v10, v11, v10
	v_add_f32_e32 v12, v13, v12
	v_add_f32_e32 v14, v15, v14
	v_add_f32_e32 v16, v17, v16
	v_add_f32_e32 v18, v19, v18
	v_add_f32_e32 v20, v21, v20
	v_add_f32_e32 v22, v23, v22
	v_add_f32_e32 v34, v35, v34
	v_add_f32_e32 v36, v37, v36
	ds_swizzle_b32 v7, v6 offset:swizzle(SWAP,16)
	ds_swizzle_b32 v9, v8 offset:swizzle(SWAP,16)
	ds_swizzle_b32 v11, v10 offset:swizzle(SWAP,16)
	ds_swizzle_b32 v13, v12 offset:swizzle(SWAP,16)
	ds_swizzle_b32 v15, v14 offset:swizzle(SWAP,16)
	ds_swizzle_b32 v17, v16 offset:swizzle(SWAP,16)
	ds_swizzle_b32 v19, v18 offset:swizzle(SWAP,16)
	ds_swizzle_b32 v21, v20 offset:swizzle(SWAP,16)
	ds_swizzle_b32 v23, v22 offset:swizzle(SWAP,16)
	ds_swizzle_b32 v35, v34 offset:swizzle(SWAP,16)
	ds_swizzle_b32 v37, v36 offset:swizzle(SWAP,16)
	s_waitcnt lgkmcnt(10)
	v_add_f32_e32 v6, v6, v7
	s_waitcnt lgkmcnt(9)
	v_add_f32_e32 v8, v8, v9
	s_waitcnt lgkmcnt(8)
	v_add_f32_e32 v10, v10, v11
	s_waitcnt lgkmcnt(7)
	v_add_f32_e32 v12, v12, v13
	s_waitcnt lgkmcnt(6)
	v_add_f32_e32 v14, v14, v15
	s_waitcnt lgkmcnt(5)
	v_add_f32_e32 v16, v16, v17
	s_waitcnt lgkmcnt(4)
	v_add_f32_e32 v18, v18, v19
	s_waitcnt lgkmcnt(3)
	v_add_f32_e32 v20, v20, v21
	s_waitcnt lgkmcnt(2)
	v_add_f32_e32 v22, v22, v23
	s_waitcnt lgkmcnt(1)
	v_add_f32_e32 v34, v34, v35
	s_waitcnt lgkmcnt(0)
	v_add_f32_e32 v36, v36, v37
	v_mov_b32_e32 v7, v6
	v_mov_b32_e32 v9, v8
	v_mov_b32_e32 v11, v10
	v_mov_b32_e32 v13, v12
	v_mov_b32_e32 v15, v14
	v_mov_b32_e32 v17, v16
	v_mov_b32_e32 v19, v18
	v_mov_b32_e32 v21, v20
	v_mov_b32_e32 v23, v22
	v_mov_b32_e32 v35, v34
	v_mov_b32_e32 v37, v36
	v_permlane32_swap_b32_e32 v6, v7
	v_permlane32_swap_b32_e32 v8, v9
	v_permlane32_swap_b32_e32 v10, v11
	v_permlane32_swap_b32_e32 v12, v13
	v_permlane32_swap_b32_e32 v14, v15
	v_permlane32_swap_b32_e32 v16, v17
	v_permlane32_swap_b32_e32 v18, v19
	v_permlane32_swap_b32_e32 v20, v21
	v_permlane32_swap_b32_e32 v22, v23
	v_permlane32_swap_b32_e32 v32, v33
	v_permlane32_swap_b32_e32 v34, v35
	v_permlane32_swap_b32_e32 v36, v37
	v_cmp_eq_u32_e32 vcc, 0, v224
	s_and_saveexec_b64 s[30:31], vcc
	s_cbranch_execz .LBB0_459
	s_lshl_b32 s3, s2, 2
	s_add_i32 s3, s60, s3
	v_add_f32_e32 v8, v8, v9
	v_add_f32_e32 v6, v6, v7
	v_lshl_add_u32 v7, v216, 5, s3
	v_add_f32_e32 v16, v16, v17
	v_add_f32_e32 v14, v14, v15
	v_add_f32_e32 v12, v12, v13
	v_add_f32_e32 v10, v10, v11
	ds_write2_b32 v7, v6, v8 offset1:4
	ds_write2_b32 v7, v10, v12 offset0:128 offset1:132
	v_add_u32_e32 v6, 0x400, v7
	v_add_f32_e32 v24, v24, v25
	v_add_f32_e32 v22, v22, v23
	v_add_f32_e32 v20, v20, v21
	v_add_f32_e32 v18, v18, v19
	ds_write2_b32 v6, v14, v16 offset1:4
	ds_write2_b32 v6, v18, v20 offset0:128 offset1:132
	v_add_u32_e32 v6, 0x1000, v7
	v_add_f32_e32 v32, v32, v33
	v_add_f32_e32 v30, v30, v31
	v_add_f32_e32 v28, v28, v29
	v_add_f32_e32 v26, v26, v27
	ds_write2_b32 v6, v22, v24 offset1:4
	ds_write2_b32 v6, v26, v28 offset0:128 offset1:132
	v_add_u32_e32 v6, 0x1400, v7
	v_add_f32_e32 v36, v36, v37
	v_add_f32_e32 v34, v34, v35
	ds_write2_b32 v6, v30, v32 offset1:4
	ds_write2_b32 v6, v34, v36 offset0:128 offset1:132

.LBB0_483:
	v_mov_b32_e32 v140, v0
	s_lshl_b32 s15, s24, 8
	s_mov_b64 s[26:27], s[84:85]
	v_and_b32_e32 v154, 15, v140
	s_add_i32 s15, s15, s47
	v_bfe_u32 v152, v140, 4, 2
	v_or_b32_e32 v140, s15, v154
	s_add_u32 s28, s26, s12
	s_addc_u32 s29, s27, s13
	v_ashrrev_i32_e32 v141, 31, v140
	v_lshl_add_u64 v[142:143], v[140:141], 2, s[28:29]
	s_mov_b64 s[28:29], 0x31000
	s_mov_b32 s17, 0x31000
	v_lshl_add_u64 v[150:151], v[142:143], 0, s[28:29]
	v_add_co_u32_e32 v142, vcc, s17, v142
	s_lshl_b32 s7, s7, 11
	s_nop 0
	v_addc_co_u32_e32 v143, vcc, 0, v143, vcc
	global_load_dword v142, v[142:143], off
	s_and_b32 s7, s7, 0x800
	global_load_dword v205, v[150:151], off offset:64
	global_load_dword v204, v[150:151], off offset:128
	global_load_dword v203, v[150:151], off offset:192
	global_load_dword v202, v[150:151], off offset:512
	global_load_dword v201, v[150:151], off offset:576
	global_load_dword v200, v[150:151], off offset:640
	global_load_dword v199, v[150:151], off offset:704
	s_waitcnt vmcnt(0)
	v_fmamk_f32 v142, v142, 0x3b000000, v246
	v_cmp_gt_f32_e32 vcc, s95, v142
	v_mul_f32_e32 v143, 0x4b800000, v142
	s_nop 0
	v_cndmask_b32_e32 v142, v142, v143, vcc
	v_rsq_f32_e32 v142, v142
	s_nop 0
	v_mul_f32_e32 v143, 0x45800000, v142
	v_cndmask_b32_e32 v156, v142, v143, vcc
	v_pk_mul_f32 v[148:149], v[130:131], v[156:157] op_sel_hi:[1,0]
	v_pk_mul_f32 v[130:131], v[118:119], v[156:157] op_sel_hi:[1,0]
	v_pk_mul_f32 v[146:147], v[132:133], v[156:157] op_sel_hi:[1,0]
	v_pk_mul_f32 v[142:143], v[128:129], v[156:157] op_sel_hi:[1,0]
	v_pk_mul_f32 v[144:145], v[126:127], v[156:157] op_sel_hi:[1,0]
	v_pk_mul_f32 v[128:129], v[124:125], v[156:157] op_sel_hi:[1,0]
	v_pk_mul_f32 v[132:133], v[122:123], v[156:157] op_sel_hi:[1,0]
	v_pk_mul_f32 v[126:127], v[120:121], v[156:157] op_sel_hi:[1,0]
	s_waitcnt vmcnt(0)
	v_fmamk_f32 v118, v205, 0x3b000000, v246
	v_cmp_gt_f32_e32 vcc, s95, v118
	v_mul_f32_e32 v119, 0x4b800000, v118
	s_nop 0
	v_cndmask_b32_e32 v118, v118, v119, vcc
	v_rsq_f32_e32 v118, v118
	s_nop 0
	v_mul_f32_e32 v119, 0x45800000, v118
	v_cndmask_b32_e32 v156, v118, v119, vcc
	v_pk_mul_f32 v[124:125], v[114:115], v[156:157] op_sel_hi:[1,0]
	v_pk_mul_f32 v[114:115], v[102:103], v[156:157] op_sel_hi:[1,0]
	v_pk_mul_f32 v[122:123], v[116:117], v[156:157] op_sel_hi:[1,0]
	v_pk_mul_f32 v[118:119], v[112:113], v[156:157] op_sel_hi:[1,0]
	v_pk_mul_f32 v[120:121], v[110:111], v[156:157] op_sel_hi:[1,0]
	v_pk_mul_f32 v[112:113], v[108:109], v[156:157] op_sel_hi:[1,0]
	v_pk_mul_f32 v[116:117], v[106:107], v[156:157] op_sel_hi:[1,0]
	v_pk_mul_f32 v[110:111], v[104:105], v[156:157] op_sel_hi:[1,0]
	s_waitcnt vmcnt(0)
	v_fmamk_f32 v102, v204, 0x3b000000, v246
	v_cmp_gt_f32_e32 vcc, s95, v102
	v_mul_f32_e32 v103, 0x4b800000, v102
	s_nop 0
	v_cndmask_b32_e32 v102, v102, v103, vcc
	v_rsq_f32_e32 v102, v102
	s_nop 0
	v_mul_f32_e32 v103, 0x45800000, v102
	v_cndmask_b32_e32 v102, v102, v103, vcc
	v_pk_mul_f32 v[100:101], v[100:101], v[102:103] op_sel_hi:[1,0]
	v_pk_mul_f32 v[98:99], v[98:99], v[102:103] op_sel_hi:[1,0]
	v_pk_mul_f32 v[96:97], v[96:97], v[102:103] op_sel_hi:[1,0]
	v_pk_mul_f32 v[94:95], v[94:95], v[102:103] op_sel_hi:[1,0]
	v_pk_mul_f32 v[92:93], v[92:93], v[102:103] op_sel_hi:[1,0]
	v_pk_mul_f32 v[90:91], v[90:91], v[102:103] op_sel_hi:[1,0]
	v_pk_mul_f32 v[88:89], v[88:89], v[102:103] op_sel_hi:[1,0]
	v_pk_mul_f32 v[86:87], v[86:87], v[102:103] op_sel_hi:[1,0]
	v_mul_f32_e32 v153, v91, v91
	v_mul_f32_e32 v155, v93, v93
	v_fmac_f32_e32 v153, v90, v90
	v_fmac_f32_e32 v155, v92, v92
	v_add_f32_e32 v153, v153, v155
	v_mul_f32_e32 v155, v87, v87
	v_fmac_f32_e32 v155, v86, v86
	v_add_f32_e32 v153, v155, v153
	v_mul_f32_e32 v155, v89, v89
	v_fmac_f32_e32 v155, v88, v88
	v_add_f32_e32 v153, v155, v153
	ds_swizzle_b32 v155, v153 offset:swizzle(SWAP,16)
	s_waitcnt lgkmcnt(0)
	v_add_f32_e32 v153, v153, v155
	v_mov_b32_e32 v155, v153
	s_nop 1
	v_permlane32_swap_b32_e32 v153, v155
	s_waitcnt vmcnt(0)
	v_fmamk_f32 v102, v203, 0x3b000000, v246
	v_cmp_gt_f32_e32 vcc, s95, v102
	v_mul_f32_e32 v103, 0x4b800000, v102
	s_nop 0
	v_cndmask_b32_e32 v102, v102, v103, vcc
	v_rsq_f32_e32 v102, v102
	s_nop 0
	v_mul_f32_e32 v103, 0x45800000, v102
	v_cndmask_b32_e32 v102, v102, v103, vcc
	v_pk_mul_f32 v[84:85], v[84:85], v[102:103] op_sel_hi:[1,0]
	v_pk_mul_f32 v[82:83], v[82:83], v[102:103] op_sel_hi:[1,0]
	v_pk_mul_f32 v[80:81], v[80:81], v[102:103] op_sel_hi:[1,0]
	v_pk_mul_f32 v[78:79], v[78:79], v[102:103] op_sel_hi:[1,0]
	v_pk_mul_f32 v[76:77], v[76:77], v[102:103] op_sel_hi:[1,0]
	v_pk_mul_f32 v[74:75], v[74:75], v[102:103] op_sel_hi:[1,0]
	v_pk_mul_f32 v[72:73], v[72:73], v[102:103] op_sel_hi:[1,0]
	v_pk_mul_f32 v[70:71], v[70:71], v[102:103] op_sel_hi:[1,0]
	v_mul_f32_e32 v156, v83, v83
	v_mul_f32_e32 v157, v85, v85
	v_mul_f32_e32 v158, v75, v75
	v_mul_f32_e32 v159, v77, v77
	v_fmac_f32_e32 v156, v82, v82
	v_fmac_f32_e32 v157, v84, v84
	v_fmac_f32_e32 v158, v74, v74
	v_fmac_f32_e32 v159, v76, v76
	v_add_f32_e32 v156, v156, v157
	v_mul_f32_e32 v157, v79, v79
	v_add_f32_e32 v158, v158, v159
	v_mul_f32_e32 v159, v71, v71
	v_fmac_f32_e32 v157, v78, v78
	v_fmac_f32_e32 v159, v70, v70
	v_add_f32_e32 v156, v157, v156
	v_mul_f32_e32 v157, v81, v81
	v_add_f32_e32 v158, v159, v158
	v_mul_f32_e32 v159, v73, v73
	v_fmac_f32_e32 v157, v80, v80
	v_fmac_f32_e32 v159, v72, v72
	v_add_f32_e32 v156, v157, v156
	v_add_f32_e32 v158, v159, v158
	ds_swizzle_b32 v157, v156 offset:swizzle(SWAP,16)
	ds_swizzle_b32 v159, v158 offset:swizzle(SWAP,16)
	s_waitcnt lgkmcnt(1)
	v_add_f32_e32 v156, v156, v157
	s_waitcnt lgkmcnt(0)
	v_add_f32_e32 v158, v158, v159
	v_mov_b32_e32 v157, v156
	v_mov_b32_e32 v159, v158
	s_nop 0
	v_permlane32_swap_b32_e32 v156, v157
	v_permlane32_swap_b32_e32 v158, v159
	s_waitcnt vmcnt(0)
	v_fmamk_f32 v102, v202, 0x3b000000, v246
	v_cmp_gt_f32_e32 vcc, s95, v102
	v_mul_f32_e32 v103, 0x4b800000, v102
	s_nop 0
	v_cndmask_b32_e32 v102, v102, v103, vcc
	v_rsq_f32_e32 v102, v102
	s_nop 0
	v_mul_f32_e32 v103, 0x45800000, v102
	v_cndmask_b32_e32 v102, v102, v103, vcc
	v_pk_mul_f32 v[68:69], v[68:69], v[102:103] op_sel_hi:[1,0]
	v_pk_mul_f32 v[66:67], v[66:67], v[102:103] op_sel_hi:[1,0]
	v_pk_mul_f32 v[64:65], v[64:65], v[102:103] op_sel_hi:[1,0]
	v_pk_mul_f32 v[62:63], v[62:63], v[102:103] op_sel_hi:[1,0]
	v_pk_mul_f32 v[60:61], v[60:61], v[102:103] op_sel_hi:[1,0]
	v_pk_mul_f32 v[58:59], v[58:59], v[102:103] op_sel_hi:[1,0]
	v_pk_mul_f32 v[56:57], v[56:57], v[102:103] op_sel_hi:[1,0]
	v_pk_mul_f32 v[54:55], v[54:55], v[102:103] op_sel_hi:[1,0]
	v_mul_f32_e32 v160, v67, v67
	v_mul_f32_e32 v161, v69, v69
	v_mul_f32_e32 v162, v59, v59
	v_mul_f32_e32 v163, v61, v61
	v_fmac_f32_e32 v160, v66, v66
	v_fmac_f32_e32 v161, v68, v68
	v_fmac_f32_e32 v162, v58, v58
	v_fmac_f32_e32 v163, v60, v60
	v_add_f32_e32 v160, v160, v161
	v_mul_f32_e32 v161, v63, v63
	v_add_f32_e32 v162, v162, v163
	v_mul_f32_e32 v163, v55, v55
	v_fmac_f32_e32 v161, v62, v62
	v_fmac_f32_e32 v163, v54, v54
	v_add_f32_e32 v160, v161, v160
	v_mul_f32_e32 v161, v65, v65
	v_add_f32_e32 v162, v163, v162
	v_mul_f32_e32 v163, v57, v57
	v_fmac_f32_e32 v161, v64, v64
	v_fmac_f32_e32 v163, v56, v56
	v_add_f32_e32 v160, v161, v160
	v_add_f32_e32 v162, v163, v162
	ds_swizzle_b32 v161, v160 offset:swizzle(SWAP,16)
	ds_swizzle_b32 v163, v162 offset:swizzle(SWAP,16)
	s_waitcnt lgkmcnt(1)
	v_add_f32_e32 v160, v160, v161
	s_waitcnt lgkmcnt(0)
	v_add_f32_e32 v162, v162, v163
	v_mov_b32_e32 v161, v160
	v_mov_b32_e32 v163, v162
	s_nop 0
	v_permlane32_swap_b32_e32 v160, v161
	v_permlane32_swap_b32_e32 v162, v163
	s_waitcnt vmcnt(0)
	v_fmamk_f32 v102, v201, 0x3b000000, v246
	v_cmp_gt_f32_e32 vcc, s95, v102
	v_mul_f32_e32 v103, 0x4b800000, v102
	s_nop 0
	v_cndmask_b32_e32 v102, v102, v103, vcc
	v_rsq_f32_e32 v102, v102
	s_nop 0
	v_mul_f32_e32 v103, 0x45800000, v102
	v_cndmask_b32_e32 v102, v102, v103, vcc
	v_pk_mul_f32 v[52:53], v[52:53], v[102:103] op_sel_hi:[1,0]
	v_pk_mul_f32 v[50:51], v[50:51], v[102:103] op_sel_hi:[1,0]
	v_pk_mul_f32 v[48:49], v[48:49], v[102:103] op_sel_hi:[1,0]
	v_pk_mul_f32 v[46:47], v[46:47], v[102:103] op_sel_hi:[1,0]
	v_pk_mul_f32 v[44:45], v[44:45], v[102:103] op_sel_hi:[1,0]
	v_pk_mul_f32 v[42:43], v[42:43], v[102:103] op_sel_hi:[1,0]
	v_pk_mul_f32 v[40:41], v[40:41], v[102:103] op_sel_hi:[1,0]
	v_pk_mul_f32 v[38:39], v[38:39], v[102:103] op_sel_hi:[1,0]
	v_mul_f32_e32 v164, v51, v51
	v_mul_f32_e32 v165, v53, v53
	v_mul_f32_e32 v166, v43, v43
	v_mul_f32_e32 v167, v45, v45
	v_fmac_f32_e32 v164, v50, v50
	v_fmac_f32_e32 v165, v52, v52
	v_fmac_f32_e32 v166, v42, v42
	v_fmac_f32_e32 v167, v44, v44
	v_add_f32_e32 v164, v164, v165
	v_mul_f32_e32 v165, v47, v47
	v_add_f32_e32 v166, v166, v167
	v_mul_f32_e32 v167, v39, v39
	v_fmac_f32_e32 v165, v46, v46
	v_fmac_f32_e32 v167, v38, v38
	v_add_f32_e32 v164, v165, v164
	v_mul_f32_e32 v165, v49, v49
	v_add_f32_e32 v166, v167, v166
	v_mul_f32_e32 v167, v41, v41
	v_fmac_f32_e32 v165, v48, v48
	v_fmac_f32_e32 v167, v40, v40
	v_add_f32_e32 v164, v165, v164
	v_add_f32_e32 v166, v167, v166
	ds_swizzle_b32 v165, v164 offset:swizzle(SWAP,16)
	ds_swizzle_b32 v167, v166 offset:swizzle(SWAP,16)
	s_waitcnt lgkmcnt(1)
	v_add_f32_e32 v164, v164, v165
	s_waitcnt lgkmcnt(0)
	v_add_f32_e32 v166, v166, v167
	v_mov_b32_e32 v165, v164
	v_mov_b32_e32 v167, v166
	s_nop 0
	v_permlane32_swap_b32_e32 v164, v165
	v_permlane32_swap_b32_e32 v166, v167
	s_waitcnt vmcnt(0)
	v_fmamk_f32 v102, v200, 0x3b000000, v246
	v_cmp_gt_f32_e32 vcc, s95, v102
	v_mul_f32_e32 v103, 0x4b800000, v102
	s_nop 0
	v_cndmask_b32_e32 v102, v102, v103, vcc
	v_rsq_f32_e32 v102, v102
	s_nop 0
	v_mul_f32_e32 v103, 0x45800000, v102
	v_cndmask_b32_e32 v102, v102, v103, vcc
	v_pk_mul_f32 v[36:37], v[36:37], v[102:103] op_sel_hi:[1,0]
	v_pk_mul_f32 v[34:35], v[34:35], v[102:103] op_sel_hi:[1,0]
	v_pk_mul_f32 v[32:33], v[32:33], v[102:103] op_sel_hi:[1,0]
	v_pk_mul_f32 v[30:31], v[30:31], v[102:103] op_sel_hi:[1,0]
	v_pk_mul_f32 v[28:29], v[28:29], v[102:103] op_sel_hi:[1,0]
	v_pk_mul_f32 v[26:27], v[26:27], v[102:103] op_sel_hi:[1,0]
	v_pk_mul_f32 v[24:25], v[24:25], v[102:103] op_sel_hi:[1,0]
	v_pk_mul_f32 v[22:23], v[22:23], v[102:103] op_sel_hi:[1,0]
	v_mul_f32_e32 v168, v35, v35
	v_mul_f32_e32 v169, v37, v37
	v_mul_f32_e32 v170, v27, v27
	v_mul_f32_e32 v171, v29, v29
	v_fmac_f32_e32 v168, v34, v34
	v_fmac_f32_e32 v169, v36, v36
	v_fmac_f32_e32 v170, v26, v26
	v_fmac_f32_e32 v171, v28, v28
	v_add_f32_e32 v168, v168, v169
	v_mul_f32_e32 v169, v31, v31
	v_add_f32_e32 v170, v170, v171
	v_mul_f32_e32 v171, v23, v23
	v_fmac_f32_e32 v169, v30, v30
	v_fmac_f32_e32 v171, v22, v22
	v_add_f32_e32 v168, v169, v168
	v_mul_f32_e32 v169, v33, v33
	v_add_f32_e32 v170, v171, v170
	v_mul_f32_e32 v171, v25, v25
	v_fmac_f32_e32 v169, v32, v32
	v_fmac_f32_e32 v171, v24, v24
	v_add_f32_e32 v168, v169, v168
	v_add_f32_e32 v170, v171, v170
	ds_swizzle_b32 v169, v168 offset:swizzle(SWAP,16)
	ds_swizzle_b32 v171, v170 offset:swizzle(SWAP,16)
	s_waitcnt lgkmcnt(1)
	v_add_f32_e32 v168, v168, v169
	s_waitcnt lgkmcnt(0)
	v_add_f32_e32 v170, v170, v171
	v_mov_b32_e32 v169, v168
	v_mov_b32_e32 v171, v170
	s_nop 0
	v_permlane32_swap_b32_e32 v168, v169
	v_permlane32_swap_b32_e32 v170, v171
	s_waitcnt vmcnt(0)
	v_fmamk_f32 v102, v199, 0x3b000000, v246
	v_cmp_gt_f32_e32 vcc, s95, v102
	v_mul_f32_e32 v103, 0x4b800000, v102
	s_nop 0
	v_cndmask_b32_e32 v102, v102, v103, vcc
	v_rsq_f32_e32 v102, v102
	s_nop 0
	v_mul_f32_e32 v103, 0x45800000, v102
	v_cndmask_b32_e32 v150, v102, v103, vcc
	v_pk_mul_f32 v[104:105], v[20:21], v[150:151] op_sel_hi:[1,0]
	v_pk_mul_f32 v[108:109], v[18:19], v[150:151] op_sel_hi:[1,0]
	v_pk_mul_f32 v[102:103], v[16:17], v[150:151] op_sel_hi:[1,0]
	v_pk_mul_f32 v[16:17], v[12:13], v[150:151] op_sel_hi:[1,0]
	v_pk_mul_f32 v[20:21], v[10:11], v[150:151] op_sel_hi:[1,0]
	v_pk_mul_f32 v[106:107], v[14:15], v[150:151] op_sel_hi:[1,0]
	v_pk_mul_f32 v[14:15], v[8:9], v[150:151] op_sel_hi:[1,0]
	v_pk_mul_f32 v[18:19], v[6:7], v[150:151] op_sel_hi:[1,0]
	v_mul_f32_e32 v6, v149, v149
	v_mul_f32_e32 v7, v147, v147
	v_mul_f32_e32 v8, v133, v133
	v_mul_f32_e32 v9, v129, v129
	v_mul_f32_e32 v10, v125, v125
	v_mul_f32_e32 v11, v123, v123
	v_mul_f32_e32 v12, v117, v117
	v_mul_f32_e32 v13, v113, v113
	v_mul_f32_e32 v150, v99, v99
	v_mul_f32_e32 v151, v101, v101
	v_mul_f32_e32 v172, v109, v109
	v_mul_f32_e32 v173, v105, v105
	v_mul_f32_e32 v174, v21, v21
	v_mul_f32_e32 v175, v17, v17
	v_fmac_f32_e32 v6, v148, v148
	v_fmac_f32_e32 v7, v146, v146
	v_fmac_f32_e32 v8, v132, v132
	v_fmac_f32_e32 v9, v128, v128
	v_fmac_f32_e32 v10, v124, v124
	v_fmac_f32_e32 v11, v122, v122
	v_fmac_f32_e32 v12, v116, v116
	v_fmac_f32_e32 v13, v112, v112
	v_fmac_f32_e32 v150, v98, v98
	v_fmac_f32_e32 v151, v100, v100
	v_fmac_f32_e32 v172, v108, v108
	v_fmac_f32_e32 v173, v104, v104
	v_fmac_f32_e32 v174, v20, v20
	v_fmac_f32_e32 v175, v16, v16
	v_add_f32_e32 v6, v6, v7
	v_mul_f32_e32 v7, v145, v145
	v_add_f32_e32 v8, v8, v9
	v_mul_f32_e32 v9, v131, v131
	v_add_f32_e32 v10, v10, v11
	v_mul_f32_e32 v11, v121, v121
	v_add_f32_e32 v12, v12, v13
	v_mul_f32_e32 v13, v115, v115
	v_add_f32_e32 v150, v150, v151
	v_mul_f32_e32 v151, v95, v95
	v_add_f32_e32 v172, v172, v173
	v_mul_f32_e32 v173, v107, v107
	v_add_f32_e32 v174, v174, v175
	v_mul_f32_e32 v175, v19, v19
	v_fmac_f32_e32 v7, v144, v144
	v_fmac_f32_e32 v9, v130, v130
	v_fmac_f32_e32 v11, v120, v120
	v_fmac_f32_e32 v13, v114, v114
	v_fmac_f32_e32 v151, v94, v94
	v_fmac_f32_e32 v173, v106, v106
	v_fmac_f32_e32 v175, v18, v18
	v_add_f32_e32 v6, v7, v6
	v_mul_f32_e32 v7, v143, v143
	v_add_f32_e32 v8, v9, v8
	v_mul_f32_e32 v9, v127, v127
	v_add_f32_e32 v10, v11, v10
	v_mul_f32_e32 v11, v119, v119
	v_add_f32_e32 v12, v13, v12
	v_mul_f32_e32 v13, v111, v111
	v_add_f32_e32 v150, v151, v150
	v_mul_f32_e32 v151, v97, v97
	v_add_f32_e32 v172, v173, v172
	v_mul_f32_e32 v173, v103, v103
	v_add_f32_e32 v174, v175, v174
	v_mul_f32_e32 v175, v15, v15
	v_fmac_f32_e32 v7, v142, v142
	v_fmac_f32_e32 v9, v126, v126
	v_fmac_f32_e32 v11, v118, v118
	v_fmac_f32_e32 v13, v110, v110
	v_fmac_f32_e32 v151, v96, v96
	v_fmac_f32_e32 v173, v102, v102
	v_fmac_f32_e32 v175, v14, v14
	v_add_f32_e32 v6, v7, v6
	v_add_f32_e32 v8, v9, v8
	v_add_f32_e32 v10, v11, v10
	v_add_f32_e32 v12, v13, v12
	v_add_f32_e32 v150, v151, v150
	v_add_f32_e32 v172, v173, v172
	v_add_f32_e32 v174, v175, v174
	ds_swizzle_b32 v7, v6 offset:swizzle(SWAP,16)
	ds_swizzle_b32 v9, v8 offset:swizzle(SWAP,16)
	ds_swizzle_b32 v11, v10 offset:swizzle(SWAP,16)
	ds_swizzle_b32 v13, v12 offset:swizzle(SWAP,16)
	ds_swizzle_b32 v151, v150 offset:swizzle(SWAP,16)
	ds_swizzle_b32 v173, v172 offset:swizzle(SWAP,16)
	ds_swizzle_b32 v175, v174 offset:swizzle(SWAP,16)
	s_waitcnt lgkmcnt(6)
	v_add_f32_e32 v6, v6, v7
	s_waitcnt lgkmcnt(5)
	v_add_f32_e32 v8, v8, v9
	s_waitcnt lgkmcnt(4)
	v_add_f32_e32 v10, v10, v11
	s_waitcnt lgkmcnt(3)
	v_add_f32_e32 v12, v12, v13
	s_waitcnt lgkmcnt(2)
	v_add_f32_e32 v150, v150, v151
	s_waitcnt lgkmcnt(1)
	v_add_f32_e32 v172, v172, v173
	s_waitcnt lgkmcnt(0)
	v_add_f32_e32 v174, v174, v175
	v_mov_b32_e32 v7, v6
	v_mov_b32_e32 v9, v8
	v_mov_b32_e32 v11, v10
	v_mov_b32_e32 v13, v12
	v_mov_b32_e32 v151, v150
	v_mov_b32_e32 v173, v172
	v_mov_b32_e32 v175, v174
	v_permlane32_swap_b32_e32 v6, v7
	v_permlane32_swap_b32_e32 v8, v9
	v_permlane32_swap_b32_e32 v10, v11
	v_permlane32_swap_b32_e32 v12, v13
	v_permlane32_swap_b32_e32 v150, v151
	v_permlane32_swap_b32_e32 v172, v173
	v_permlane32_swap_b32_e32 v174, v175
	v_cmp_eq_u32_e32 vcc, 0, v152
	s_and_saveexec_b64 s[28:29], vcc
	s_cbranch_execz .LBB0_485
	s_lshl_b32 s17, s7, 2
	s_add_i32 s17, s51, s17
	v_add_f32_e32 v8, v8, v9
	v_add_f32_e32 v6, v6, v7
	v_lshl_add_u32 v7, v154, 5, s17
	v_add_f32_e32 v153, v153, v155
	v_add_f32_e32 v150, v150, v151
	v_add_f32_e32 v12, v12, v13
	v_add_f32_e32 v10, v10, v11
	ds_write2_b32 v7, v6, v8 offset1:4
	ds_write2_b32 v7, v10, v12 offset0:128 offset1:132
	v_add_u32_e32 v6, 0x400, v7
	v_add_f32_e32 v162, v162, v163
	v_add_f32_e32 v160, v160, v161
	v_add_f32_e32 v158, v158, v159
	v_add_f32_e32 v156, v156, v157
	ds_write2_b32 v6, v150, v153 offset1:4
	ds_write2_b32 v6, v156, v158 offset0:128 offset1:132
	v_add_u32_e32 v6, 0x1000, v7
	v_add_f32_e32 v170, v170, v171
	v_add_f32_e32 v168, v168, v169
	v_add_f32_e32 v166, v166, v167
	v_add_f32_e32 v164, v164, v165
	ds_write2_b32 v6, v160, v162 offset1:4
	ds_write2_b32 v6, v164, v166 offset0:128 offset1:132
	v_add_u32_e32 v6, 0x1400, v7
	v_add_f32_e32 v174, v174, v175
	v_add_f32_e32 v172, v172, v173
	ds_write2_b32 v6, v168, v170 offset1:4
	ds_write2_b32 v6, v172, v174 offset0:128 offset1:132
